# FFN-up K-loop: LDS-DMA loads placed after MFMA 4/9/14 of each 16-MFMA group (was 1/6/11), further from the group's LDS fragment reads
# speedup vs baseline: 1.0107x; 1.0107x over previous
;     ...
;   if (PART != 2) {
;     GEMM_ISSUE(0, 0);
;     if (nk > 1) GEMM_ISSUE(1, 1);
;   }
;   if (PART == 1) return;
;   int st = 0;
;   for (int kt = 0; kt < nk; ++kt) {
;     if (kt + 1 < nk) asm volatile("s_waitcnt vmcnt(6)" ::: "memory");
;     else asm volatile("s_waitcnt vmcnt(0)" ::: "memory");
;     __builtin_amdgcn_s_barrier();
;     asm volatile("" ::: "memory");
;     if (kt + 2 < nk) { const int st2 = (st >= 1) ? st - 1 : 2; GEMM_ISSUE(kt + 2, st2); }
;     const char* la = lds + st * STAGE_B;
;     const char* lb = la + 32768;
;     const unsigned sa_u = (unsigned)(size_t)la + arow_u, sb_u = (unsigned)(size_t)lb + brow_u;
;     const unsigned a0 = sa_u + co0, a1 = sa_u + co1, a2 = sa_u + co2, a3 = sa_u + co3;
;     const unsigned b0 = sb_u + co0, b1 = sb_u + co1, b2 = sb_u + co2, b3 = sb_u + co3;
;     {
;       bf16x8 p0, p1, q0, q1, u0, u1, w0, w1;
;       asm volatile(
;         "ds_read_b128 %4, %12\n\tds_read_b128 %5, %12 offset:4096\n\tds_read_b128 %6, %16\n\tds_read_b128 %7, %16 offset:4096\n\t"
;         "ds_read_b128 %8, %13\n\tds_read_b128 %9, %13 offset:4096\n\tds_read_b128 %10, %17\n\tds_read_b128 %11, %17 offset:4096\n\t"
;         "s_waitcnt lgkmcnt(4)\n\t"
;         "v_mfma_f32_32x32x16_bf16 %0, %4, %6, %0\n\tv_mfma_f32_32x32x16_bf16 %1, %4, %7, %1\n\tv_mfma_f32_32x32x16_bf16 %2, %5, %6, %2\n\tv_mfma_f32_32x32x16_bf16 %3, %5, %7, %3\n\t"
;         "ds_read_b128 %4, %14\n\tds_read_b128 %5, %14 offset:4096\n\tds_read_b128 %6, %18\n\tds_read_b128 %7, %18 offset:4096\n\t"
;         "s_waitcnt lgkmcnt(4)\n\t"
;         "v_mfma_f32_32x32x16_bf16 %0, %8, %10, %0\n\tv_mfma_f32_32x32x16_bf16 %1, %8, %11, %1\n\tv_mfma_f32_32x32x16_bf16 %2, %9, %10, %2\n\tv_mfma_f32_32x32x16_bf16 %3, %9, %11, %3\n\t"
;         "ds_read_b128 %8, %15\n\tds_read_b128 %9, %15 offset:4096\n\tds_read_b128 %10, %19\n\tds_read_b128 %11, %19 offset:4096\n\t"
;         "s_waitcnt lgkmcnt(4)\n\t"
;         "v_mfma_f32_32x32x16_bf16 %0, %4, %6, %0\n\tv_mfma_f32_32x32x16_bf16 %1, %4, %7, %1\n\tv_mfma_f32_32x32x16_bf16 %2, %5, %6, %2\n\tv_mfma_f32_32x32x16_bf16 %3, %5, %7, %3\n\t"
;         "s_waitcnt lgkmcnt(0)\n\t"
;         "v_mfma_f32_32x32x16_bf16 %0, %8, %10, %0\n\tv_mfma_f32_32x32x16_bf16 %1, %8, %11, %1\n\tv_mfma_f32_32x32x16_bf16 %2, %9, %10, %2\n\tv_mfma_f32_32x32x16_bf16 %3, %9, %11, %3"
.Ly11_w0:
	s_barrier
	s_cmp_eq_u32 s100, 1
	s_cbranch_scc1 .Ly11_v1
	s_cmp_eq_u32 s100, 2
	s_cbranch_scc1 .Ly11_v2
	ds_read_b128 v[84:87], v76
	ds_read_b128 v[88:91], v76 offset:2048
	ds_read_b128 v[92:95], v76 offset:4096
	ds_read_b128 v[96:99], v76 offset:6144
	ds_read_b128 v[100:103], v78
	ds_read_b128 v[104:107], v78 offset:2048
	ds_read_b128 v[108:111], v78 offset:4096
	ds_read_b128 v[112:115], v78 offset:6144
	s_mov_b32 s24, 0x100
	s_mov_b32 s25, 0
	s_add_u32 m0, s30, 0x18000
	v_lshl_add_u64 v[124:125], v[64:65], 0, s[24:25]
	global_load_lds_dwordx4 v[124:125], off
	s_add_u32 m0, s30, 0x1a000
	v_lshl_add_u64 v[126:127], v[66:67], 0, s[24:25]
	global_load_lds_dwordx4 v[126:127], off
	s_add_u32 m0, s30, 0x1c000
	v_lshl_add_u64 v[124:125], v[68:69], 0, s[24:25]
	global_load_lds_dwordx4 v[124:125], off
	ds_read_b128 v[136:139], v77
	ds_read_b128 v[140:143], v77 offset:2048
	ds_read_b128 v[144:147], v77 offset:4096
	ds_read_b128 v[148:151], v77 offset:6144
	ds_read_b128 v[152:155], v79
	ds_read_b128 v[156:159], v79 offset:2048
	ds_read_b128 v[160:163], v79 offset:4096
	ds_read_b128 v[164:167], v79 offset:6144
	s_waitcnt lgkmcnt(8)
	v_mfma_f32_16x16x32_bf16 v[0:3], v[84:87], v[100:103], v[0:3]
	v_mfma_f32_16x16x32_bf16 v[4:7], v[84:87], v[104:107], v[4:7]
	v_mfma_f32_16x16x32_bf16 v[8:11], v[84:87], v[108:111], v[8:11]
	v_mfma_f32_16x16x32_bf16 v[12:15], v[84:87], v[112:115], v[12:15]
	v_mfma_f32_16x16x32_bf16 v[16:19], v[88:91], v[100:103], v[16:19]
	s_add_u32 m0, s30, 0x1e000
	v_lshl_add_u64 v[126:127], v[70:71], 0, s[24:25]
	global_load_lds_dwordx4 v[126:127], off
	v_mfma_f32_16x16x32_bf16 v[20:23], v[88:91], v[104:107], v[20:23]
	v_mfma_f32_16x16x32_bf16 v[24:27], v[88:91], v[108:111], v[24:27]
	v_mfma_f32_16x16x32_bf16 v[28:31], v[88:91], v[112:115], v[28:31]
	v_mfma_f32_16x16x32_bf16 v[32:35], v[92:95], v[100:103], v[32:35]
	v_mfma_f32_16x16x32_bf16 v[36:39], v[92:95], v[104:107], v[36:39]
	s_add_u32 m0, s30, 0x20000
	v_lshl_add_u64 v[124:125], v[72:73], 0, s[24:25]
	global_load_lds_dwordx4 v[124:125], off
	v_mfma_f32_16x16x32_bf16 v[40:43], v[92:95], v[108:111], v[40:43]
	v_mfma_f32_16x16x32_bf16 v[44:47], v[92:95], v[112:115], v[44:47]
	v_mfma_f32_16x16x32_bf16 v[48:51], v[96:99], v[100:103], v[48:51]
	v_mfma_f32_16x16x32_bf16 v[52:55], v[96:99], v[104:107], v[52:55]
	v_mfma_f32_16x16x32_bf16 v[56:59], v[96:99], v[108:111], v[56:59]
	s_add_u32 m0, s30, 0x22000
	v_lshl_add_u64 v[126:127], v[74:75], 0, s[24:25]
	global_load_lds_dwordx4 v[126:127], off
	v_mfma_f32_16x16x32_bf16 v[60:63], v[96:99], v[112:115], v[60:63]
	s_waitcnt vmcnt(6) lgkmcnt(0)
	s_barrier
	ds_read_b128 v[84:87], v76 offset:49152
	ds_read_b128 v[88:91], v76 offset:51200
	ds_read_b128 v[92:95], v76 offset:53248
	ds_read_b128 v[96:99], v76 offset:55296
	ds_read_b128 v[100:103], v78 offset:49152
	ds_read_b128 v[104:107], v78 offset:51200
	ds_read_b128 v[108:111], v78 offset:53248
	ds_read_b128 v[112:115], v78 offset:55296
	v_mfma_f32_16x16x32_bf16 v[0:3], v[136:139], v[152:155], v[0:3]
	v_mfma_f32_16x16x32_bf16 v[4:7], v[136:139], v[156:159], v[4:7]
	v_mfma_f32_16x16x32_bf16 v[8:11], v[136:139], v[160:163], v[8:11]
	v_mfma_f32_16x16x32_bf16 v[12:15], v[136:139], v[164:167], v[12:15]
	v_mfma_f32_16x16x32_bf16 v[16:19], v[140:143], v[152:155], v[16:19]
	s_mov_b32 s24, 0x180
	s_mov_b32 s25, 0
	s_mov_b32 m0, s30
	v_lshl_add_u64 v[124:125], v[64:65], 0, s[24:25]
	global_load_lds_dwordx4 v[124:125], off
	v_mfma_f32_16x16x32_bf16 v[20:23], v[140:143], v[156:159], v[20:23]
	v_mfma_f32_16x16x32_bf16 v[24:27], v[140:143], v[160:163], v[24:27]
	v_mfma_f32_16x16x32_bf16 v[28:31], v[140:143], v[164:167], v[28:31]
	v_mfma_f32_16x16x32_bf16 v[32:35], v[144:147], v[152:155], v[32:35]
	v_mfma_f32_16x16x32_bf16 v[36:39], v[144:147], v[156:159], v[36:39]
	s_add_u32 m0, s30, 0x2000
	v_lshl_add_u64 v[126:127], v[66:67], 0, s[24:25]
	global_load_lds_dwordx4 v[126:127], off
	v_mfma_f32_16x16x32_bf16 v[40:43], v[144:147], v[160:163], v[40:43]
	v_mfma_f32_16x16x32_bf16 v[44:47], v[144:147], v[164:167], v[44:47]
	v_mfma_f32_16x16x32_bf16 v[48:51], v[148:151], v[152:155], v[48:51]
	v_mfma_f32_16x16x32_bf16 v[52:55], v[148:151], v[156:159], v[52:55]
	v_mfma_f32_16x16x32_bf16 v[56:59], v[148:151], v[160:163], v[56:59]
	s_add_u32 m0, s30, 0x4000
	v_lshl_add_u64 v[124:125], v[68:69], 0, s[24:25]
	global_load_lds_dwordx4 v[124:125], off
	v_mfma_f32_16x16x32_bf16 v[60:63], v[148:151], v[164:167], v[60:63]
	ds_read_b128 v[136:139], v77 offset:49152
	ds_read_b128 v[140:143], v77 offset:51200
	ds_read_b128 v[144:147], v77 offset:53248
	ds_read_b128 v[148:151], v77 offset:55296
	ds_read_b128 v[152:155], v79 offset:49152
	ds_read_b128 v[156:159], v79 offset:51200
	ds_read_b128 v[160:163], v79 offset:53248
	ds_read_b128 v[164:167], v79 offset:55296
	s_waitcnt lgkmcnt(8)
	v_mfma_f32_16x16x32_bf16 v[0:3], v[84:87], v[100:103], v[0:3]
	v_mfma_f32_16x16x32_bf16 v[4:7], v[84:87], v[104:107], v[4:7]
	v_mfma_f32_16x16x32_bf16 v[8:11], v[84:87], v[108:111], v[8:11]
	v_mfma_f32_16x16x32_bf16 v[12:15], v[84:87], v[112:115], v[12:15]
	v_mfma_f32_16x16x32_bf16 v[16:19], v[88:91], v[100:103], v[16:19]
	s_add_u32 m0, s30, 0x6000
	v_lshl_add_u64 v[126:127], v[70:71], 0, s[24:25]
	global_load_lds_dwordx4 v[126:127], off
	v_mfma_f32_16x16x32_bf16 v[20:23], v[88:91], v[104:107], v[20:23]
	v_mfma_f32_16x16x32_bf16 v[24:27], v[88:91], v[108:111], v[24:27]
	v_mfma_f32_16x16x32_bf16 v[28:31], v[88:91], v[112:115], v[28:31]
	v_mfma_f32_16x16x32_bf16 v[32:35], v[92:95], v[100:103], v[32:35]
	v_mfma_f32_16x16x32_bf16 v[36:39], v[92:95], v[104:107], v[36:39]
	s_add_u32 m0, s30, 0x8000
	v_lshl_add_u64 v[124:125], v[72:73], 0, s[24:25]
	global_load_lds_dwordx4 v[124:125], off
	v_mfma_f32_16x16x32_bf16 v[40:43], v[92:95], v[108:111], v[40:43]
	v_mfma_f32_16x16x32_bf16 v[44:47], v[92:95], v[112:115], v[44:47]
	v_mfma_f32_16x16x32_bf16 v[48:51], v[96:99], v[100:103], v[48:51]
	v_mfma_f32_16x16x32_bf16 v[52:55], v[96:99], v[104:107], v[52:55]
	v_mfma_f32_16x16x32_bf16 v[56:59], v[96:99], v[108:111], v[56:59]
	s_add_u32 m0, s30, 0xa000
	v_lshl_add_u64 v[126:127], v[74:75], 0, s[24:25]
	global_load_lds_dwordx4 v[126:127], off
	v_mfma_f32_16x16x32_bf16 v[60:63], v[96:99], v[112:115], v[60:63]
	s_waitcnt vmcnt(6) lgkmcnt(0)
	s_barrier
;     ...
;   for (int kt = 0; kt < nk; ++kt) {
;     if (kt + 1 < nk) asm volatile("s_waitcnt vmcnt(6)" ::: "memory");
;     else asm volatile("s_waitcnt vmcnt(0)" ::: "memory");
;     __builtin_amdgcn_s_barrier();
;     asm volatile("" ::: "memory");
;     if (kt + 2 < nk) { const int st2 = (st >= 1) ? st - 1 : 2; GEMM_ISSUE(kt + 2, st2); }
;     const char* la = lds + st * STAGE_B;
;     const char* lb = la + 32768;
;     const unsigned sa_u = (unsigned)(size_t)la + arow_u, sb_u = (unsigned)(size_t)lb + brow_u;
;     const unsigned a0 = sa_u + co0, a1 = sa_u + co1, a2 = sa_u + co2, a3 = sa_u + co3;
;     const unsigned b0 = sb_u + co0, b1 = sb_u + co1, b2 = sb_u + co2, b3 = sb_u + co3;
;     {
;       bf16x8 p0, p1, q0, q1, u0, u1, w0, w1;
;       asm volatile(
;         "ds_read_b128 %4, %12\n\tds_read_b128 %5, %12 offset:4096\n\tds_read_b128 %6, %16\n\tds_read_b128 %7, %16 offset:4096\n\t"
;         "ds_read_b128 %8, %13\n\tds_read_b128 %9, %13 offset:4096\n\tds_read_b128 %10, %17\n\tds_read_b128 %11, %17 offset:4096\n\t"
;         "s_waitcnt lgkmcnt(4)\n\t"
;         "v_mfma_f32_32x32x16_bf16 %0, %4, %6, %0\n\tv_mfma_f32_32x32x16_bf16 %1, %4, %7, %1\n\tv_mfma_f32_32x32x16_bf16 %2, %5, %6, %2\n\tv_mfma_f32_32x32x16_bf16 %3, %5, %7, %3\n\t"
;         "ds_read_b128 %4, %14\n\tds_read_b128 %5, %14 offset:4096\n\tds_read_b128 %6, %18\n\tds_read_b128 %7, %18 offset:4096\n\t"
;         "s_waitcnt lgkmcnt(4)\n\t"
;         "v_mfma_f32_32x32x16_bf16 %0, %8, %10, %0\n\tv_mfma_f32_32x32x16_bf16 %1, %8, %11, %1\n\tv_mfma_f32_32x32x16_bf16 %2, %9, %10, %2\n\tv_mfma_f32_32x32x16_bf16 %3, %9, %11, %3\n\t"
;         "ds_read_b128 %8, %15\n\tds_read_b128 %9, %15 offset:4096\n\tds_read_b128 %10, %19\n\tds_read_b128 %11, %19 offset:4096\n\t"
;         "s_waitcnt lgkmcnt(4)\n\t"
;         "v_mfma_f32_32x32x16_bf16 %0, %4, %6, %0\n\tv_mfma_f32_32x32x16_bf16 %1, %4, %7, %1\n\tv_mfma_f32_32x32x16_bf16 %2, %5, %6, %2\n\tv_mfma_f32_32x32x16_bf16 %3, %5, %7, %3\n\t"
;         "s_waitcnt lgkmcnt(0)\n\t"
;         "v_mfma_f32_32x32x16_bf16 %0, %8, %10, %0\n\tv_mfma_f32_32x32x16_bf16 %1, %8, %11, %1\n\tv_mfma_f32_32x32x16_bf16 %2, %9, %10, %2\n\tv_mfma_f32_32x32x16_bf16 %3, %9, %11, %3"
	ds_read_b128 v[84:87], v80
	ds_read_b128 v[88:91], v80 offset:2048
	ds_read_b128 v[92:95], v80 offset:4096
	ds_read_b128 v[96:99], v80 offset:6144
	ds_read_b128 v[100:103], v82
	ds_read_b128 v[104:107], v82 offset:2048
	ds_read_b128 v[108:111], v82 offset:4096
	ds_read_b128 v[112:115], v82 offset:6144
	v_mfma_f32_16x16x32_bf16 v[0:3], v[136:139], v[152:155], v[0:3]
	v_mfma_f32_16x16x32_bf16 v[4:7], v[136:139], v[156:159], v[4:7]
	v_mfma_f32_16x16x32_bf16 v[8:11], v[136:139], v[160:163], v[8:11]
	v_mfma_f32_16x16x32_bf16 v[12:15], v[136:139], v[164:167], v[12:15]
	v_mfma_f32_16x16x32_bf16 v[16:19], v[140:143], v[152:155], v[16:19]
	s_mov_b32 s24, 0x200
	s_mov_b32 s25, 0
	s_add_u32 m0, s30, 0xc000
	v_lshl_add_u64 v[124:125], v[64:65], 0, s[24:25]
	global_load_lds_dwordx4 v[124:125], off
	v_mfma_f32_16x16x32_bf16 v[20:23], v[140:143], v[156:159], v[20:23]
	v_mfma_f32_16x16x32_bf16 v[24:27], v[140:143], v[160:163], v[24:27]
	v_mfma_f32_16x16x32_bf16 v[28:31], v[140:143], v[164:167], v[28:31]
	v_mfma_f32_16x16x32_bf16 v[32:35], v[144:147], v[152:155], v[32:35]
	v_mfma_f32_16x16x32_bf16 v[36:39], v[144:147], v[156:159], v[36:39]
	s_add_u32 m0, s30, 0xe000
	v_lshl_add_u64 v[126:127], v[66:67], 0, s[24:25]
	global_load_lds_dwordx4 v[126:127], off
	v_mfma_f32_16x16x32_bf16 v[40:43], v[144:147], v[160:163], v[40:43]
	v_mfma_f32_16x16x32_bf16 v[44:47], v[144:147], v[164:167], v[44:47]
	v_mfma_f32_16x16x32_bf16 v[48:51], v[148:151], v[152:155], v[48:51]
	v_mfma_f32_16x16x32_bf16 v[52:55], v[148:151], v[156:159], v[52:55]
	v_mfma_f32_16x16x32_bf16 v[56:59], v[148:151], v[160:163], v[56:59]
	s_add_u32 m0, s30, 0x10000
	v_lshl_add_u64 v[124:125], v[68:69], 0, s[24:25]
	global_load_lds_dwordx4 v[124:125], off
	v_mfma_f32_16x16x32_bf16 v[60:63], v[148:151], v[164:167], v[60:63]
	ds_read_b128 v[136:139], v81
	ds_read_b128 v[140:143], v81 offset:2048
	ds_read_b128 v[144:147], v81 offset:4096
	ds_read_b128 v[148:151], v81 offset:6144
	ds_read_b128 v[152:155], v83
	ds_read_b128 v[156:159], v83 offset:2048
	ds_read_b128 v[160:163], v83 offset:4096
	ds_read_b128 v[164:167], v83 offset:6144
	s_waitcnt lgkmcnt(8)
	v_mfma_f32_16x16x32_bf16 v[0:3], v[84:87], v[100:103], v[0:3]
	v_mfma_f32_16x16x32_bf16 v[4:7], v[84:87], v[104:107], v[4:7]
	v_mfma_f32_16x16x32_bf16 v[8:11], v[84:87], v[108:111], v[8:11]
	v_mfma_f32_16x16x32_bf16 v[12:15], v[84:87], v[112:115], v[12:15]
	v_mfma_f32_16x16x32_bf16 v[16:19], v[88:91], v[100:103], v[16:19]
	s_add_u32 m0, s30, 0x12000
	v_lshl_add_u64 v[126:127], v[70:71], 0, s[24:25]
	global_load_lds_dwordx4 v[126:127], off
	v_mfma_f32_16x16x32_bf16 v[20:23], v[88:91], v[104:107], v[20:23]
	v_mfma_f32_16x16x32_bf16 v[24:27], v[88:91], v[108:111], v[24:27]
	v_mfma_f32_16x16x32_bf16 v[28:31], v[88:91], v[112:115], v[28:31]
	v_mfma_f32_16x16x32_bf16 v[32:35], v[92:95], v[100:103], v[32:35]
	v_mfma_f32_16x16x32_bf16 v[36:39], v[92:95], v[104:107], v[36:39]
	s_add_u32 m0, s30, 0x14000
	v_lshl_add_u64 v[124:125], v[72:73], 0, s[24:25]
	global_load_lds_dwordx4 v[124:125], off
	v_mfma_f32_16x16x32_bf16 v[40:43], v[92:95], v[108:111], v[40:43]
	v_mfma_f32_16x16x32_bf16 v[44:47], v[92:95], v[112:115], v[44:47]
	v_mfma_f32_16x16x32_bf16 v[48:51], v[96:99], v[100:103], v[48:51]
	v_mfma_f32_16x16x32_bf16 v[52:55], v[96:99], v[104:107], v[52:55]
	v_mfma_f32_16x16x32_bf16 v[56:59], v[96:99], v[108:111], v[56:59]
	s_add_u32 m0, s30, 0x16000
	v_lshl_add_u64 v[126:127], v[74:75], 0, s[24:25]
	global_load_lds_dwordx4 v[126:127], off
	v_mfma_f32_16x16x32_bf16 v[60:63], v[96:99], v[112:115], v[60:63]
	s_waitcnt vmcnt(6) lgkmcnt(0)
	s_barrier
	ds_read_b128 v[84:87], v76
	ds_read_b128 v[88:91], v76 offset:2048
	ds_read_b128 v[92:95], v76 offset:4096
	ds_read_b128 v[96:99], v76 offset:6144
	ds_read_b128 v[100:103], v78
	ds_read_b128 v[104:107], v78 offset:2048
	ds_read_b128 v[108:111], v78 offset:4096
	ds_read_b128 v[112:115], v78 offset:6144
	v_mfma_f32_16x16x32_bf16 v[0:3], v[136:139], v[152:155], v[0:3]
	v_mfma_f32_16x16x32_bf16 v[4:7], v[136:139], v[156:159], v[4:7]
	v_mfma_f32_16x16x32_bf16 v[8:11], v[136:139], v[160:163], v[8:11]
	v_mfma_f32_16x16x32_bf16 v[12:15], v[136:139], v[164:167], v[12:15]
	v_mfma_f32_16x16x32_bf16 v[16:19], v[140:143], v[152:155], v[16:19]
	s_mov_b32 s24, 0x280
	s_mov_b32 s25, 0
	s_add_u32 m0, s30, 0x18000
	v_lshl_add_u64 v[124:125], v[64:65], 0, s[24:25]
	global_load_lds_dwordx4 v[124:125], off
	v_mfma_f32_16x16x32_bf16 v[20:23], v[140:143], v[156:159], v[20:23]
	v_mfma_f32_16x16x32_bf16 v[24:27], v[140:143], v[160:163], v[24:27]
	v_mfma_f32_16x16x32_bf16 v[28:31], v[140:143], v[164:167], v[28:31]
	v_mfma_f32_16x16x32_bf16 v[32:35], v[144:147], v[152:155], v[32:35]
	v_mfma_f32_16x16x32_bf16 v[36:39], v[144:147], v[156:159], v[36:39]
	s_add_u32 m0, s30, 0x1a000
	v_lshl_add_u64 v[126:127], v[66:67], 0, s[24:25]
	global_load_lds_dwordx4 v[126:127], off
	v_mfma_f32_16x16x32_bf16 v[40:43], v[144:147], v[160:163], v[40:43]
	v_mfma_f32_16x16x32_bf16 v[44:47], v[144:147], v[164:167], v[44:47]
	v_mfma_f32_16x16x32_bf16 v[48:51], v[148:151], v[152:155], v[48:51]
	v_mfma_f32_16x16x32_bf16 v[52:55], v[148:151], v[156:159], v[52:55]
	v_mfma_f32_16x16x32_bf16 v[56:59], v[148:151], v[160:163], v[56:59]
	s_add_u32 m0, s30, 0x1c000
	v_lshl_add_u64 v[124:125], v[68:69], 0, s[24:25]
	global_load_lds_dwordx4 v[124:125], off
	v_mfma_f32_16x16x32_bf16 v[60:63], v[148:151], v[164:167], v[60:63]
	ds_read_b128 v[136:139], v77
	ds_read_b128 v[140:143], v77 offset:2048
	ds_read_b128 v[144:147], v77 offset:4096
	ds_read_b128 v[148:151], v77 offset:6144
	ds_read_b128 v[152:155], v79
	ds_read_b128 v[156:159], v79 offset:2048
	ds_read_b128 v[160:163], v79 offset:4096
	ds_read_b128 v[164:167], v79 offset:6144
	s_waitcnt lgkmcnt(8)
;     ...
;   for (int kt = 0; kt < nk; ++kt) {
;     if (kt + 1 < nk) asm volatile("s_waitcnt vmcnt(6)" ::: "memory");
;     else asm volatile("s_waitcnt vmcnt(0)" ::: "memory");
;     __builtin_amdgcn_s_barrier();
;     asm volatile("" ::: "memory");
;     if (kt + 2 < nk) { const int st2 = (st >= 1) ? st - 1 : 2; GEMM_ISSUE(kt + 2, st2); }
;     const char* la = lds + st * STAGE_B;
;     const char* lb = la + 32768;
;     const unsigned sa_u = (unsigned)(size_t)la + arow_u, sb_u = (unsigned)(size_t)lb + brow_u;
;     const unsigned a0 = sa_u + co0, a1 = sa_u + co1, a2 = sa_u + co2, a3 = sa_u + co3;
;     const unsigned b0 = sb_u + co0, b1 = sb_u + co1, b2 = sb_u + co2, b3 = sb_u + co3;
;     {
;       bf16x8 p0, p1, q0, q1, u0, u1, w0, w1;
;       asm volatile(
;         "ds_read_b128 %4, %12\n\tds_read_b128 %5, %12 offset:4096\n\tds_read_b128 %6, %16\n\tds_read_b128 %7, %16 offset:4096\n\t"
;         "ds_read_b128 %8, %13\n\tds_read_b128 %9, %13 offset:4096\n\tds_read_b128 %10, %17\n\tds_read_b128 %11, %17 offset:4096\n\t"
;         "s_waitcnt lgkmcnt(4)\n\t"
;         "v_mfma_f32_32x32x16_bf16 %0, %4, %6, %0\n\tv_mfma_f32_32x32x16_bf16 %1, %4, %7, %1\n\tv_mfma_f32_32x32x16_bf16 %2, %5, %6, %2\n\tv_mfma_f32_32x32x16_bf16 %3, %5, %7, %3\n\t"
;         "ds_read_b128 %4, %14\n\tds_read_b128 %5, %14 offset:4096\n\tds_read_b128 %6, %18\n\tds_read_b128 %7, %18 offset:4096\n\t"
;         "s_waitcnt lgkmcnt(4)\n\t"
;         "v_mfma_f32_32x32x16_bf16 %0, %8, %10, %0\n\tv_mfma_f32_32x32x16_bf16 %1, %8, %11, %1\n\tv_mfma_f32_32x32x16_bf16 %2, %9, %10, %2\n\tv_mfma_f32_32x32x16_bf16 %3, %9, %11, %3\n\t"
;         "ds_read_b128 %8, %15\n\tds_read_b128 %9, %15 offset:4096\n\tds_read_b128 %10, %19\n\tds_read_b128 %11, %19 offset:4096\n\t"
;         "s_waitcnt lgkmcnt(4)\n\t"
;         "v_mfma_f32_32x32x16_bf16 %0, %4, %6, %0\n\tv_mfma_f32_32x32x16_bf16 %1, %4, %7, %1\n\tv_mfma_f32_32x32x16_bf16 %2, %5, %6, %2\n\tv_mfma_f32_32x32x16_bf16 %3, %5, %7, %3\n\t"
;         "s_waitcnt lgkmcnt(0)\n\t"
;         "v_mfma_f32_32x32x16_bf16 %0, %8, %10, %0\n\tv_mfma_f32_32x32x16_bf16 %1, %8, %11, %1\n\tv_mfma_f32_32x32x16_bf16 %2, %9, %10, %2\n\tv_mfma_f32_32x32x16_bf16 %3, %9, %11, %3"
	v_mfma_f32_16x16x32_bf16 v[0:3], v[84:87], v[100:103], v[0:3]
	v_mfma_f32_16x16x32_bf16 v[4:7], v[84:87], v[104:107], v[4:7]
	v_mfma_f32_16x16x32_bf16 v[8:11], v[84:87], v[108:111], v[8:11]
	v_mfma_f32_16x16x32_bf16 v[12:15], v[84:87], v[112:115], v[12:15]
	v_mfma_f32_16x16x32_bf16 v[16:19], v[88:91], v[100:103], v[16:19]
	s_add_u32 m0, s30, 0x1e000
	v_lshl_add_u64 v[126:127], v[70:71], 0, s[24:25]
	global_load_lds_dwordx4 v[126:127], off
	v_mfma_f32_16x16x32_bf16 v[20:23], v[88:91], v[104:107], v[20:23]
	v_mfma_f32_16x16x32_bf16 v[24:27], v[88:91], v[108:111], v[24:27]
	v_mfma_f32_16x16x32_bf16 v[28:31], v[88:91], v[112:115], v[28:31]
	v_mfma_f32_16x16x32_bf16 v[32:35], v[92:95], v[100:103], v[32:35]
	v_mfma_f32_16x16x32_bf16 v[36:39], v[92:95], v[104:107], v[36:39]
	s_add_u32 m0, s30, 0x20000
	v_lshl_add_u64 v[124:125], v[72:73], 0, s[24:25]
	global_load_lds_dwordx4 v[124:125], off
	v_mfma_f32_16x16x32_bf16 v[40:43], v[92:95], v[108:111], v[40:43]
	v_mfma_f32_16x16x32_bf16 v[44:47], v[92:95], v[112:115], v[44:47]
	v_mfma_f32_16x16x32_bf16 v[48:51], v[96:99], v[100:103], v[48:51]
	v_mfma_f32_16x16x32_bf16 v[52:55], v[96:99], v[104:107], v[52:55]
	v_mfma_f32_16x16x32_bf16 v[56:59], v[96:99], v[108:111], v[56:59]
	s_add_u32 m0, s30, 0x22000
	v_lshl_add_u64 v[126:127], v[74:75], 0, s[24:25]
	global_load_lds_dwordx4 v[126:127], off
	v_mfma_f32_16x16x32_bf16 v[60:63], v[96:99], v[112:115], v[60:63]
	s_waitcnt vmcnt(6) lgkmcnt(0)
	s_barrier
	ds_read_b128 v[84:87], v76 offset:49152
	ds_read_b128 v[88:91], v76 offset:51200
	ds_read_b128 v[92:95], v76 offset:53248
	ds_read_b128 v[96:99], v76 offset:55296
	ds_read_b128 v[100:103], v78 offset:49152
	ds_read_b128 v[104:107], v78 offset:51200
	ds_read_b128 v[108:111], v78 offset:53248
	ds_read_b128 v[112:115], v78 offset:55296
	v_mfma_f32_16x16x32_bf16 v[0:3], v[136:139], v[152:155], v[0:3]
	v_mfma_f32_16x16x32_bf16 v[4:7], v[136:139], v[156:159], v[4:7]
	v_mfma_f32_16x16x32_bf16 v[8:11], v[136:139], v[160:163], v[8:11]
	v_mfma_f32_16x16x32_bf16 v[12:15], v[136:139], v[164:167], v[12:15]
	v_mfma_f32_16x16x32_bf16 v[16:19], v[140:143], v[152:155], v[16:19]
	s_mov_b32 s24, 0x300
	s_mov_b32 s25, 0
	s_mov_b32 m0, s30
	v_lshl_add_u64 v[124:125], v[64:65], 0, s[24:25]
	global_load_lds_dwordx4 v[124:125], off
	v_mfma_f32_16x16x32_bf16 v[20:23], v[140:143], v[156:159], v[20:23]
	v_mfma_f32_16x16x32_bf16 v[24:27], v[140:143], v[160:163], v[24:27]
	v_mfma_f32_16x16x32_bf16 v[28:31], v[140:143], v[164:167], v[28:31]
	v_mfma_f32_16x16x32_bf16 v[32:35], v[144:147], v[152:155], v[32:35]
	v_mfma_f32_16x16x32_bf16 v[36:39], v[144:147], v[156:159], v[36:39]
	s_add_u32 m0, s30, 0x2000
	v_lshl_add_u64 v[126:127], v[66:67], 0, s[24:25]
	global_load_lds_dwordx4 v[126:127], off
	v_mfma_f32_16x16x32_bf16 v[40:43], v[144:147], v[160:163], v[40:43]
	v_mfma_f32_16x16x32_bf16 v[44:47], v[144:147], v[164:167], v[44:47]
	v_mfma_f32_16x16x32_bf16 v[48:51], v[148:151], v[152:155], v[48:51]
	v_mfma_f32_16x16x32_bf16 v[52:55], v[148:151], v[156:159], v[52:55]
	v_mfma_f32_16x16x32_bf16 v[56:59], v[148:151], v[160:163], v[56:59]
	s_add_u32 m0, s30, 0x4000
	v_lshl_add_u64 v[124:125], v[68:69], 0, s[24:25]
	global_load_lds_dwordx4 v[124:125], off
	v_mfma_f32_16x16x32_bf16 v[60:63], v[148:151], v[164:167], v[60:63]
	ds_read_b128 v[136:139], v77 offset:49152
	ds_read_b128 v[140:143], v77 offset:51200
	ds_read_b128 v[144:147], v77 offset:53248
	ds_read_b128 v[148:151], v77 offset:55296
	ds_read_b128 v[152:155], v79 offset:49152
	ds_read_b128 v[156:159], v79 offset:51200
	ds_read_b128 v[160:163], v79 offset:53248
	ds_read_b128 v[164:167], v79 offset:55296
	s_waitcnt lgkmcnt(8)
	v_mfma_f32_16x16x32_bf16 v[0:3], v[84:87], v[100:103], v[0:3]
	v_mfma_f32_16x16x32_bf16 v[4:7], v[84:87], v[104:107], v[4:7]
	v_mfma_f32_16x16x32_bf16 v[8:11], v[84:87], v[108:111], v[8:11]
	v_mfma_f32_16x16x32_bf16 v[12:15], v[84:87], v[112:115], v[12:15]
	v_mfma_f32_16x16x32_bf16 v[16:19], v[88:91], v[100:103], v[16:19]
	s_add_u32 m0, s30, 0x6000
	v_lshl_add_u64 v[126:127], v[70:71], 0, s[24:25]
	global_load_lds_dwordx4 v[126:127], off
	v_mfma_f32_16x16x32_bf16 v[20:23], v[88:91], v[104:107], v[20:23]
	v_mfma_f32_16x16x32_bf16 v[24:27], v[88:91], v[108:111], v[24:27]
	v_mfma_f32_16x16x32_bf16 v[28:31], v[88:91], v[112:115], v[28:31]
	v_mfma_f32_16x16x32_bf16 v[32:35], v[92:95], v[100:103], v[32:35]
	v_mfma_f32_16x16x32_bf16 v[36:39], v[92:95], v[104:107], v[36:39]
	s_add_u32 m0, s30, 0x8000
	v_lshl_add_u64 v[124:125], v[72:73], 0, s[24:25]
	global_load_lds_dwordx4 v[124:125], off
	v_mfma_f32_16x16x32_bf16 v[40:43], v[92:95], v[108:111], v[40:43]
	v_mfma_f32_16x16x32_bf16 v[44:47], v[92:95], v[112:115], v[44:47]
	v_mfma_f32_16x16x32_bf16 v[48:51], v[96:99], v[100:103], v[48:51]
	v_mfma_f32_16x16x32_bf16 v[52:55], v[96:99], v[104:107], v[52:55]
	v_mfma_f32_16x16x32_bf16 v[56:59], v[96:99], v[108:111], v[56:59]
	s_add_u32 m0, s30, 0xa000
	v_lshl_add_u64 v[126:127], v[74:75], 0, s[24:25]
	global_load_lds_dwordx4 v[126:127], off
	v_mfma_f32_16x16x32_bf16 v[60:63], v[96:99], v[112:115], v[60:63]
	s_waitcnt vmcnt(6) lgkmcnt(0)
	s_barrier
;     ...
;   for (int kt = 0; kt < nk; ++kt) {
;     if (kt + 1 < nk) asm volatile("s_waitcnt vmcnt(6)" ::: "memory");
;     else asm volatile("s_waitcnt vmcnt(0)" ::: "memory");
;     __builtin_amdgcn_s_barrier();
;     asm volatile("" ::: "memory");
;     if (kt + 2 < nk) { const int st2 = (st >= 1) ? st - 1 : 2; GEMM_ISSUE(kt + 2, st2); }
;     const char* la = lds + st * STAGE_B;
;     const char* lb = la + 32768;
;     const unsigned sa_u = (unsigned)(size_t)la + arow_u, sb_u = (unsigned)(size_t)lb + brow_u;
;     const unsigned a0 = sa_u + co0, a1 = sa_u + co1, a2 = sa_u + co2, a3 = sa_u + co3;
;     const unsigned b0 = sb_u + co0, b1 = sb_u + co1, b2 = sb_u + co2, b3 = sb_u + co3;
;     {
;       bf16x8 p0, p1, q0, q1, u0, u1, w0, w1;
;       asm volatile(
;         "ds_read_b128 %4, %12\n\tds_read_b128 %5, %12 offset:4096\n\tds_read_b128 %6, %16\n\tds_read_b128 %7, %16 offset:4096\n\t"
;         "ds_read_b128 %8, %13\n\tds_read_b128 %9, %13 offset:4096\n\tds_read_b128 %10, %17\n\tds_read_b128 %11, %17 offset:4096\n\t"
;         "s_waitcnt lgkmcnt(4)\n\t"
;         "v_mfma_f32_32x32x16_bf16 %0, %4, %6, %0\n\tv_mfma_f32_32x32x16_bf16 %1, %4, %7, %1\n\tv_mfma_f32_32x32x16_bf16 %2, %5, %6, %2\n\tv_mfma_f32_32x32x16_bf16 %3, %5, %7, %3\n\t"
;         "ds_read_b128 %4, %14\n\tds_read_b128 %5, %14 offset:4096\n\tds_read_b128 %6, %18\n\tds_read_b128 %7, %18 offset:4096\n\t"
;         "s_waitcnt lgkmcnt(4)\n\t"
;         "v_mfma_f32_32x32x16_bf16 %0, %8, %10, %0\n\tv_mfma_f32_32x32x16_bf16 %1, %8, %11, %1\n\tv_mfma_f32_32x32x16_bf16 %2, %9, %10, %2\n\tv_mfma_f32_32x32x16_bf16 %3, %9, %11, %3\n\t"
;         "ds_read_b128 %8, %15\n\tds_read_b128 %9, %15 offset:4096\n\tds_read_b128 %10, %19\n\tds_read_b128 %11, %19 offset:4096\n\t"
;         "s_waitcnt lgkmcnt(4)\n\t"
;         "v_mfma_f32_32x32x16_bf16 %0, %4, %6, %0\n\tv_mfma_f32_32x32x16_bf16 %1, %4, %7, %1\n\tv_mfma_f32_32x32x16_bf16 %2, %5, %6, %2\n\tv_mfma_f32_32x32x16_bf16 %3, %5, %7, %3\n\t"
;         "s_waitcnt lgkmcnt(0)\n\t"
;         "v_mfma_f32_32x32x16_bf16 %0, %8, %10, %0\n\tv_mfma_f32_32x32x16_bf16 %1, %8, %11, %1\n\tv_mfma_f32_32x32x16_bf16 %2, %9, %10, %2\n\tv_mfma_f32_32x32x16_bf16 %3, %9, %11, %3"
	ds_read_b128 v[84:87], v80
	ds_read_b128 v[88:91], v80 offset:2048
	ds_read_b128 v[92:95], v80 offset:4096
	ds_read_b128 v[96:99], v80 offset:6144
	ds_read_b128 v[100:103], v82
	ds_read_b128 v[104:107], v82 offset:2048
	ds_read_b128 v[108:111], v82 offset:4096
	ds_read_b128 v[112:115], v82 offset:6144
	v_mfma_f32_16x16x32_bf16 v[0:3], v[136:139], v[152:155], v[0:3]
	v_mfma_f32_16x16x32_bf16 v[4:7], v[136:139], v[156:159], v[4:7]
	v_mfma_f32_16x16x32_bf16 v[8:11], v[136:139], v[160:163], v[8:11]
	v_mfma_f32_16x16x32_bf16 v[12:15], v[136:139], v[164:167], v[12:15]
	v_mfma_f32_16x16x32_bf16 v[16:19], v[140:143], v[152:155], v[16:19]
	s_mov_b32 s24, 0x380
	s_mov_b32 s25, 0
	s_add_u32 m0, s30, 0xc000
	v_lshl_add_u64 v[124:125], v[64:65], 0, s[24:25]
	global_load_lds_dwordx4 v[124:125], off
	v_mfma_f32_16x16x32_bf16 v[20:23], v[140:143], v[156:159], v[20:23]
	v_mfma_f32_16x16x32_bf16 v[24:27], v[140:143], v[160:163], v[24:27]
	v_mfma_f32_16x16x32_bf16 v[28:31], v[140:143], v[164:167], v[28:31]
	v_mfma_f32_16x16x32_bf16 v[32:35], v[144:147], v[152:155], v[32:35]
	v_mfma_f32_16x16x32_bf16 v[36:39], v[144:147], v[156:159], v[36:39]
	s_add_u32 m0, s30, 0xe000
	v_lshl_add_u64 v[126:127], v[66:67], 0, s[24:25]
	global_load_lds_dwordx4 v[126:127], off
	v_mfma_f32_16x16x32_bf16 v[40:43], v[144:147], v[160:163], v[40:43]
	v_mfma_f32_16x16x32_bf16 v[44:47], v[144:147], v[164:167], v[44:47]
	v_mfma_f32_16x16x32_bf16 v[48:51], v[148:151], v[152:155], v[48:51]
	v_mfma_f32_16x16x32_bf16 v[52:55], v[148:151], v[156:159], v[52:55]
	v_mfma_f32_16x16x32_bf16 v[56:59], v[148:151], v[160:163], v[56:59]
	s_add_u32 m0, s30, 0x10000
	v_lshl_add_u64 v[124:125], v[68:69], 0, s[24:25]
	global_load_lds_dwordx4 v[124:125], off
	v_mfma_f32_16x16x32_bf16 v[60:63], v[148:151], v[164:167], v[60:63]
	ds_read_b128 v[136:139], v81
	ds_read_b128 v[140:143], v81 offset:2048
	ds_read_b128 v[144:147], v81 offset:4096
	ds_read_b128 v[148:151], v81 offset:6144
	ds_read_b128 v[152:155], v83
	ds_read_b128 v[156:159], v83 offset:2048
	ds_read_b128 v[160:163], v83 offset:4096
	ds_read_b128 v[164:167], v83 offset:6144
	s_waitcnt lgkmcnt(8)
	v_mfma_f32_16x16x32_bf16 v[0:3], v[84:87], v[100:103], v[0:3]
	v_mfma_f32_16x16x32_bf16 v[4:7], v[84:87], v[104:107], v[4:7]
	v_mfma_f32_16x16x32_bf16 v[8:11], v[84:87], v[108:111], v[8:11]
	v_mfma_f32_16x16x32_bf16 v[12:15], v[84:87], v[112:115], v[12:15]
	v_mfma_f32_16x16x32_bf16 v[16:19], v[88:91], v[100:103], v[16:19]
	s_add_u32 m0, s30, 0x12000
	v_lshl_add_u64 v[126:127], v[70:71], 0, s[24:25]
	global_load_lds_dwordx4 v[126:127], off
	v_mfma_f32_16x16x32_bf16 v[20:23], v[88:91], v[104:107], v[20:23]
	v_mfma_f32_16x16x32_bf16 v[24:27], v[88:91], v[108:111], v[24:27]
	v_mfma_f32_16x16x32_bf16 v[28:31], v[88:91], v[112:115], v[28:31]
	v_mfma_f32_16x16x32_bf16 v[32:35], v[92:95], v[100:103], v[32:35]
	v_mfma_f32_16x16x32_bf16 v[36:39], v[92:95], v[104:107], v[36:39]
	s_add_u32 m0, s30, 0x14000
	v_lshl_add_u64 v[124:125], v[72:73], 0, s[24:25]
	global_load_lds_dwordx4 v[124:125], off
	v_mfma_f32_16x16x32_bf16 v[40:43], v[92:95], v[108:111], v[40:43]
	v_mfma_f32_16x16x32_bf16 v[44:47], v[92:95], v[112:115], v[44:47]
	v_mfma_f32_16x16x32_bf16 v[48:51], v[96:99], v[100:103], v[48:51]
	v_mfma_f32_16x16x32_bf16 v[52:55], v[96:99], v[104:107], v[52:55]
	v_mfma_f32_16x16x32_bf16 v[56:59], v[96:99], v[108:111], v[56:59]
	s_add_u32 m0, s30, 0x16000
	v_lshl_add_u64 v[126:127], v[74:75], 0, s[24:25]
	global_load_lds_dwordx4 v[126:127], off
	v_mfma_f32_16x16x32_bf16 v[60:63], v[96:99], v[112:115], v[60:63]
	s_waitcnt vmcnt(6) lgkmcnt(0)
	s_barrier
	ds_read_b128 v[84:87], v76
	ds_read_b128 v[88:91], v76 offset:2048
	ds_read_b128 v[92:95], v76 offset:4096
	ds_read_b128 v[96:99], v76 offset:6144
	ds_read_b128 v[100:103], v78
	ds_read_b128 v[104:107], v78 offset:2048
	ds_read_b128 v[108:111], v78 offset:4096
	ds_read_b128 v[112:115], v78 offset:6144
	v_mfma_f32_16x16x32_bf16 v[0:3], v[136:139], v[152:155], v[0:3]
	v_mfma_f32_16x16x32_bf16 v[4:7], v[136:139], v[156:159], v[4:7]
	v_mfma_f32_16x16x32_bf16 v[8:11], v[136:139], v[160:163], v[8:11]
	v_mfma_f32_16x16x32_bf16 v[12:15], v[136:139], v[164:167], v[12:15]
	v_mfma_f32_16x16x32_bf16 v[16:19], v[140:143], v[152:155], v[16:19]
	s_mov_b32 s24, 0x400
	s_mov_b32 s25, 0
	s_add_u32 m0, s30, 0x18000
	v_lshl_add_u64 v[124:125], v[64:65], 0, s[24:25]
	global_load_lds_dwordx4 v[124:125], off
	v_mfma_f32_16x16x32_bf16 v[20:23], v[140:143], v[156:159], v[20:23]
	v_mfma_f32_16x16x32_bf16 v[24:27], v[140:143], v[160:163], v[24:27]
	v_mfma_f32_16x16x32_bf16 v[28:31], v[140:143], v[164:167], v[28:31]
	v_mfma_f32_16x16x32_bf16 v[32:35], v[144:147], v[152:155], v[32:35]
	v_mfma_f32_16x16x32_bf16 v[36:39], v[144:147], v[156:159], v[36:39]
	s_add_u32 m0, s30, 0x1a000
	v_lshl_add_u64 v[126:127], v[66:67], 0, s[24:25]
	global_load_lds_dwordx4 v[126:127], off
	v_mfma_f32_16x16x32_bf16 v[40:43], v[144:147], v[160:163], v[40:43]
	v_mfma_f32_16x16x32_bf16 v[44:47], v[144:147], v[164:167], v[44:47]
	v_mfma_f32_16x16x32_bf16 v[48:51], v[148:151], v[152:155], v[48:51]
	v_mfma_f32_16x16x32_bf16 v[52:55], v[148:151], v[156:159], v[52:55]
	v_mfma_f32_16x16x32_bf16 v[56:59], v[148:151], v[160:163], v[56:59]
	s_add_u32 m0, s30, 0x1c000
	v_lshl_add_u64 v[124:125], v[68:69], 0, s[24:25]
	global_load_lds_dwordx4 v[124:125], off
	v_mfma_f32_16x16x32_bf16 v[60:63], v[148:151], v[164:167], v[60:63]
	ds_read_b128 v[136:139], v77
	ds_read_b128 v[140:143], v77 offset:2048
	ds_read_b128 v[144:147], v77 offset:4096
	ds_read_b128 v[148:151], v77 offset:6144
	ds_read_b128 v[152:155], v79
	ds_read_b128 v[156:159], v79 offset:2048
	ds_read_b128 v[160:163], v79 offset:4096
	ds_read_b128 v[164:167], v79 offset:6144
	s_waitcnt lgkmcnt(8)
;     ...
;   for (int kt = 0; kt < nk; ++kt) {
;     if (kt + 1 < nk) asm volatile("s_waitcnt vmcnt(6)" ::: "memory");
;     else asm volatile("s_waitcnt vmcnt(0)" ::: "memory");
;     __builtin_amdgcn_s_barrier();
;     asm volatile("" ::: "memory");
;     if (kt + 2 < nk) { const int st2 = (st >= 1) ? st - 1 : 2; GEMM_ISSUE(kt + 2, st2); }
;     const char* la = lds + st * STAGE_B;
;     const char* lb = la + 32768;
;     const unsigned sa_u = (unsigned)(size_t)la + arow_u, sb_u = (unsigned)(size_t)lb + brow_u;
;     const unsigned a0 = sa_u + co0, a1 = sa_u + co1, a2 = sa_u + co2, a3 = sa_u + co3;
;     const unsigned b0 = sb_u + co0, b1 = sb_u + co1, b2 = sb_u + co2, b3 = sb_u + co3;
;     {
;       bf16x8 p0, p1, q0, q1, u0, u1, w0, w1;
;       asm volatile(
;         "ds_read_b128 %4, %12\n\tds_read_b128 %5, %12 offset:4096\n\tds_read_b128 %6, %16\n\tds_read_b128 %7, %16 offset:4096\n\t"
;         "ds_read_b128 %8, %13\n\tds_read_b128 %9, %13 offset:4096\n\tds_read_b128 %10, %17\n\tds_read_b128 %11, %17 offset:4096\n\t"
;         "s_waitcnt lgkmcnt(4)\n\t"
;         "v_mfma_f32_32x32x16_bf16 %0, %4, %6, %0\n\tv_mfma_f32_32x32x16_bf16 %1, %4, %7, %1\n\tv_mfma_f32_32x32x16_bf16 %2, %5, %6, %2\n\tv_mfma_f32_32x32x16_bf16 %3, %5, %7, %3\n\t"
;         "ds_read_b128 %4, %14\n\tds_read_b128 %5, %14 offset:4096\n\tds_read_b128 %6, %18\n\tds_read_b128 %7, %18 offset:4096\n\t"
;         "s_waitcnt lgkmcnt(4)\n\t"
;         "v_mfma_f32_32x32x16_bf16 %0, %8, %10, %0\n\tv_mfma_f32_32x32x16_bf16 %1, %8, %11, %1\n\tv_mfma_f32_32x32x16_bf16 %2, %9, %10, %2\n\tv_mfma_f32_32x32x16_bf16 %3, %9, %11, %3\n\t"
;         "ds_read_b128 %8, %15\n\tds_read_b128 %9, %15 offset:4096\n\tds_read_b128 %10, %19\n\tds_read_b128 %11, %19 offset:4096\n\t"
;         "s_waitcnt lgkmcnt(4)\n\t"
;         "v_mfma_f32_32x32x16_bf16 %0, %4, %6, %0\n\tv_mfma_f32_32x32x16_bf16 %1, %4, %7, %1\n\tv_mfma_f32_32x32x16_bf16 %2, %5, %6, %2\n\tv_mfma_f32_32x32x16_bf16 %3, %5, %7, %3\n\t"
;         "s_waitcnt lgkmcnt(0)\n\t"
;         "v_mfma_f32_32x32x16_bf16 %0, %8, %10, %0\n\tv_mfma_f32_32x32x16_bf16 %1, %8, %11, %1\n\tv_mfma_f32_32x32x16_bf16 %2, %9, %10, %2\n\tv_mfma_f32_32x32x16_bf16 %3, %9, %11, %3"
	v_mfma_f32_16x16x32_bf16 v[0:3], v[84:87], v[100:103], v[0:3]
	v_mfma_f32_16x16x32_bf16 v[4:7], v[84:87], v[104:107], v[4:7]
	v_mfma_f32_16x16x32_bf16 v[8:11], v[84:87], v[108:111], v[8:11]
	v_mfma_f32_16x16x32_bf16 v[12:15], v[84:87], v[112:115], v[12:15]
	v_mfma_f32_16x16x32_bf16 v[16:19], v[88:91], v[100:103], v[16:19]
	s_add_u32 m0, s30, 0x1e000
	v_lshl_add_u64 v[126:127], v[70:71], 0, s[24:25]
	global_load_lds_dwordx4 v[126:127], off
	v_mfma_f32_16x16x32_bf16 v[20:23], v[88:91], v[104:107], v[20:23]
	v_mfma_f32_16x16x32_bf16 v[24:27], v[88:91], v[108:111], v[24:27]
	v_mfma_f32_16x16x32_bf16 v[28:31], v[88:91], v[112:115], v[28:31]
	v_mfma_f32_16x16x32_bf16 v[32:35], v[92:95], v[100:103], v[32:35]
	v_mfma_f32_16x16x32_bf16 v[36:39], v[92:95], v[104:107], v[36:39]
	s_add_u32 m0, s30, 0x20000
	v_lshl_add_u64 v[124:125], v[72:73], 0, s[24:25]
	global_load_lds_dwordx4 v[124:125], off
	v_mfma_f32_16x16x32_bf16 v[40:43], v[92:95], v[108:111], v[40:43]
	v_mfma_f32_16x16x32_bf16 v[44:47], v[92:95], v[112:115], v[44:47]
	v_mfma_f32_16x16x32_bf16 v[48:51], v[96:99], v[100:103], v[48:51]
	v_mfma_f32_16x16x32_bf16 v[52:55], v[96:99], v[104:107], v[52:55]
	v_mfma_f32_16x16x32_bf16 v[56:59], v[96:99], v[108:111], v[56:59]
	s_add_u32 m0, s30, 0x22000
	v_lshl_add_u64 v[126:127], v[74:75], 0, s[24:25]
	global_load_lds_dwordx4 v[126:127], off
	v_mfma_f32_16x16x32_bf16 v[60:63], v[96:99], v[112:115], v[60:63]
	s_waitcnt vmcnt(6) lgkmcnt(0)
	s_barrier
	ds_read_b128 v[84:87], v76 offset:49152
	ds_read_b128 v[88:91], v76 offset:51200
	ds_read_b128 v[92:95], v76 offset:53248
	ds_read_b128 v[96:99], v76 offset:55296
	ds_read_b128 v[100:103], v78 offset:49152
	ds_read_b128 v[104:107], v78 offset:51200
	ds_read_b128 v[108:111], v78 offset:53248
	ds_read_b128 v[112:115], v78 offset:55296
	v_mfma_f32_16x16x32_bf16 v[0:3], v[136:139], v[152:155], v[0:3]
	v_mfma_f32_16x16x32_bf16 v[4:7], v[136:139], v[156:159], v[4:7]
	v_mfma_f32_16x16x32_bf16 v[8:11], v[136:139], v[160:163], v[8:11]
	v_mfma_f32_16x16x32_bf16 v[12:15], v[136:139], v[164:167], v[12:15]
	v_mfma_f32_16x16x32_bf16 v[16:19], v[140:143], v[152:155], v[16:19]
	s_mov_b32 s24, 0x480
	s_mov_b32 s25, 0
	s_mov_b32 m0, s30
	v_lshl_add_u64 v[124:125], v[64:65], 0, s[24:25]
	global_load_lds_dwordx4 v[124:125], off
	v_mfma_f32_16x16x32_bf16 v[20:23], v[140:143], v[156:159], v[20:23]
	v_mfma_f32_16x16x32_bf16 v[24:27], v[140:143], v[160:163], v[24:27]
	v_mfma_f32_16x16x32_bf16 v[28:31], v[140:143], v[164:167], v[28:31]
	v_mfma_f32_16x16x32_bf16 v[32:35], v[144:147], v[152:155], v[32:35]
	v_mfma_f32_16x16x32_bf16 v[36:39], v[144:147], v[156:159], v[36:39]
	s_add_u32 m0, s30, 0x2000
	v_lshl_add_u64 v[126:127], v[66:67], 0, s[24:25]
	global_load_lds_dwordx4 v[126:127], off
	v_mfma_f32_16x16x32_bf16 v[40:43], v[144:147], v[160:163], v[40:43]
	v_mfma_f32_16x16x32_bf16 v[44:47], v[144:147], v[164:167], v[44:47]
	v_mfma_f32_16x16x32_bf16 v[48:51], v[148:151], v[152:155], v[48:51]
	v_mfma_f32_16x16x32_bf16 v[52:55], v[148:151], v[156:159], v[52:55]
	v_mfma_f32_16x16x32_bf16 v[56:59], v[148:151], v[160:163], v[56:59]
	s_add_u32 m0, s30, 0x4000
	v_lshl_add_u64 v[124:125], v[68:69], 0, s[24:25]
	global_load_lds_dwordx4 v[124:125], off
	v_mfma_f32_16x16x32_bf16 v[60:63], v[148:151], v[164:167], v[60:63]
	ds_read_b128 v[136:139], v77 offset:49152
	ds_read_b128 v[140:143], v77 offset:51200
	ds_read_b128 v[144:147], v77 offset:53248
	ds_read_b128 v[148:151], v77 offset:55296
	ds_read_b128 v[152:155], v79 offset:49152
	ds_read_b128 v[156:159], v79 offset:51200
	ds_read_b128 v[160:163], v79 offset:53248
	ds_read_b128 v[164:167], v79 offset:55296
	s_waitcnt lgkmcnt(8)
	v_mfma_f32_16x16x32_bf16 v[0:3], v[84:87], v[100:103], v[0:3]
	v_mfma_f32_16x16x32_bf16 v[4:7], v[84:87], v[104:107], v[4:7]
	v_mfma_f32_16x16x32_bf16 v[8:11], v[84:87], v[108:111], v[8:11]
	v_mfma_f32_16x16x32_bf16 v[12:15], v[84:87], v[112:115], v[12:15]
	v_mfma_f32_16x16x32_bf16 v[16:19], v[88:91], v[100:103], v[16:19]
	s_add_u32 m0, s30, 0x6000
	v_lshl_add_u64 v[126:127], v[70:71], 0, s[24:25]
	global_load_lds_dwordx4 v[126:127], off
	v_mfma_f32_16x16x32_bf16 v[20:23], v[88:91], v[104:107], v[20:23]
	v_mfma_f32_16x16x32_bf16 v[24:27], v[88:91], v[108:111], v[24:27]
	v_mfma_f32_16x16x32_bf16 v[28:31], v[88:91], v[112:115], v[28:31]
	v_mfma_f32_16x16x32_bf16 v[32:35], v[92:95], v[100:103], v[32:35]
	v_mfma_f32_16x16x32_bf16 v[36:39], v[92:95], v[104:107], v[36:39]
	s_add_u32 m0, s30, 0x8000
	v_lshl_add_u64 v[124:125], v[72:73], 0, s[24:25]
	global_load_lds_dwordx4 v[124:125], off
	v_mfma_f32_16x16x32_bf16 v[40:43], v[92:95], v[108:111], v[40:43]
	v_mfma_f32_16x16x32_bf16 v[44:47], v[92:95], v[112:115], v[44:47]
	v_mfma_f32_16x16x32_bf16 v[48:51], v[96:99], v[100:103], v[48:51]
	v_mfma_f32_16x16x32_bf16 v[52:55], v[96:99], v[104:107], v[52:55]
	v_mfma_f32_16x16x32_bf16 v[56:59], v[96:99], v[108:111], v[56:59]
	s_add_u32 m0, s30, 0xa000
	v_lshl_add_u64 v[126:127], v[74:75], 0, s[24:25]
	global_load_lds_dwordx4 v[126:127], off
	v_mfma_f32_16x16x32_bf16 v[60:63], v[96:99], v[112:115], v[60:63]
	s_waitcnt vmcnt(6) lgkmcnt(0)
	s_barrier
;     ...
;   for (int kt = 0; kt < nk; ++kt) {
;     if (kt + 1 < nk) asm volatile("s_waitcnt vmcnt(6)" ::: "memory");
;     else asm volatile("s_waitcnt vmcnt(0)" ::: "memory");
;     __builtin_amdgcn_s_barrier();
;     asm volatile("" ::: "memory");
;     if (kt + 2 < nk) { const int st2 = (st >= 1) ? st - 1 : 2; GEMM_ISSUE(kt + 2, st2); }
;     const char* la = lds + st * STAGE_B;
;     const char* lb = la + 32768;
;     const unsigned sa_u = (unsigned)(size_t)la + arow_u, sb_u = (unsigned)(size_t)lb + brow_u;
;     const unsigned a0 = sa_u + co0, a1 = sa_u + co1, a2 = sa_u + co2, a3 = sa_u + co3;
;     const unsigned b0 = sb_u + co0, b1 = sb_u + co1, b2 = sb_u + co2, b3 = sb_u + co3;
;     {
;       bf16x8 p0, p1, q0, q1, u0, u1, w0, w1;
;       asm volatile(
;         "ds_read_b128 %4, %12\n\tds_read_b128 %5, %12 offset:4096\n\tds_read_b128 %6, %16\n\tds_read_b128 %7, %16 offset:4096\n\t"
;         "ds_read_b128 %8, %13\n\tds_read_b128 %9, %13 offset:4096\n\tds_read_b128 %10, %17\n\tds_read_b128 %11, %17 offset:4096\n\t"
;         "s_waitcnt lgkmcnt(4)\n\t"
;         "v_mfma_f32_32x32x16_bf16 %0, %4, %6, %0\n\tv_mfma_f32_32x32x16_bf16 %1, %4, %7, %1\n\tv_mfma_f32_32x32x16_bf16 %2, %5, %6, %2\n\tv_mfma_f32_32x32x16_bf16 %3, %5, %7, %3\n\t"
;         "ds_read_b128 %4, %14\n\tds_read_b128 %5, %14 offset:4096\n\tds_read_b128 %6, %18\n\tds_read_b128 %7, %18 offset:4096\n\t"
;         "s_waitcnt lgkmcnt(4)\n\t"
;         "v_mfma_f32_32x32x16_bf16 %0, %8, %10, %0\n\tv_mfma_f32_32x32x16_bf16 %1, %8, %11, %1\n\tv_mfma_f32_32x32x16_bf16 %2, %9, %10, %2\n\tv_mfma_f32_32x32x16_bf16 %3, %9, %11, %3\n\t"
;         "ds_read_b128 %8, %15\n\tds_read_b128 %9, %15 offset:4096\n\tds_read_b128 %10, %19\n\tds_read_b128 %11, %19 offset:4096\n\t"
;         "s_waitcnt lgkmcnt(4)\n\t"
;         "v_mfma_f32_32x32x16_bf16 %0, %4, %6, %0\n\tv_mfma_f32_32x32x16_bf16 %1, %4, %7, %1\n\tv_mfma_f32_32x32x16_bf16 %2, %5, %6, %2\n\tv_mfma_f32_32x32x16_bf16 %3, %5, %7, %3\n\t"
;         "s_waitcnt lgkmcnt(0)\n\t"
;         "v_mfma_f32_32x32x16_bf16 %0, %8, %10, %0\n\tv_mfma_f32_32x32x16_bf16 %1, %8, %11, %1\n\tv_mfma_f32_32x32x16_bf16 %2, %9, %10, %2\n\tv_mfma_f32_32x32x16_bf16 %3, %9, %11, %3"
	ds_read_b128 v[84:87], v80
	ds_read_b128 v[88:91], v80 offset:2048
	ds_read_b128 v[92:95], v80 offset:4096
	ds_read_b128 v[96:99], v80 offset:6144
	ds_read_b128 v[100:103], v82
	ds_read_b128 v[104:107], v82 offset:2048
	ds_read_b128 v[108:111], v82 offset:4096
	ds_read_b128 v[112:115], v82 offset:6144
	v_mfma_f32_16x16x32_bf16 v[0:3], v[136:139], v[152:155], v[0:3]
	v_mfma_f32_16x16x32_bf16 v[4:7], v[136:139], v[156:159], v[4:7]
	v_mfma_f32_16x16x32_bf16 v[8:11], v[136:139], v[160:163], v[8:11]
	v_mfma_f32_16x16x32_bf16 v[12:15], v[136:139], v[164:167], v[12:15]
	v_mfma_f32_16x16x32_bf16 v[16:19], v[140:143], v[152:155], v[16:19]
	s_mov_b32 s24, 0x500
	s_mov_b32 s25, 0
	s_add_u32 m0, s30, 0xc000
	v_lshl_add_u64 v[124:125], v[64:65], 0, s[24:25]
	global_load_lds_dwordx4 v[124:125], off
	v_mfma_f32_16x16x32_bf16 v[20:23], v[140:143], v[156:159], v[20:23]
	v_mfma_f32_16x16x32_bf16 v[24:27], v[140:143], v[160:163], v[24:27]
	v_mfma_f32_16x16x32_bf16 v[28:31], v[140:143], v[164:167], v[28:31]
	v_mfma_f32_16x16x32_bf16 v[32:35], v[144:147], v[152:155], v[32:35]
	v_mfma_f32_16x16x32_bf16 v[36:39], v[144:147], v[156:159], v[36:39]
	s_add_u32 m0, s30, 0xe000
	v_lshl_add_u64 v[126:127], v[66:67], 0, s[24:25]
	global_load_lds_dwordx4 v[126:127], off
	v_mfma_f32_16x16x32_bf16 v[40:43], v[144:147], v[160:163], v[40:43]
	v_mfma_f32_16x16x32_bf16 v[44:47], v[144:147], v[164:167], v[44:47]
	v_mfma_f32_16x16x32_bf16 v[48:51], v[148:151], v[152:155], v[48:51]
	v_mfma_f32_16x16x32_bf16 v[52:55], v[148:151], v[156:159], v[52:55]
	v_mfma_f32_16x16x32_bf16 v[56:59], v[148:151], v[160:163], v[56:59]
	s_add_u32 m0, s30, 0x10000
	v_lshl_add_u64 v[124:125], v[68:69], 0, s[24:25]
	global_load_lds_dwordx4 v[124:125], off
	v_mfma_f32_16x16x32_bf16 v[60:63], v[148:151], v[164:167], v[60:63]
	ds_read_b128 v[136:139], v81
	ds_read_b128 v[140:143], v81 offset:2048
	ds_read_b128 v[144:147], v81 offset:4096
	ds_read_b128 v[148:151], v81 offset:6144
	ds_read_b128 v[152:155], v83
	ds_read_b128 v[156:159], v83 offset:2048
	ds_read_b128 v[160:163], v83 offset:4096
	ds_read_b128 v[164:167], v83 offset:6144
	s_waitcnt lgkmcnt(8)
	v_mfma_f32_16x16x32_bf16 v[0:3], v[84:87], v[100:103], v[0:3]
	v_mfma_f32_16x16x32_bf16 v[4:7], v[84:87], v[104:107], v[4:7]
	v_mfma_f32_16x16x32_bf16 v[8:11], v[84:87], v[108:111], v[8:11]
	v_mfma_f32_16x16x32_bf16 v[12:15], v[84:87], v[112:115], v[12:15]
	v_mfma_f32_16x16x32_bf16 v[16:19], v[88:91], v[100:103], v[16:19]
	s_add_u32 m0, s30, 0x12000
	v_lshl_add_u64 v[126:127], v[70:71], 0, s[24:25]
	global_load_lds_dwordx4 v[126:127], off
	v_mfma_f32_16x16x32_bf16 v[20:23], v[88:91], v[104:107], v[20:23]
	v_mfma_f32_16x16x32_bf16 v[24:27], v[88:91], v[108:111], v[24:27]
	v_mfma_f32_16x16x32_bf16 v[28:31], v[88:91], v[112:115], v[28:31]
	v_mfma_f32_16x16x32_bf16 v[32:35], v[92:95], v[100:103], v[32:35]
	v_mfma_f32_16x16x32_bf16 v[36:39], v[92:95], v[104:107], v[36:39]
	s_add_u32 m0, s30, 0x14000
	v_lshl_add_u64 v[124:125], v[72:73], 0, s[24:25]
	global_load_lds_dwordx4 v[124:125], off
	v_mfma_f32_16x16x32_bf16 v[40:43], v[92:95], v[108:111], v[40:43]
	v_mfma_f32_16x16x32_bf16 v[44:47], v[92:95], v[112:115], v[44:47]
	v_mfma_f32_16x16x32_bf16 v[48:51], v[96:99], v[100:103], v[48:51]
	v_mfma_f32_16x16x32_bf16 v[52:55], v[96:99], v[104:107], v[52:55]
	v_mfma_f32_16x16x32_bf16 v[56:59], v[96:99], v[108:111], v[56:59]
	s_add_u32 m0, s30, 0x16000
	v_lshl_add_u64 v[126:127], v[74:75], 0, s[24:25]
	global_load_lds_dwordx4 v[126:127], off
	v_mfma_f32_16x16x32_bf16 v[60:63], v[96:99], v[112:115], v[60:63]
	s_waitcnt vmcnt(6) lgkmcnt(0)
	s_barrier
	ds_read_b128 v[84:87], v76
	ds_read_b128 v[88:91], v76 offset:2048
	ds_read_b128 v[92:95], v76 offset:4096
	ds_read_b128 v[96:99], v76 offset:6144
	ds_read_b128 v[100:103], v78
	ds_read_b128 v[104:107], v78 offset:2048
	ds_read_b128 v[108:111], v78 offset:4096
	ds_read_b128 v[112:115], v78 offset:6144
	v_mfma_f32_16x16x32_bf16 v[0:3], v[136:139], v[152:155], v[0:3]
	v_mfma_f32_16x16x32_bf16 v[4:7], v[136:139], v[156:159], v[4:7]
	v_mfma_f32_16x16x32_bf16 v[8:11], v[136:139], v[160:163], v[8:11]
	v_mfma_f32_16x16x32_bf16 v[12:15], v[136:139], v[164:167], v[12:15]
	v_mfma_f32_16x16x32_bf16 v[16:19], v[140:143], v[152:155], v[16:19]
	s_mov_b32 s24, 0x580
	s_mov_b32 s25, 0
	s_add_u32 m0, s30, 0x18000
	v_lshl_add_u64 v[124:125], v[64:65], 0, s[24:25]
	global_load_lds_dwordx4 v[124:125], off
	v_mfma_f32_16x16x32_bf16 v[20:23], v[140:143], v[156:159], v[20:23]
	v_mfma_f32_16x16x32_bf16 v[24:27], v[140:143], v[160:163], v[24:27]
	v_mfma_f32_16x16x32_bf16 v[28:31], v[140:143], v[164:167], v[28:31]
	v_mfma_f32_16x16x32_bf16 v[32:35], v[144:147], v[152:155], v[32:35]
	v_mfma_f32_16x16x32_bf16 v[36:39], v[144:147], v[156:159], v[36:39]
	s_add_u32 m0, s30, 0x1a000
	v_lshl_add_u64 v[126:127], v[66:67], 0, s[24:25]
	global_load_lds_dwordx4 v[126:127], off
	v_mfma_f32_16x16x32_bf16 v[40:43], v[144:147], v[160:163], v[40:43]
	v_mfma_f32_16x16x32_bf16 v[44:47], v[144:147], v[164:167], v[44:47]
	v_mfma_f32_16x16x32_bf16 v[48:51], v[148:151], v[152:155], v[48:51]
	v_mfma_f32_16x16x32_bf16 v[52:55], v[148:151], v[156:159], v[52:55]
	v_mfma_f32_16x16x32_bf16 v[56:59], v[148:151], v[160:163], v[56:59]
	s_add_u32 m0, s30, 0x1c000
	v_lshl_add_u64 v[124:125], v[68:69], 0, s[24:25]
	global_load_lds_dwordx4 v[124:125], off
	v_mfma_f32_16x16x32_bf16 v[60:63], v[148:151], v[164:167], v[60:63]
	ds_read_b128 v[136:139], v77
	ds_read_b128 v[140:143], v77 offset:2048
	ds_read_b128 v[144:147], v77 offset:4096
	ds_read_b128 v[148:151], v77 offset:6144
	ds_read_b128 v[152:155], v79
	ds_read_b128 v[156:159], v79 offset:2048
	ds_read_b128 v[160:163], v79 offset:4096
	ds_read_b128 v[164:167], v79 offset:6144
	s_waitcnt lgkmcnt(8)
;     ...
;   for (int kt = 0; kt < nk; ++kt) {
;     if (kt + 1 < nk) asm volatile("s_waitcnt vmcnt(6)" ::: "memory");
;     else asm volatile("s_waitcnt vmcnt(0)" ::: "memory");
;     __builtin_amdgcn_s_barrier();
;     asm volatile("" ::: "memory");
;     if (kt + 2 < nk) { const int st2 = (st >= 1) ? st - 1 : 2; GEMM_ISSUE(kt + 2, st2); }
;     const char* la = lds + st * STAGE_B;
;     const char* lb = la + 32768;
;     const unsigned sa_u = (unsigned)(size_t)la + arow_u, sb_u = (unsigned)(size_t)lb + brow_u;
;     const unsigned a0 = sa_u + co0, a1 = sa_u + co1, a2 = sa_u + co2, a3 = sa_u + co3;
;     const unsigned b0 = sb_u + co0, b1 = sb_u + co1, b2 = sb_u + co2, b3 = sb_u + co3;
;     {
;       bf16x8 p0, p1, q0, q1, u0, u1, w0, w1;
;       asm volatile(
;         "ds_read_b128 %4, %12\n\tds_read_b128 %5, %12 offset:4096\n\tds_read_b128 %6, %16\n\tds_read_b128 %7, %16 offset:4096\n\t"
;         "ds_read_b128 %8, %13\n\tds_read_b128 %9, %13 offset:4096\n\tds_read_b128 %10, %17\n\tds_read_b128 %11, %17 offset:4096\n\t"
;         "s_waitcnt lgkmcnt(4)\n\t"
;         "v_mfma_f32_32x32x16_bf16 %0, %4, %6, %0\n\tv_mfma_f32_32x32x16_bf16 %1, %4, %7, %1\n\tv_mfma_f32_32x32x16_bf16 %2, %5, %6, %2\n\tv_mfma_f32_32x32x16_bf16 %3, %5, %7, %3\n\t"
;         "ds_read_b128 %4, %14\n\tds_read_b128 %5, %14 offset:4096\n\tds_read_b128 %6, %18\n\tds_read_b128 %7, %18 offset:4096\n\t"
;         "s_waitcnt lgkmcnt(4)\n\t"
;         "v_mfma_f32_32x32x16_bf16 %0, %8, %10, %0\n\tv_mfma_f32_32x32x16_bf16 %1, %8, %11, %1\n\tv_mfma_f32_32x32x16_bf16 %2, %9, %10, %2\n\tv_mfma_f32_32x32x16_bf16 %3, %9, %11, %3\n\t"
;         "ds_read_b128 %8, %15\n\tds_read_b128 %9, %15 offset:4096\n\tds_read_b128 %10, %19\n\tds_read_b128 %11, %19 offset:4096\n\t"
;         "s_waitcnt lgkmcnt(4)\n\t"
;         "v_mfma_f32_32x32x16_bf16 %0, %4, %6, %0\n\tv_mfma_f32_32x32x16_bf16 %1, %4, %7, %1\n\tv_mfma_f32_32x32x16_bf16 %2, %5, %6, %2\n\tv_mfma_f32_32x32x16_bf16 %3, %5, %7, %3\n\t"
;         "s_waitcnt lgkmcnt(0)\n\t"
;         "v_mfma_f32_32x32x16_bf16 %0, %8, %10, %0\n\tv_mfma_f32_32x32x16_bf16 %1, %8, %11, %1\n\tv_mfma_f32_32x32x16_bf16 %2, %9, %10, %2\n\tv_mfma_f32_32x32x16_bf16 %3, %9, %11, %3"
	v_mfma_f32_16x16x32_bf16 v[0:3], v[84:87], v[100:103], v[0:3]
	v_mfma_f32_16x16x32_bf16 v[4:7], v[84:87], v[104:107], v[4:7]
	v_mfma_f32_16x16x32_bf16 v[8:11], v[84:87], v[108:111], v[8:11]
	v_mfma_f32_16x16x32_bf16 v[12:15], v[84:87], v[112:115], v[12:15]
	v_mfma_f32_16x16x32_bf16 v[16:19], v[88:91], v[100:103], v[16:19]
	s_add_u32 m0, s30, 0x1e000
	v_lshl_add_u64 v[126:127], v[70:71], 0, s[24:25]
	global_load_lds_dwordx4 v[126:127], off
	v_mfma_f32_16x16x32_bf16 v[20:23], v[88:91], v[104:107], v[20:23]
	v_mfma_f32_16x16x32_bf16 v[24:27], v[88:91], v[108:111], v[24:27]
	v_mfma_f32_16x16x32_bf16 v[28:31], v[88:91], v[112:115], v[28:31]
	v_mfma_f32_16x16x32_bf16 v[32:35], v[92:95], v[100:103], v[32:35]
	v_mfma_f32_16x16x32_bf16 v[36:39], v[92:95], v[104:107], v[36:39]
	s_add_u32 m0, s30, 0x20000
	v_lshl_add_u64 v[124:125], v[72:73], 0, s[24:25]
	global_load_lds_dwordx4 v[124:125], off
	v_mfma_f32_16x16x32_bf16 v[40:43], v[92:95], v[108:111], v[40:43]
	v_mfma_f32_16x16x32_bf16 v[44:47], v[92:95], v[112:115], v[44:47]
	v_mfma_f32_16x16x32_bf16 v[48:51], v[96:99], v[100:103], v[48:51]
	v_mfma_f32_16x16x32_bf16 v[52:55], v[96:99], v[104:107], v[52:55]
	v_mfma_f32_16x16x32_bf16 v[56:59], v[96:99], v[108:111], v[56:59]
	s_add_u32 m0, s30, 0x22000
	v_lshl_add_u64 v[126:127], v[74:75], 0, s[24:25]
	global_load_lds_dwordx4 v[126:127], off
	v_mfma_f32_16x16x32_bf16 v[60:63], v[96:99], v[112:115], v[60:63]
	s_waitcnt vmcnt(6) lgkmcnt(0)
	s_barrier
	ds_read_b128 v[84:87], v76 offset:49152
	ds_read_b128 v[88:91], v76 offset:51200
	ds_read_b128 v[92:95], v76 offset:53248
	ds_read_b128 v[96:99], v76 offset:55296
	ds_read_b128 v[100:103], v78 offset:49152
	ds_read_b128 v[104:107], v78 offset:51200
	ds_read_b128 v[108:111], v78 offset:53248
	ds_read_b128 v[112:115], v78 offset:55296
	v_mfma_f32_16x16x32_bf16 v[0:3], v[136:139], v[152:155], v[0:3]
	v_mfma_f32_16x16x32_bf16 v[4:7], v[136:139], v[156:159], v[4:7]
	v_mfma_f32_16x16x32_bf16 v[8:11], v[136:139], v[160:163], v[8:11]
	v_mfma_f32_16x16x32_bf16 v[12:15], v[136:139], v[164:167], v[12:15]
	v_mfma_f32_16x16x32_bf16 v[16:19], v[140:143], v[152:155], v[16:19]
	s_mov_b32 s24, 0x600
	s_mov_b32 s25, 0
	s_mov_b32 m0, s30
	v_lshl_add_u64 v[124:125], v[64:65], 0, s[24:25]
	global_load_lds_dwordx4 v[124:125], off
	v_mfma_f32_16x16x32_bf16 v[20:23], v[140:143], v[156:159], v[20:23]
	v_mfma_f32_16x16x32_bf16 v[24:27], v[140:143], v[160:163], v[24:27]
	v_mfma_f32_16x16x32_bf16 v[28:31], v[140:143], v[164:167], v[28:31]
	v_mfma_f32_16x16x32_bf16 v[32:35], v[144:147], v[152:155], v[32:35]
	v_mfma_f32_16x16x32_bf16 v[36:39], v[144:147], v[156:159], v[36:39]
	s_add_u32 m0, s30, 0x2000
	v_lshl_add_u64 v[126:127], v[66:67], 0, s[24:25]
	global_load_lds_dwordx4 v[126:127], off
	v_mfma_f32_16x16x32_bf16 v[40:43], v[144:147], v[160:163], v[40:43]
	v_mfma_f32_16x16x32_bf16 v[44:47], v[144:147], v[164:167], v[44:47]
	v_mfma_f32_16x16x32_bf16 v[48:51], v[148:151], v[152:155], v[48:51]
	v_mfma_f32_16x16x32_bf16 v[52:55], v[148:151], v[156:159], v[52:55]
	v_mfma_f32_16x16x32_bf16 v[56:59], v[148:151], v[160:163], v[56:59]
	s_add_u32 m0, s30, 0x4000
	v_lshl_add_u64 v[124:125], v[68:69], 0, s[24:25]
	global_load_lds_dwordx4 v[124:125], off
	v_mfma_f32_16x16x32_bf16 v[60:63], v[148:151], v[164:167], v[60:63]
	ds_read_b128 v[136:139], v77 offset:49152
	ds_read_b128 v[140:143], v77 offset:51200
	ds_read_b128 v[144:147], v77 offset:53248
	ds_read_b128 v[148:151], v77 offset:55296
	ds_read_b128 v[152:155], v79 offset:49152
	ds_read_b128 v[156:159], v79 offset:51200
	ds_read_b128 v[160:163], v79 offset:53248
	ds_read_b128 v[164:167], v79 offset:55296
	s_waitcnt lgkmcnt(8)
	v_mfma_f32_16x16x32_bf16 v[0:3], v[84:87], v[100:103], v[0:3]
	v_mfma_f32_16x16x32_bf16 v[4:7], v[84:87], v[104:107], v[4:7]
	v_mfma_f32_16x16x32_bf16 v[8:11], v[84:87], v[108:111], v[8:11]
	v_mfma_f32_16x16x32_bf16 v[12:15], v[84:87], v[112:115], v[12:15]
	v_mfma_f32_16x16x32_bf16 v[16:19], v[88:91], v[100:103], v[16:19]
	s_add_u32 m0, s30, 0x6000
	v_lshl_add_u64 v[126:127], v[70:71], 0, s[24:25]
	global_load_lds_dwordx4 v[126:127], off
	v_mfma_f32_16x16x32_bf16 v[20:23], v[88:91], v[104:107], v[20:23]
	v_mfma_f32_16x16x32_bf16 v[24:27], v[88:91], v[108:111], v[24:27]
	v_mfma_f32_16x16x32_bf16 v[28:31], v[88:91], v[112:115], v[28:31]
	v_mfma_f32_16x16x32_bf16 v[32:35], v[92:95], v[100:103], v[32:35]
	v_mfma_f32_16x16x32_bf16 v[36:39], v[92:95], v[104:107], v[36:39]
	s_add_u32 m0, s30, 0x8000
	v_lshl_add_u64 v[124:125], v[72:73], 0, s[24:25]
	global_load_lds_dwordx4 v[124:125], off
	v_mfma_f32_16x16x32_bf16 v[40:43], v[92:95], v[108:111], v[40:43]
	v_mfma_f32_16x16x32_bf16 v[44:47], v[92:95], v[112:115], v[44:47]
	v_mfma_f32_16x16x32_bf16 v[48:51], v[96:99], v[100:103], v[48:51]
	v_mfma_f32_16x16x32_bf16 v[52:55], v[96:99], v[104:107], v[52:55]
	v_mfma_f32_16x16x32_bf16 v[56:59], v[96:99], v[108:111], v[56:59]
	s_add_u32 m0, s30, 0xa000
	v_lshl_add_u64 v[126:127], v[74:75], 0, s[24:25]
	global_load_lds_dwordx4 v[126:127], off
	v_mfma_f32_16x16x32_bf16 v[60:63], v[96:99], v[112:115], v[60:63]
	s_waitcnt vmcnt(6) lgkmcnt(0)
	s_barrier
;     ...
;   for (int kt = 0; kt < nk; ++kt) {
;     if (kt + 1 < nk) asm volatile("s_waitcnt vmcnt(6)" ::: "memory");
;     else asm volatile("s_waitcnt vmcnt(0)" ::: "memory");
;     __builtin_amdgcn_s_barrier();
;     asm volatile("" ::: "memory");
;     if (kt + 2 < nk) { const int st2 = (st >= 1) ? st - 1 : 2; GEMM_ISSUE(kt + 2, st2); }
;     const char* la = lds + st * STAGE_B;
;     const char* lb = la + 32768;
;     const unsigned sa_u = (unsigned)(size_t)la + arow_u, sb_u = (unsigned)(size_t)lb + brow_u;
;     const unsigned a0 = sa_u + co0, a1 = sa_u + co1, a2 = sa_u + co2, a3 = sa_u + co3;
;     const unsigned b0 = sb_u + co0, b1 = sb_u + co1, b2 = sb_u + co2, b3 = sb_u + co3;
;     {
;       bf16x8 p0, p1, q0, q1, u0, u1, w0, w1;
;       asm volatile(
;         "ds_read_b128 %4, %12\n\tds_read_b128 %5, %12 offset:4096\n\tds_read_b128 %6, %16\n\tds_read_b128 %7, %16 offset:4096\n\t"
;         "ds_read_b128 %8, %13\n\tds_read_b128 %9, %13 offset:4096\n\tds_read_b128 %10, %17\n\tds_read_b128 %11, %17 offset:4096\n\t"
;         "s_waitcnt lgkmcnt(4)\n\t"
;         "v_mfma_f32_32x32x16_bf16 %0, %4, %6, %0\n\tv_mfma_f32_32x32x16_bf16 %1, %4, %7, %1\n\tv_mfma_f32_32x32x16_bf16 %2, %5, %6, %2\n\tv_mfma_f32_32x32x16_bf16 %3, %5, %7, %3\n\t"
;         "ds_read_b128 %4, %14\n\tds_read_b128 %5, %14 offset:4096\n\tds_read_b128 %6, %18\n\tds_read_b128 %7, %18 offset:4096\n\t"
;         "s_waitcnt lgkmcnt(4)\n\t"
;         "v_mfma_f32_32x32x16_bf16 %0, %8, %10, %0\n\tv_mfma_f32_32x32x16_bf16 %1, %8, %11, %1\n\tv_mfma_f32_32x32x16_bf16 %2, %9, %10, %2\n\tv_mfma_f32_32x32x16_bf16 %3, %9, %11, %3\n\t"
;         "ds_read_b128 %8, %15\n\tds_read_b128 %9, %15 offset:4096\n\tds_read_b128 %10, %19\n\tds_read_b128 %11, %19 offset:4096\n\t"
;         "s_waitcnt lgkmcnt(4)\n\t"
;         "v_mfma_f32_32x32x16_bf16 %0, %4, %6, %0\n\tv_mfma_f32_32x32x16_bf16 %1, %4, %7, %1\n\tv_mfma_f32_32x32x16_bf16 %2, %5, %6, %2\n\tv_mfma_f32_32x32x16_bf16 %3, %5, %7, %3\n\t"
;         "s_waitcnt lgkmcnt(0)\n\t"
;         "v_mfma_f32_32x32x16_bf16 %0, %8, %10, %0\n\tv_mfma_f32_32x32x16_bf16 %1, %8, %11, %1\n\tv_mfma_f32_32x32x16_bf16 %2, %9, %10, %2\n\tv_mfma_f32_32x32x16_bf16 %3, %9, %11, %3"
	ds_read_b128 v[84:87], v80
	ds_read_b128 v[88:91], v80 offset:2048
	ds_read_b128 v[92:95], v80 offset:4096
	ds_read_b128 v[96:99], v80 offset:6144
	ds_read_b128 v[100:103], v82
	ds_read_b128 v[104:107], v82 offset:2048
	ds_read_b128 v[108:111], v82 offset:4096
	ds_read_b128 v[112:115], v82 offset:6144
	v_mfma_f32_16x16x32_bf16 v[0:3], v[136:139], v[152:155], v[0:3]
	v_mfma_f32_16x16x32_bf16 v[4:7], v[136:139], v[156:159], v[4:7]
	v_mfma_f32_16x16x32_bf16 v[8:11], v[136:139], v[160:163], v[8:11]
	v_mfma_f32_16x16x32_bf16 v[12:15], v[136:139], v[164:167], v[12:15]
	v_mfma_f32_16x16x32_bf16 v[16:19], v[140:143], v[152:155], v[16:19]
	s_mov_b32 s24, 0x680
	s_mov_b32 s25, 0
	s_add_u32 m0, s30, 0xc000
	v_lshl_add_u64 v[124:125], v[64:65], 0, s[24:25]
	global_load_lds_dwordx4 v[124:125], off
	v_mfma_f32_16x16x32_bf16 v[20:23], v[140:143], v[156:159], v[20:23]
	v_mfma_f32_16x16x32_bf16 v[24:27], v[140:143], v[160:163], v[24:27]
	v_mfma_f32_16x16x32_bf16 v[28:31], v[140:143], v[164:167], v[28:31]
	v_mfma_f32_16x16x32_bf16 v[32:35], v[144:147], v[152:155], v[32:35]
	v_mfma_f32_16x16x32_bf16 v[36:39], v[144:147], v[156:159], v[36:39]
	s_add_u32 m0, s30, 0xe000
	v_lshl_add_u64 v[126:127], v[66:67], 0, s[24:25]
	global_load_lds_dwordx4 v[126:127], off
	v_mfma_f32_16x16x32_bf16 v[40:43], v[144:147], v[160:163], v[40:43]
	v_mfma_f32_16x16x32_bf16 v[44:47], v[144:147], v[164:167], v[44:47]
	v_mfma_f32_16x16x32_bf16 v[48:51], v[148:151], v[152:155], v[48:51]
	v_mfma_f32_16x16x32_bf16 v[52:55], v[148:151], v[156:159], v[52:55]
	v_mfma_f32_16x16x32_bf16 v[56:59], v[148:151], v[160:163], v[56:59]
	s_add_u32 m0, s30, 0x10000
	v_lshl_add_u64 v[124:125], v[68:69], 0, s[24:25]
	global_load_lds_dwordx4 v[124:125], off
	v_mfma_f32_16x16x32_bf16 v[60:63], v[148:151], v[164:167], v[60:63]
	ds_read_b128 v[136:139], v81
	ds_read_b128 v[140:143], v81 offset:2048
	ds_read_b128 v[144:147], v81 offset:4096
	ds_read_b128 v[148:151], v81 offset:6144
	ds_read_b128 v[152:155], v83
	ds_read_b128 v[156:159], v83 offset:2048
	ds_read_b128 v[160:163], v83 offset:4096
	ds_read_b128 v[164:167], v83 offset:6144
	s_waitcnt lgkmcnt(8)
	v_mfma_f32_16x16x32_bf16 v[0:3], v[84:87], v[100:103], v[0:3]
	v_mfma_f32_16x16x32_bf16 v[4:7], v[84:87], v[104:107], v[4:7]
	v_mfma_f32_16x16x32_bf16 v[8:11], v[84:87], v[108:111], v[8:11]
	v_mfma_f32_16x16x32_bf16 v[12:15], v[84:87], v[112:115], v[12:15]
	v_mfma_f32_16x16x32_bf16 v[16:19], v[88:91], v[100:103], v[16:19]
	s_add_u32 m0, s30, 0x12000
	v_lshl_add_u64 v[126:127], v[70:71], 0, s[24:25]
	global_load_lds_dwordx4 v[126:127], off
	v_mfma_f32_16x16x32_bf16 v[20:23], v[88:91], v[104:107], v[20:23]
	v_mfma_f32_16x16x32_bf16 v[24:27], v[88:91], v[108:111], v[24:27]
	v_mfma_f32_16x16x32_bf16 v[28:31], v[88:91], v[112:115], v[28:31]
	v_mfma_f32_16x16x32_bf16 v[32:35], v[92:95], v[100:103], v[32:35]
	v_mfma_f32_16x16x32_bf16 v[36:39], v[92:95], v[104:107], v[36:39]
	s_add_u32 m0, s30, 0x14000
	v_lshl_add_u64 v[124:125], v[72:73], 0, s[24:25]
	global_load_lds_dwordx4 v[124:125], off
	v_mfma_f32_16x16x32_bf16 v[40:43], v[92:95], v[108:111], v[40:43]
	v_mfma_f32_16x16x32_bf16 v[44:47], v[92:95], v[112:115], v[44:47]
	v_mfma_f32_16x16x32_bf16 v[48:51], v[96:99], v[100:103], v[48:51]
	v_mfma_f32_16x16x32_bf16 v[52:55], v[96:99], v[104:107], v[52:55]
	v_mfma_f32_16x16x32_bf16 v[56:59], v[96:99], v[108:111], v[56:59]
	s_add_u32 m0, s30, 0x16000
	v_lshl_add_u64 v[126:127], v[74:75], 0, s[24:25]
	global_load_lds_dwordx4 v[126:127], off
	v_mfma_f32_16x16x32_bf16 v[60:63], v[96:99], v[112:115], v[60:63]
	s_waitcnt vmcnt(6) lgkmcnt(0)
	s_barrier
	ds_read_b128 v[84:87], v76
	ds_read_b128 v[88:91], v76 offset:2048
	ds_read_b128 v[92:95], v76 offset:4096
	ds_read_b128 v[96:99], v76 offset:6144
	ds_read_b128 v[100:103], v78
	ds_read_b128 v[104:107], v78 offset:2048
	ds_read_b128 v[108:111], v78 offset:4096
	ds_read_b128 v[112:115], v78 offset:6144
	v_mfma_f32_16x16x32_bf16 v[0:3], v[136:139], v[152:155], v[0:3]
	v_mfma_f32_16x16x32_bf16 v[4:7], v[136:139], v[156:159], v[4:7]
	v_mfma_f32_16x16x32_bf16 v[8:11], v[136:139], v[160:163], v[8:11]
	v_mfma_f32_16x16x32_bf16 v[12:15], v[136:139], v[164:167], v[12:15]
	v_mfma_f32_16x16x32_bf16 v[16:19], v[140:143], v[152:155], v[16:19]
	s_mov_b32 s24, 0x700
	s_mov_b32 s25, 0
	s_add_u32 m0, s30, 0x18000
	v_lshl_add_u64 v[124:125], v[64:65], 0, s[24:25]
	global_load_lds_dwordx4 v[124:125], off
	v_mfma_f32_16x16x32_bf16 v[20:23], v[140:143], v[156:159], v[20:23]
	v_mfma_f32_16x16x32_bf16 v[24:27], v[140:143], v[160:163], v[24:27]
	v_mfma_f32_16x16x32_bf16 v[28:31], v[140:143], v[164:167], v[28:31]
	v_mfma_f32_16x16x32_bf16 v[32:35], v[144:147], v[152:155], v[32:35]
	v_mfma_f32_16x16x32_bf16 v[36:39], v[144:147], v[156:159], v[36:39]
	s_add_u32 m0, s30, 0x1a000
	v_lshl_add_u64 v[126:127], v[66:67], 0, s[24:25]
	global_load_lds_dwordx4 v[126:127], off
	v_mfma_f32_16x16x32_bf16 v[40:43], v[144:147], v[160:163], v[40:43]
	v_mfma_f32_16x16x32_bf16 v[44:47], v[144:147], v[164:167], v[44:47]
	v_mfma_f32_16x16x32_bf16 v[48:51], v[148:151], v[152:155], v[48:51]
	v_mfma_f32_16x16x32_bf16 v[52:55], v[148:151], v[156:159], v[52:55]
	v_mfma_f32_16x16x32_bf16 v[56:59], v[148:151], v[160:163], v[56:59]
	s_add_u32 m0, s30, 0x1c000
	v_lshl_add_u64 v[124:125], v[68:69], 0, s[24:25]
	global_load_lds_dwordx4 v[124:125], off
	v_mfma_f32_16x16x32_bf16 v[60:63], v[148:151], v[164:167], v[60:63]
	ds_read_b128 v[136:139], v77
	ds_read_b128 v[140:143], v77 offset:2048
	ds_read_b128 v[144:147], v77 offset:4096
	ds_read_b128 v[148:151], v77 offset:6144
	ds_read_b128 v[152:155], v79
	ds_read_b128 v[156:159], v79 offset:2048
	ds_read_b128 v[160:163], v79 offset:4096
	ds_read_b128 v[164:167], v79 offset:6144
	s_waitcnt lgkmcnt(8)
;     ...
;   for (int kt = 0; kt < nk; ++kt) {
;     if (kt + 1 < nk) asm volatile("s_waitcnt vmcnt(6)" ::: "memory");
;     else asm volatile("s_waitcnt vmcnt(0)" ::: "memory");
;     __builtin_amdgcn_s_barrier();
;     asm volatile("" ::: "memory");
;     if (kt + 2 < nk) { const int st2 = (st >= 1) ? st - 1 : 2; GEMM_ISSUE(kt + 2, st2); }
;     const char* la = lds + st * STAGE_B;
;     const char* lb = la + 32768;
;     const unsigned sa_u = (unsigned)(size_t)la + arow_u, sb_u = (unsigned)(size_t)lb + brow_u;
;     const unsigned a0 = sa_u + co0, a1 = sa_u + co1, a2 = sa_u + co2, a3 = sa_u + co3;
;     const unsigned b0 = sb_u + co0, b1 = sb_u + co1, b2 = sb_u + co2, b3 = sb_u + co3;
;     {
;       bf16x8 p0, p1, q0, q1, u0, u1, w0, w1;
;       asm volatile(
;         "ds_read_b128 %4, %12\n\tds_read_b128 %5, %12 offset:4096\n\tds_read_b128 %6, %16\n\tds_read_b128 %7, %16 offset:4096\n\t"
;         "ds_read_b128 %8, %13\n\tds_read_b128 %9, %13 offset:4096\n\tds_read_b128 %10, %17\n\tds_read_b128 %11, %17 offset:4096\n\t"
;         "s_waitcnt lgkmcnt(4)\n\t"
;         "v_mfma_f32_32x32x16_bf16 %0, %4, %6, %0\n\tv_mfma_f32_32x32x16_bf16 %1, %4, %7, %1\n\tv_mfma_f32_32x32x16_bf16 %2, %5, %6, %2\n\tv_mfma_f32_32x32x16_bf16 %3, %5, %7, %3\n\t"
;         "ds_read_b128 %4, %14\n\tds_read_b128 %5, %14 offset:4096\n\tds_read_b128 %6, %18\n\tds_read_b128 %7, %18 offset:4096\n\t"
;         "s_waitcnt lgkmcnt(4)\n\t"
;         "v_mfma_f32_32x32x16_bf16 %0, %8, %10, %0\n\tv_mfma_f32_32x32x16_bf16 %1, %8, %11, %1\n\tv_mfma_f32_32x32x16_bf16 %2, %9, %10, %2\n\tv_mfma_f32_32x32x16_bf16 %3, %9, %11, %3\n\t"
;         "ds_read_b128 %8, %15\n\tds_read_b128 %9, %15 offset:4096\n\tds_read_b128 %10, %19\n\tds_read_b128 %11, %19 offset:4096\n\t"
;         "s_waitcnt lgkmcnt(4)\n\t"
;         "v_mfma_f32_32x32x16_bf16 %0, %4, %6, %0\n\tv_mfma_f32_32x32x16_bf16 %1, %4, %7, %1\n\tv_mfma_f32_32x32x16_bf16 %2, %5, %6, %2\n\tv_mfma_f32_32x32x16_bf16 %3, %5, %7, %3\n\t"
;         "s_waitcnt lgkmcnt(0)\n\t"
;         "v_mfma_f32_32x32x16_bf16 %0, %8, %10, %0\n\tv_mfma_f32_32x32x16_bf16 %1, %8, %11, %1\n\tv_mfma_f32_32x32x16_bf16 %2, %9, %10, %2\n\tv_mfma_f32_32x32x16_bf16 %3, %9, %11, %3"
	v_mfma_f32_16x16x32_bf16 v[0:3], v[84:87], v[100:103], v[0:3]
	v_mfma_f32_16x16x32_bf16 v[4:7], v[84:87], v[104:107], v[4:7]
	v_mfma_f32_16x16x32_bf16 v[8:11], v[84:87], v[108:111], v[8:11]
	v_mfma_f32_16x16x32_bf16 v[12:15], v[84:87], v[112:115], v[12:15]
	v_mfma_f32_16x16x32_bf16 v[16:19], v[88:91], v[100:103], v[16:19]
	s_add_u32 m0, s30, 0x1e000
	v_lshl_add_u64 v[126:127], v[70:71], 0, s[24:25]
	global_load_lds_dwordx4 v[126:127], off
	v_mfma_f32_16x16x32_bf16 v[20:23], v[88:91], v[104:107], v[20:23]
	v_mfma_f32_16x16x32_bf16 v[24:27], v[88:91], v[108:111], v[24:27]
	v_mfma_f32_16x16x32_bf16 v[28:31], v[88:91], v[112:115], v[28:31]
	v_mfma_f32_16x16x32_bf16 v[32:35], v[92:95], v[100:103], v[32:35]
	v_mfma_f32_16x16x32_bf16 v[36:39], v[92:95], v[104:107], v[36:39]
	s_add_u32 m0, s30, 0x20000
	v_lshl_add_u64 v[124:125], v[72:73], 0, s[24:25]
	global_load_lds_dwordx4 v[124:125], off
	v_mfma_f32_16x16x32_bf16 v[40:43], v[92:95], v[108:111], v[40:43]
	v_mfma_f32_16x16x32_bf16 v[44:47], v[92:95], v[112:115], v[44:47]
	v_mfma_f32_16x16x32_bf16 v[48:51], v[96:99], v[100:103], v[48:51]
	v_mfma_f32_16x16x32_bf16 v[52:55], v[96:99], v[104:107], v[52:55]
	v_mfma_f32_16x16x32_bf16 v[56:59], v[96:99], v[108:111], v[56:59]
	s_add_u32 m0, s30, 0x22000
	v_lshl_add_u64 v[126:127], v[74:75], 0, s[24:25]
	global_load_lds_dwordx4 v[126:127], off
	v_mfma_f32_16x16x32_bf16 v[60:63], v[96:99], v[112:115], v[60:63]
	s_waitcnt vmcnt(6) lgkmcnt(0)
	s_barrier
	ds_read_b128 v[84:87], v76 offset:49152
	ds_read_b128 v[88:91], v76 offset:51200
	ds_read_b128 v[92:95], v76 offset:53248
	ds_read_b128 v[96:99], v76 offset:55296
	ds_read_b128 v[100:103], v78 offset:49152
	ds_read_b128 v[104:107], v78 offset:51200
	ds_read_b128 v[108:111], v78 offset:53248
	ds_read_b128 v[112:115], v78 offset:55296
	v_mfma_f32_16x16x32_bf16 v[0:3], v[136:139], v[152:155], v[0:3]
	v_mfma_f32_16x16x32_bf16 v[4:7], v[136:139], v[156:159], v[4:7]
	v_mfma_f32_16x16x32_bf16 v[8:11], v[136:139], v[160:163], v[8:11]
	v_mfma_f32_16x16x32_bf16 v[12:15], v[136:139], v[164:167], v[12:15]
	v_mfma_f32_16x16x32_bf16 v[16:19], v[140:143], v[152:155], v[16:19]
	s_mov_b32 s24, 0x780
	s_mov_b32 s25, 0
	s_mov_b32 m0, s30
	v_lshl_add_u64 v[124:125], v[64:65], 0, s[24:25]
	global_load_lds_dwordx4 v[124:125], off
	v_mfma_f32_16x16x32_bf16 v[20:23], v[140:143], v[156:159], v[20:23]
	v_mfma_f32_16x16x32_bf16 v[24:27], v[140:143], v[160:163], v[24:27]
	v_mfma_f32_16x16x32_bf16 v[28:31], v[140:143], v[164:167], v[28:31]
	v_mfma_f32_16x16x32_bf16 v[32:35], v[144:147], v[152:155], v[32:35]
	v_mfma_f32_16x16x32_bf16 v[36:39], v[144:147], v[156:159], v[36:39]
	s_add_u32 m0, s30, 0x2000
	v_lshl_add_u64 v[126:127], v[66:67], 0, s[24:25]
	global_load_lds_dwordx4 v[126:127], off
	v_mfma_f32_16x16x32_bf16 v[40:43], v[144:147], v[160:163], v[40:43]
	v_mfma_f32_16x16x32_bf16 v[44:47], v[144:147], v[164:167], v[44:47]
	v_mfma_f32_16x16x32_bf16 v[48:51], v[148:151], v[152:155], v[48:51]
	v_mfma_f32_16x16x32_bf16 v[52:55], v[148:151], v[156:159], v[52:55]
	v_mfma_f32_16x16x32_bf16 v[56:59], v[148:151], v[160:163], v[56:59]
	s_add_u32 m0, s30, 0x4000
	v_lshl_add_u64 v[124:125], v[68:69], 0, s[24:25]
	global_load_lds_dwordx4 v[124:125], off
	v_mfma_f32_16x16x32_bf16 v[60:63], v[148:151], v[164:167], v[60:63]
	ds_read_b128 v[136:139], v77 offset:49152
	ds_read_b128 v[140:143], v77 offset:51200
	ds_read_b128 v[144:147], v77 offset:53248
	ds_read_b128 v[148:151], v77 offset:55296
	ds_read_b128 v[152:155], v79 offset:49152
	ds_read_b128 v[156:159], v79 offset:51200
	ds_read_b128 v[160:163], v79 offset:53248
	ds_read_b128 v[164:167], v79 offset:55296
	s_waitcnt lgkmcnt(8)
	v_mfma_f32_16x16x32_bf16 v[0:3], v[84:87], v[100:103], v[0:3]
	v_mfma_f32_16x16x32_bf16 v[4:7], v[84:87], v[104:107], v[4:7]
	v_mfma_f32_16x16x32_bf16 v[8:11], v[84:87], v[108:111], v[8:11]
	v_mfma_f32_16x16x32_bf16 v[12:15], v[84:87], v[112:115], v[12:15]
	v_mfma_f32_16x16x32_bf16 v[16:19], v[88:91], v[100:103], v[16:19]
	s_add_u32 m0, s30, 0x6000
	v_lshl_add_u64 v[126:127], v[70:71], 0, s[24:25]
	global_load_lds_dwordx4 v[126:127], off
	v_mfma_f32_16x16x32_bf16 v[20:23], v[88:91], v[104:107], v[20:23]
	v_mfma_f32_16x16x32_bf16 v[24:27], v[88:91], v[108:111], v[24:27]
	v_mfma_f32_16x16x32_bf16 v[28:31], v[88:91], v[112:115], v[28:31]
	v_mfma_f32_16x16x32_bf16 v[32:35], v[92:95], v[100:103], v[32:35]
	v_mfma_f32_16x16x32_bf16 v[36:39], v[92:95], v[104:107], v[36:39]
	s_add_u32 m0, s30, 0x8000
	v_lshl_add_u64 v[124:125], v[72:73], 0, s[24:25]
	global_load_lds_dwordx4 v[124:125], off
	v_mfma_f32_16x16x32_bf16 v[40:43], v[92:95], v[108:111], v[40:43]
	v_mfma_f32_16x16x32_bf16 v[44:47], v[92:95], v[112:115], v[44:47]
	v_mfma_f32_16x16x32_bf16 v[48:51], v[96:99], v[100:103], v[48:51]
	v_mfma_f32_16x16x32_bf16 v[52:55], v[96:99], v[104:107], v[52:55]
	v_mfma_f32_16x16x32_bf16 v[56:59], v[96:99], v[108:111], v[56:59]
	s_add_u32 m0, s30, 0xa000
	v_lshl_add_u64 v[126:127], v[74:75], 0, s[24:25]
	global_load_lds_dwordx4 v[126:127], off
	v_mfma_f32_16x16x32_bf16 v[60:63], v[96:99], v[112:115], v[60:63]
	s_waitcnt vmcnt(6) lgkmcnt(0)
	s_barrier
;     ...
;   if (PART != 2) {
;     GEMM_ISSUE(0, 0);
;     if (nk > 1) GEMM_ISSUE(1, 1);
;   }
;     ...
;   for (int kt = 0; kt < nk; ++kt) {
;     if (kt + 1 < nk) asm volatile("s_waitcnt vmcnt(6)" ::: "memory");
;     else asm volatile("s_waitcnt vmcnt(0)" ::: "memory");
;     __builtin_amdgcn_s_barrier();
;     asm volatile("" ::: "memory");
;     if (kt + 2 < nk) { const int st2 = (st >= 1) ? st - 1 : 2; GEMM_ISSUE(kt + 2, st2); }
;     const char* la = lds + st * STAGE_B;
;     const char* lb = la + 32768;
;     const unsigned sa_u = (unsigned)(size_t)la + arow_u, sb_u = (unsigned)(size_t)lb + brow_u;
;     const unsigned a0 = sa_u + co0, a1 = sa_u + co1, a2 = sa_u + co2, a3 = sa_u + co3;
;     const unsigned b0 = sb_u + co0, b1 = sb_u + co1, b2 = sb_u + co2, b3 = sb_u + co3;
;     {
;       bf16x8 p0, p1, q0, q1, u0, u1, w0, w1;
;       asm volatile(
;         "ds_read_b128 %4, %12\n\tds_read_b128 %5, %12 offset:4096\n\tds_read_b128 %6, %16\n\tds_read_b128 %7, %16 offset:4096\n\t"
;         "ds_read_b128 %8, %13\n\tds_read_b128 %9, %13 offset:4096\n\tds_read_b128 %10, %17\n\tds_read_b128 %11, %17 offset:4096\n\t"
;         "s_waitcnt lgkmcnt(4)\n\t"
;         "v_mfma_f32_32x32x16_bf16 %0, %4, %6, %0\n\tv_mfma_f32_32x32x16_bf16 %1, %4, %7, %1\n\tv_mfma_f32_32x32x16_bf16 %2, %5, %6, %2\n\tv_mfma_f32_32x32x16_bf16 %3, %5, %7, %3\n\t"
;         "ds_read_b128 %4, %14\n\tds_read_b128 %5, %14 offset:4096\n\tds_read_b128 %6, %18\n\tds_read_b128 %7, %18 offset:4096\n\t"
;         "s_waitcnt lgkmcnt(4)\n\t"
;         "v_mfma_f32_32x32x16_bf16 %0, %8, %10, %0\n\tv_mfma_f32_32x32x16_bf16 %1, %8, %11, %1\n\tv_mfma_f32_32x32x16_bf16 %2, %9, %10, %2\n\tv_mfma_f32_32x32x16_bf16 %3, %9, %11, %3\n\t"
;         "ds_read_b128 %8, %15\n\tds_read_b128 %9, %15 offset:4096\n\tds_read_b128 %10, %19\n\tds_read_b128 %11, %19 offset:4096\n\t"
;         "s_waitcnt lgkmcnt(4)\n\t"
;         "v_mfma_f32_32x32x16_bf16 %0, %4, %6, %0\n\tv_mfma_f32_32x32x16_bf16 %1, %4, %7, %1\n\tv_mfma_f32_32x32x16_bf16 %2, %5, %6, %2\n\tv_mfma_f32_32x32x16_bf16 %3, %5, %7, %3\n\t"
;         "s_waitcnt lgkmcnt(0)\n\t"
;         "v_mfma_f32_32x32x16_bf16 %0, %8, %10, %0\n\tv_mfma_f32_32x32x16_bf16 %1, %8, %11, %1\n\tv_mfma_f32_32x32x16_bf16 %2, %9, %10, %2\n\tv_mfma_f32_32x32x16_bf16 %3, %9, %11, %3"
	ds_read_b128 v[84:87], v80
	ds_read_b128 v[88:91], v80 offset:2048
	ds_read_b128 v[92:95], v80 offset:4096
	ds_read_b128 v[96:99], v80 offset:6144
	ds_read_b128 v[100:103], v82
	ds_read_b128 v[104:107], v82 offset:2048
	ds_read_b128 v[108:111], v82 offset:4096
	ds_read_b128 v[112:115], v82 offset:6144
	v_mfma_f32_16x16x32_bf16 v[0:3], v[136:139], v[152:155], v[0:3]
	v_mfma_f32_16x16x32_bf16 v[4:7], v[136:139], v[156:159], v[4:7]
	v_mfma_f32_16x16x32_bf16 v[8:11], v[136:139], v[160:163], v[8:11]
	v_mfma_f32_16x16x32_bf16 v[12:15], v[136:139], v[164:167], v[12:15]
	v_mfma_f32_16x16x32_bf16 v[16:19], v[140:143], v[152:155], v[16:19]
	s_add_u32 s24, s56, 0x0
	s_addc_u32 s25, s57, 0
	s_add_u32 m0, s30, 0xc000
	v_lshl_add_u64 v[124:125], v[64:65], 0, s[24:25]
	global_load_lds_dwordx4 v[124:125], off
	v_mfma_f32_16x16x32_bf16 v[20:23], v[140:143], v[156:159], v[20:23]
	v_mfma_f32_16x16x32_bf16 v[24:27], v[140:143], v[160:163], v[24:27]
	v_mfma_f32_16x16x32_bf16 v[28:31], v[140:143], v[164:167], v[28:31]
	v_mfma_f32_16x16x32_bf16 v[32:35], v[144:147], v[152:155], v[32:35]
	v_mfma_f32_16x16x32_bf16 v[36:39], v[144:147], v[156:159], v[36:39]
	s_add_u32 m0, s30, 0xe000
	v_lshl_add_u64 v[126:127], v[66:67], 0, s[24:25]
	global_load_lds_dwordx4 v[126:127], off
	v_mfma_f32_16x16x32_bf16 v[40:43], v[144:147], v[160:163], v[40:43]
	v_mfma_f32_16x16x32_bf16 v[44:47], v[144:147], v[164:167], v[44:47]
	v_mfma_f32_16x16x32_bf16 v[48:51], v[148:151], v[152:155], v[48:51]
	v_mfma_f32_16x16x32_bf16 v[52:55], v[148:151], v[156:159], v[52:55]
	v_mfma_f32_16x16x32_bf16 v[56:59], v[148:151], v[160:163], v[56:59]
	s_add_u32 m0, s30, 0x10000
	v_lshl_add_u64 v[124:125], v[68:69], 0, s[24:25]
	global_load_lds_dwordx4 v[124:125], off
	v_mfma_f32_16x16x32_bf16 v[60:63], v[148:151], v[164:167], v[60:63]
	ds_read_b128 v[136:139], v81
	ds_read_b128 v[140:143], v81 offset:2048
	ds_read_b128 v[144:147], v81 offset:4096
	ds_read_b128 v[148:151], v81 offset:6144
	ds_read_b128 v[152:155], v83
	ds_read_b128 v[156:159], v83 offset:2048
	ds_read_b128 v[160:163], v83 offset:4096
	ds_read_b128 v[164:167], v83 offset:6144
	s_waitcnt lgkmcnt(8)
	v_mfma_f32_16x16x32_bf16 v[0:3], v[84:87], v[100:103], v[0:3]
	v_mfma_f32_16x16x32_bf16 v[4:7], v[84:87], v[104:107], v[4:7]
	v_mfma_f32_16x16x32_bf16 v[8:11], v[84:87], v[108:111], v[8:11]
	v_mfma_f32_16x16x32_bf16 v[12:15], v[84:87], v[112:115], v[12:15]
	v_mfma_f32_16x16x32_bf16 v[16:19], v[88:91], v[100:103], v[16:19]
	s_add_u32 m0, s30, 0x12000
	v_lshl_add_u64 v[126:127], v[70:71], 0, s[24:25]
	global_load_lds_dwordx4 v[126:127], off
	v_mfma_f32_16x16x32_bf16 v[20:23], v[88:91], v[104:107], v[20:23]
	v_mfma_f32_16x16x32_bf16 v[24:27], v[88:91], v[108:111], v[24:27]
	v_mfma_f32_16x16x32_bf16 v[28:31], v[88:91], v[112:115], v[28:31]
	v_mfma_f32_16x16x32_bf16 v[32:35], v[92:95], v[100:103], v[32:35]
	v_mfma_f32_16x16x32_bf16 v[36:39], v[92:95], v[104:107], v[36:39]
	s_add_u32 s24, s58, 0x0
	s_addc_u32 s25, s59, 0
	s_add_u32 m0, s30, 0x14000
	v_lshl_add_u64 v[124:125], v[72:73], 0, s[24:25]
	global_load_lds_dwordx4 v[124:125], off
	v_mfma_f32_16x16x32_bf16 v[40:43], v[92:95], v[108:111], v[40:43]
	v_mfma_f32_16x16x32_bf16 v[44:47], v[92:95], v[112:115], v[44:47]
	v_mfma_f32_16x16x32_bf16 v[48:51], v[96:99], v[100:103], v[48:51]
	v_mfma_f32_16x16x32_bf16 v[52:55], v[96:99], v[104:107], v[52:55]
	v_mfma_f32_16x16x32_bf16 v[56:59], v[96:99], v[108:111], v[56:59]
	s_add_u32 m0, s30, 0x16000
	v_lshl_add_u64 v[126:127], v[74:75], 0, s[24:25]
	global_load_lds_dwordx4 v[126:127], off
	v_mfma_f32_16x16x32_bf16 v[60:63], v[96:99], v[112:115], v[60:63]
	s_waitcnt vmcnt(6) lgkmcnt(0)
	s_barrier
	ds_read_b128 v[84:87], v76
	ds_read_b128 v[88:91], v76 offset:2048
	ds_read_b128 v[92:95], v76 offset:4096
	ds_read_b128 v[96:99], v76 offset:6144
	ds_read_b128 v[100:103], v78
	ds_read_b128 v[104:107], v78 offset:2048
	ds_read_b128 v[108:111], v78 offset:4096
	ds_read_b128 v[112:115], v78 offset:6144
	v_mfma_f32_16x16x32_bf16 v[0:3], v[136:139], v[152:155], v[0:3]
	v_mfma_f32_16x16x32_bf16 v[4:7], v[136:139], v[156:159], v[4:7]
	v_mfma_f32_16x16x32_bf16 v[8:11], v[136:139], v[160:163], v[8:11]
	v_mfma_f32_16x16x32_bf16 v[12:15], v[136:139], v[164:167], v[12:15]
	v_mfma_f32_16x16x32_bf16 v[16:19], v[140:143], v[152:155], v[16:19]
	s_add_u32 s24, s56, 0x80
	s_addc_u32 s25, s57, 0
	s_add_u32 m0, s30, 0x18000
	v_lshl_add_u64 v[124:125], v[64:65], 0, s[24:25]
	global_load_lds_dwordx4 v[124:125], off
	v_mfma_f32_16x16x32_bf16 v[20:23], v[140:143], v[156:159], v[20:23]
	v_mfma_f32_16x16x32_bf16 v[24:27], v[140:143], v[160:163], v[24:27]
	v_mfma_f32_16x16x32_bf16 v[28:31], v[140:143], v[164:167], v[28:31]
	v_mfma_f32_16x16x32_bf16 v[32:35], v[144:147], v[152:155], v[32:35]
	v_mfma_f32_16x16x32_bf16 v[36:39], v[144:147], v[156:159], v[36:39]
	s_add_u32 m0, s30, 0x1a000
	v_lshl_add_u64 v[126:127], v[66:67], 0, s[24:25]
	global_load_lds_dwordx4 v[126:127], off
	v_mfma_f32_16x16x32_bf16 v[40:43], v[144:147], v[160:163], v[40:43]
	v_mfma_f32_16x16x32_bf16 v[44:47], v[144:147], v[164:167], v[44:47]
	v_mfma_f32_16x16x32_bf16 v[48:51], v[148:151], v[152:155], v[48:51]
	v_mfma_f32_16x16x32_bf16 v[52:55], v[148:151], v[156:159], v[52:55]
	v_mfma_f32_16x16x32_bf16 v[56:59], v[148:151], v[160:163], v[56:59]
	s_add_u32 m0, s30, 0x1c000
	v_lshl_add_u64 v[124:125], v[68:69], 0, s[24:25]
	global_load_lds_dwordx4 v[124:125], off
	v_mfma_f32_16x16x32_bf16 v[60:63], v[148:151], v[164:167], v[60:63]
	ds_read_b128 v[136:139], v77
	ds_read_b128 v[140:143], v77 offset:2048
	ds_read_b128 v[144:147], v77 offset:4096
	ds_read_b128 v[148:151], v77 offset:6144
	ds_read_b128 v[152:155], v79
	ds_read_b128 v[156:159], v79 offset:2048
	ds_read_b128 v[160:163], v79 offset:4096
	ds_read_b128 v[164:167], v79 offset:6144
	s_waitcnt lgkmcnt(8)
;     ...
;   for (int kt = 0; kt < nk; ++kt) {
;     if (kt + 1 < nk) asm volatile("s_waitcnt vmcnt(6)" ::: "memory");
;     else asm volatile("s_waitcnt vmcnt(0)" ::: "memory");
;     __builtin_amdgcn_s_barrier();
;     asm volatile("" ::: "memory");
;     if (kt + 2 < nk) { const int st2 = (st >= 1) ? st - 1 : 2; GEMM_ISSUE(kt + 2, st2); }
;     const char* la = lds + st * STAGE_B;
;     const char* lb = la + 32768;
;     const unsigned sa_u = (unsigned)(size_t)la + arow_u, sb_u = (unsigned)(size_t)lb + brow_u;
;     const unsigned a0 = sa_u + co0, a1 = sa_u + co1, a2 = sa_u + co2, a3 = sa_u + co3;
;     const unsigned b0 = sb_u + co0, b1 = sb_u + co1, b2 = sb_u + co2, b3 = sb_u + co3;
;     {
;       bf16x8 p0, p1, q0, q1, u0, u1, w0, w1;
;       asm volatile(
;         "ds_read_b128 %4, %12\n\tds_read_b128 %5, %12 offset:4096\n\tds_read_b128 %6, %16\n\tds_read_b128 %7, %16 offset:4096\n\t"
;         "ds_read_b128 %8, %13\n\tds_read_b128 %9, %13 offset:4096\n\tds_read_b128 %10, %17\n\tds_read_b128 %11, %17 offset:4096\n\t"
;         "s_waitcnt lgkmcnt(4)\n\t"
;         "v_mfma_f32_32x32x16_bf16 %0, %4, %6, %0\n\tv_mfma_f32_32x32x16_bf16 %1, %4, %7, %1\n\tv_mfma_f32_32x32x16_bf16 %2, %5, %6, %2\n\tv_mfma_f32_32x32x16_bf16 %3, %5, %7, %3\n\t"
;         "ds_read_b128 %4, %14\n\tds_read_b128 %5, %14 offset:4096\n\tds_read_b128 %6, %18\n\tds_read_b128 %7, %18 offset:4096\n\t"
;         "s_waitcnt lgkmcnt(4)\n\t"
;         "v_mfma_f32_32x32x16_bf16 %0, %8, %10, %0\n\tv_mfma_f32_32x32x16_bf16 %1, %8, %11, %1\n\tv_mfma_f32_32x32x16_bf16 %2, %9, %10, %2\n\tv_mfma_f32_32x32x16_bf16 %3, %9, %11, %3\n\t"
;         "ds_read_b128 %8, %15\n\tds_read_b128 %9, %15 offset:4096\n\tds_read_b128 %10, %19\n\tds_read_b128 %11, %19 offset:4096\n\t"
;         "s_waitcnt lgkmcnt(4)\n\t"
;         "v_mfma_f32_32x32x16_bf16 %0, %4, %6, %0\n\tv_mfma_f32_32x32x16_bf16 %1, %4, %7, %1\n\tv_mfma_f32_32x32x16_bf16 %2, %5, %6, %2\n\tv_mfma_f32_32x32x16_bf16 %3, %5, %7, %3\n\t"
;         "s_waitcnt lgkmcnt(0)\n\t"
;         "v_mfma_f32_32x32x16_bf16 %0, %8, %10, %0\n\tv_mfma_f32_32x32x16_bf16 %1, %8, %11, %1\n\tv_mfma_f32_32x32x16_bf16 %2, %9, %10, %2\n\tv_mfma_f32_32x32x16_bf16 %3, %9, %11, %3"
	v_mfma_f32_16x16x32_bf16 v[0:3], v[84:87], v[100:103], v[0:3]
	v_mfma_f32_16x16x32_bf16 v[4:7], v[84:87], v[104:107], v[4:7]
	v_mfma_f32_16x16x32_bf16 v[8:11], v[84:87], v[108:111], v[8:11]
	v_mfma_f32_16x16x32_bf16 v[12:15], v[84:87], v[112:115], v[12:15]
	v_mfma_f32_16x16x32_bf16 v[16:19], v[88:91], v[100:103], v[16:19]
	s_add_u32 m0, s30, 0x1e000
	v_lshl_add_u64 v[126:127], v[70:71], 0, s[24:25]
	global_load_lds_dwordx4 v[126:127], off
	v_mfma_f32_16x16x32_bf16 v[20:23], v[88:91], v[104:107], v[20:23]
	v_mfma_f32_16x16x32_bf16 v[24:27], v[88:91], v[108:111], v[24:27]
	v_mfma_f32_16x16x32_bf16 v[28:31], v[88:91], v[112:115], v[28:31]
	v_mfma_f32_16x16x32_bf16 v[32:35], v[92:95], v[100:103], v[32:35]
	v_mfma_f32_16x16x32_bf16 v[36:39], v[92:95], v[104:107], v[36:39]
	s_add_u32 s24, s58, 0x80
	s_addc_u32 s25, s59, 0
	s_add_u32 m0, s30, 0x20000
	v_lshl_add_u64 v[124:125], v[72:73], 0, s[24:25]
	global_load_lds_dwordx4 v[124:125], off
	v_mfma_f32_16x16x32_bf16 v[40:43], v[92:95], v[108:111], v[40:43]
	v_mfma_f32_16x16x32_bf16 v[44:47], v[92:95], v[112:115], v[44:47]
	v_mfma_f32_16x16x32_bf16 v[48:51], v[96:99], v[100:103], v[48:51]
	v_mfma_f32_16x16x32_bf16 v[52:55], v[96:99], v[104:107], v[52:55]
	v_mfma_f32_16x16x32_bf16 v[56:59], v[96:99], v[108:111], v[56:59]
	s_add_u32 m0, s30, 0x22000
	v_lshl_add_u64 v[126:127], v[74:75], 0, s[24:25]
	global_load_lds_dwordx4 v[126:127], off
	v_mfma_f32_16x16x32_bf16 v[60:63], v[96:99], v[112:115], v[60:63]
	s_waitcnt lgkmcnt(0)
	v_mfma_f32_16x16x32_bf16 v[0:3], v[136:139], v[152:155], v[0:3]
	v_mfma_f32_16x16x32_bf16 v[4:7], v[136:139], v[156:159], v[4:7]
	v_mfma_f32_16x16x32_bf16 v[8:11], v[136:139], v[160:163], v[8:11]
	v_mfma_f32_16x16x32_bf16 v[12:15], v[136:139], v[164:167], v[12:15]
	v_mfma_f32_16x16x32_bf16 v[16:19], v[140:143], v[152:155], v[16:19]
	v_mfma_f32_16x16x32_bf16 v[20:23], v[140:143], v[156:159], v[20:23]
	v_mfma_f32_16x16x32_bf16 v[24:27], v[140:143], v[160:163], v[24:27]
	v_mfma_f32_16x16x32_bf16 v[28:31], v[140:143], v[164:167], v[28:31]
	v_mfma_f32_16x16x32_bf16 v[32:35], v[144:147], v[152:155], v[32:35]
	v_mfma_f32_16x16x32_bf16 v[36:39], v[144:147], v[156:159], v[36:39]
	v_mfma_f32_16x16x32_bf16 v[40:43], v[144:147], v[160:163], v[40:43]
	v_mfma_f32_16x16x32_bf16 v[44:47], v[144:147], v[164:167], v[44:47]
	v_mfma_f32_16x16x32_bf16 v[48:51], v[148:151], v[152:155], v[48:51]
	v_mfma_f32_16x16x32_bf16 v[52:55], v[148:151], v[156:159], v[52:55]
	v_mfma_f32_16x16x32_bf16 v[56:59], v[148:151], v[160:163], v[56:59]
	v_mfma_f32_16x16x32_bf16 v[60:63], v[148:151], v[164:167], v[60:63]
	s_branch .Ly11_done
.Ly11_v1:
	ds_read_b128 v[84:87], v76 offset:49152
	ds_read_b128 v[88:91], v76 offset:51200
	ds_read_b128 v[92:95], v76 offset:53248
	ds_read_b128 v[96:99], v76 offset:55296
	ds_read_b128 v[100:103], v78 offset:49152
	ds_read_b128 v[104:107], v78 offset:51200
	ds_read_b128 v[108:111], v78 offset:53248
	ds_read_b128 v[112:115], v78 offset:55296
	s_mov_b32 s24, 0x100
	s_mov_b32 s25, 0
	s_mov_b32 m0, s30
	v_lshl_add_u64 v[124:125], v[64:65], 0, s[24:25]
	global_load_lds_dwordx4 v[124:125], off
	s_add_u32 m0, s30, 0x2000
	v_lshl_add_u64 v[126:127], v[66:67], 0, s[24:25]
	global_load_lds_dwordx4 v[126:127], off
	s_add_u32 m0, s30, 0x4000
	v_lshl_add_u64 v[124:125], v[68:69], 0, s[24:25]
	global_load_lds_dwordx4 v[124:125], off
	ds_read_b128 v[136:139], v77 offset:49152
	ds_read_b128 v[140:143], v77 offset:51200
	ds_read_b128 v[144:147], v77 offset:53248
	ds_read_b128 v[148:151], v77 offset:55296
	ds_read_b128 v[152:155], v79 offset:49152
	ds_read_b128 v[156:159], v79 offset:51200
	ds_read_b128 v[160:163], v79 offset:53248
	ds_read_b128 v[164:167], v79 offset:55296
	s_waitcnt lgkmcnt(8)
	v_mfma_f32_16x16x32_bf16 v[0:3], v[84:87], v[100:103], v[0:3]
	v_mfma_f32_16x16x32_bf16 v[4:7], v[84:87], v[104:107], v[4:7]
	v_mfma_f32_16x16x32_bf16 v[8:11], v[84:87], v[108:111], v[8:11]
	v_mfma_f32_16x16x32_bf16 v[12:15], v[84:87], v[112:115], v[12:15]
	v_mfma_f32_16x16x32_bf16 v[16:19], v[88:91], v[100:103], v[16:19]
	s_add_u32 m0, s30, 0x6000
	v_lshl_add_u64 v[126:127], v[70:71], 0, s[24:25]
	global_load_lds_dwordx4 v[126:127], off
	v_mfma_f32_16x16x32_bf16 v[20:23], v[88:91], v[104:107], v[20:23]
	v_mfma_f32_16x16x32_bf16 v[24:27], v[88:91], v[108:111], v[24:27]
	v_mfma_f32_16x16x32_bf16 v[28:31], v[88:91], v[112:115], v[28:31]
	v_mfma_f32_16x16x32_bf16 v[32:35], v[92:95], v[100:103], v[32:35]
	v_mfma_f32_16x16x32_bf16 v[36:39], v[92:95], v[104:107], v[36:39]
	s_add_u32 m0, s30, 0x8000
	v_lshl_add_u64 v[124:125], v[72:73], 0, s[24:25]
	global_load_lds_dwordx4 v[124:125], off
	v_mfma_f32_16x16x32_bf16 v[40:43], v[92:95], v[108:111], v[40:43]
	v_mfma_f32_16x16x32_bf16 v[44:47], v[92:95], v[112:115], v[44:47]
	v_mfma_f32_16x16x32_bf16 v[48:51], v[96:99], v[100:103], v[48:51]
	v_mfma_f32_16x16x32_bf16 v[52:55], v[96:99], v[104:107], v[52:55]
	v_mfma_f32_16x16x32_bf16 v[56:59], v[96:99], v[108:111], v[56:59]
	s_add_u32 m0, s30, 0xa000
	v_lshl_add_u64 v[126:127], v[74:75], 0, s[24:25]
	global_load_lds_dwordx4 v[126:127], off
	v_mfma_f32_16x16x32_bf16 v[60:63], v[96:99], v[112:115], v[60:63]
	s_waitcnt vmcnt(6) lgkmcnt(0)
	s_barrier
;     ...
;   for (int kt = 0; kt < nk; ++kt) {
;     if (kt + 1 < nk) asm volatile("s_waitcnt vmcnt(6)" ::: "memory");
;     else asm volatile("s_waitcnt vmcnt(0)" ::: "memory");
;     __builtin_amdgcn_s_barrier();
;     asm volatile("" ::: "memory");
;     if (kt + 2 < nk) { const int st2 = (st >= 1) ? st - 1 : 2; GEMM_ISSUE(kt + 2, st2); }
;     const char* la = lds + st * STAGE_B;
;     const char* lb = la + 32768;
;     const unsigned sa_u = (unsigned)(size_t)la + arow_u, sb_u = (unsigned)(size_t)lb + brow_u;
;     const unsigned a0 = sa_u + co0, a1 = sa_u + co1, a2 = sa_u + co2, a3 = sa_u + co3;
;     const unsigned b0 = sb_u + co0, b1 = sb_u + co1, b2 = sb_u + co2, b3 = sb_u + co3;
;     {
;       bf16x8 p0, p1, q0, q1, u0, u1, w0, w1;
;       asm volatile(
;         "ds_read_b128 %4, %12\n\tds_read_b128 %5, %12 offset:4096\n\tds_read_b128 %6, %16\n\tds_read_b128 %7, %16 offset:4096\n\t"
;         "ds_read_b128 %8, %13\n\tds_read_b128 %9, %13 offset:4096\n\tds_read_b128 %10, %17\n\tds_read_b128 %11, %17 offset:4096\n\t"
;         "s_waitcnt lgkmcnt(4)\n\t"
;         "v_mfma_f32_32x32x16_bf16 %0, %4, %6, %0\n\tv_mfma_f32_32x32x16_bf16 %1, %4, %7, %1\n\tv_mfma_f32_32x32x16_bf16 %2, %5, %6, %2\n\tv_mfma_f32_32x32x16_bf16 %3, %5, %7, %3\n\t"
;         "ds_read_b128 %4, %14\n\tds_read_b128 %5, %14 offset:4096\n\tds_read_b128 %6, %18\n\tds_read_b128 %7, %18 offset:4096\n\t"
;         "s_waitcnt lgkmcnt(4)\n\t"
;         "v_mfma_f32_32x32x16_bf16 %0, %8, %10, %0\n\tv_mfma_f32_32x32x16_bf16 %1, %8, %11, %1\n\tv_mfma_f32_32x32x16_bf16 %2, %9, %10, %2\n\tv_mfma_f32_32x32x16_bf16 %3, %9, %11, %3\n\t"
;         "ds_read_b128 %8, %15\n\tds_read_b128 %9, %15 offset:4096\n\tds_read_b128 %10, %19\n\tds_read_b128 %11, %19 offset:4096\n\t"
;         "s_waitcnt lgkmcnt(4)\n\t"
;         "v_mfma_f32_32x32x16_bf16 %0, %4, %6, %0\n\tv_mfma_f32_32x32x16_bf16 %1, %4, %7, %1\n\tv_mfma_f32_32x32x16_bf16 %2, %5, %6, %2\n\tv_mfma_f32_32x32x16_bf16 %3, %5, %7, %3\n\t"
;         "s_waitcnt lgkmcnt(0)\n\t"
;         "v_mfma_f32_32x32x16_bf16 %0, %8, %10, %0\n\tv_mfma_f32_32x32x16_bf16 %1, %8, %11, %1\n\tv_mfma_f32_32x32x16_bf16 %2, %9, %10, %2\n\tv_mfma_f32_32x32x16_bf16 %3, %9, %11, %3"
	ds_read_b128 v[84:87], v80
	ds_read_b128 v[88:91], v80 offset:2048
	ds_read_b128 v[92:95], v80 offset:4096
	ds_read_b128 v[96:99], v80 offset:6144
	ds_read_b128 v[100:103], v82
	ds_read_b128 v[104:107], v82 offset:2048
	ds_read_b128 v[108:111], v82 offset:4096
	ds_read_b128 v[112:115], v82 offset:6144
	v_mfma_f32_16x16x32_bf16 v[0:3], v[136:139], v[152:155], v[0:3]
	v_mfma_f32_16x16x32_bf16 v[4:7], v[136:139], v[156:159], v[4:7]
	v_mfma_f32_16x16x32_bf16 v[8:11], v[136:139], v[160:163], v[8:11]
	v_mfma_f32_16x16x32_bf16 v[12:15], v[136:139], v[164:167], v[12:15]
	v_mfma_f32_16x16x32_bf16 v[16:19], v[140:143], v[152:155], v[16:19]
	s_mov_b32 s24, 0x180
	s_mov_b32 s25, 0
	s_add_u32 m0, s30, 0xc000
	v_lshl_add_u64 v[124:125], v[64:65], 0, s[24:25]
	global_load_lds_dwordx4 v[124:125], off
	v_mfma_f32_16x16x32_bf16 v[20:23], v[140:143], v[156:159], v[20:23]
	v_mfma_f32_16x16x32_bf16 v[24:27], v[140:143], v[160:163], v[24:27]
	v_mfma_f32_16x16x32_bf16 v[28:31], v[140:143], v[164:167], v[28:31]
	v_mfma_f32_16x16x32_bf16 v[32:35], v[144:147], v[152:155], v[32:35]
	v_mfma_f32_16x16x32_bf16 v[36:39], v[144:147], v[156:159], v[36:39]
	s_add_u32 m0, s30, 0xe000
	v_lshl_add_u64 v[126:127], v[66:67], 0, s[24:25]
	global_load_lds_dwordx4 v[126:127], off
	v_mfma_f32_16x16x32_bf16 v[40:43], v[144:147], v[160:163], v[40:43]
	v_mfma_f32_16x16x32_bf16 v[44:47], v[144:147], v[164:167], v[44:47]
	v_mfma_f32_16x16x32_bf16 v[48:51], v[148:151], v[152:155], v[48:51]
	v_mfma_f32_16x16x32_bf16 v[52:55], v[148:151], v[156:159], v[52:55]
	v_mfma_f32_16x16x32_bf16 v[56:59], v[148:151], v[160:163], v[56:59]
	s_add_u32 m0, s30, 0x10000
	v_lshl_add_u64 v[124:125], v[68:69], 0, s[24:25]
	global_load_lds_dwordx4 v[124:125], off
	v_mfma_f32_16x16x32_bf16 v[60:63], v[148:151], v[164:167], v[60:63]
	ds_read_b128 v[136:139], v81
	ds_read_b128 v[140:143], v81 offset:2048
	ds_read_b128 v[144:147], v81 offset:4096
	ds_read_b128 v[148:151], v81 offset:6144
	ds_read_b128 v[152:155], v83
	ds_read_b128 v[156:159], v83 offset:2048
	ds_read_b128 v[160:163], v83 offset:4096
	ds_read_b128 v[164:167], v83 offset:6144
	s_waitcnt lgkmcnt(8)
	v_mfma_f32_16x16x32_bf16 v[0:3], v[84:87], v[100:103], v[0:3]
	v_mfma_f32_16x16x32_bf16 v[4:7], v[84:87], v[104:107], v[4:7]
	v_mfma_f32_16x16x32_bf16 v[8:11], v[84:87], v[108:111], v[8:11]
	v_mfma_f32_16x16x32_bf16 v[12:15], v[84:87], v[112:115], v[12:15]
	v_mfma_f32_16x16x32_bf16 v[16:19], v[88:91], v[100:103], v[16:19]
	s_add_u32 m0, s30, 0x12000
	v_lshl_add_u64 v[126:127], v[70:71], 0, s[24:25]
	global_load_lds_dwordx4 v[126:127], off
	v_mfma_f32_16x16x32_bf16 v[20:23], v[88:91], v[104:107], v[20:23]
	v_mfma_f32_16x16x32_bf16 v[24:27], v[88:91], v[108:111], v[24:27]
	v_mfma_f32_16x16x32_bf16 v[28:31], v[88:91], v[112:115], v[28:31]
	v_mfma_f32_16x16x32_bf16 v[32:35], v[92:95], v[100:103], v[32:35]
	v_mfma_f32_16x16x32_bf16 v[36:39], v[92:95], v[104:107], v[36:39]
	s_add_u32 m0, s30, 0x14000
	v_lshl_add_u64 v[124:125], v[72:73], 0, s[24:25]
	global_load_lds_dwordx4 v[124:125], off
	v_mfma_f32_16x16x32_bf16 v[40:43], v[92:95], v[108:111], v[40:43]
	v_mfma_f32_16x16x32_bf16 v[44:47], v[92:95], v[112:115], v[44:47]
	v_mfma_f32_16x16x32_bf16 v[48:51], v[96:99], v[100:103], v[48:51]
	v_mfma_f32_16x16x32_bf16 v[52:55], v[96:99], v[104:107], v[52:55]
	v_mfma_f32_16x16x32_bf16 v[56:59], v[96:99], v[108:111], v[56:59]
	s_add_u32 m0, s30, 0x16000
	v_lshl_add_u64 v[126:127], v[74:75], 0, s[24:25]
	global_load_lds_dwordx4 v[126:127], off
	v_mfma_f32_16x16x32_bf16 v[60:63], v[96:99], v[112:115], v[60:63]
	s_waitcnt vmcnt(6) lgkmcnt(0)
	s_barrier
	ds_read_b128 v[84:87], v76
	ds_read_b128 v[88:91], v76 offset:2048
	ds_read_b128 v[92:95], v76 offset:4096
	ds_read_b128 v[96:99], v76 offset:6144
	ds_read_b128 v[100:103], v78
	ds_read_b128 v[104:107], v78 offset:2048
	ds_read_b128 v[108:111], v78 offset:4096
	ds_read_b128 v[112:115], v78 offset:6144
	v_mfma_f32_16x16x32_bf16 v[0:3], v[136:139], v[152:155], v[0:3]
	v_mfma_f32_16x16x32_bf16 v[4:7], v[136:139], v[156:159], v[4:7]
	v_mfma_f32_16x16x32_bf16 v[8:11], v[136:139], v[160:163], v[8:11]
	v_mfma_f32_16x16x32_bf16 v[12:15], v[136:139], v[164:167], v[12:15]
	v_mfma_f32_16x16x32_bf16 v[16:19], v[140:143], v[152:155], v[16:19]
	s_mov_b32 s24, 0x200
	s_mov_b32 s25, 0
	s_add_u32 m0, s30, 0x18000
	v_lshl_add_u64 v[124:125], v[64:65], 0, s[24:25]
	global_load_lds_dwordx4 v[124:125], off
	v_mfma_f32_16x16x32_bf16 v[20:23], v[140:143], v[156:159], v[20:23]
	v_mfma_f32_16x16x32_bf16 v[24:27], v[140:143], v[160:163], v[24:27]
	v_mfma_f32_16x16x32_bf16 v[28:31], v[140:143], v[164:167], v[28:31]
	v_mfma_f32_16x16x32_bf16 v[32:35], v[144:147], v[152:155], v[32:35]
	v_mfma_f32_16x16x32_bf16 v[36:39], v[144:147], v[156:159], v[36:39]
	s_add_u32 m0, s30, 0x1a000
	v_lshl_add_u64 v[126:127], v[66:67], 0, s[24:25]
	global_load_lds_dwordx4 v[126:127], off
	v_mfma_f32_16x16x32_bf16 v[40:43], v[144:147], v[160:163], v[40:43]
	v_mfma_f32_16x16x32_bf16 v[44:47], v[144:147], v[164:167], v[44:47]
	v_mfma_f32_16x16x32_bf16 v[48:51], v[148:151], v[152:155], v[48:51]
	v_mfma_f32_16x16x32_bf16 v[52:55], v[148:151], v[156:159], v[52:55]
	v_mfma_f32_16x16x32_bf16 v[56:59], v[148:151], v[160:163], v[56:59]
	s_add_u32 m0, s30, 0x1c000
	v_lshl_add_u64 v[124:125], v[68:69], 0, s[24:25]
	global_load_lds_dwordx4 v[124:125], off
	v_mfma_f32_16x16x32_bf16 v[60:63], v[148:151], v[164:167], v[60:63]
	ds_read_b128 v[136:139], v77
	ds_read_b128 v[140:143], v77 offset:2048
	ds_read_b128 v[144:147], v77 offset:4096
	ds_read_b128 v[148:151], v77 offset:6144
	ds_read_b128 v[152:155], v79
	ds_read_b128 v[156:159], v79 offset:2048
	ds_read_b128 v[160:163], v79 offset:4096
	ds_read_b128 v[164:167], v79 offset:6144
	s_waitcnt lgkmcnt(8)
;     ...
;   for (int kt = 0; kt < nk; ++kt) {
;     if (kt + 1 < nk) asm volatile("s_waitcnt vmcnt(6)" ::: "memory");
;     else asm volatile("s_waitcnt vmcnt(0)" ::: "memory");
;     __builtin_amdgcn_s_barrier();
;     asm volatile("" ::: "memory");
;     if (kt + 2 < nk) { const int st2 = (st >= 1) ? st - 1 : 2; GEMM_ISSUE(kt + 2, st2); }
;     const char* la = lds + st * STAGE_B;
;     const char* lb = la + 32768;
;     const unsigned sa_u = (unsigned)(size_t)la + arow_u, sb_u = (unsigned)(size_t)lb + brow_u;
;     const unsigned a0 = sa_u + co0, a1 = sa_u + co1, a2 = sa_u + co2, a3 = sa_u + co3;
;     const unsigned b0 = sb_u + co0, b1 = sb_u + co1, b2 = sb_u + co2, b3 = sb_u + co3;
;     {
;       bf16x8 p0, p1, q0, q1, u0, u1, w0, w1;
;       asm volatile(
;         "ds_read_b128 %4, %12\n\tds_read_b128 %5, %12 offset:4096\n\tds_read_b128 %6, %16\n\tds_read_b128 %7, %16 offset:4096\n\t"
;         "ds_read_b128 %8, %13\n\tds_read_b128 %9, %13 offset:4096\n\tds_read_b128 %10, %17\n\tds_read_b128 %11, %17 offset:4096\n\t"
;         "s_waitcnt lgkmcnt(4)\n\t"
;         "v_mfma_f32_32x32x16_bf16 %0, %4, %6, %0\n\tv_mfma_f32_32x32x16_bf16 %1, %4, %7, %1\n\tv_mfma_f32_32x32x16_bf16 %2, %5, %6, %2\n\tv_mfma_f32_32x32x16_bf16 %3, %5, %7, %3\n\t"
;         "ds_read_b128 %4, %14\n\tds_read_b128 %5, %14 offset:4096\n\tds_read_b128 %6, %18\n\tds_read_b128 %7, %18 offset:4096\n\t"
;         "s_waitcnt lgkmcnt(4)\n\t"
;         "v_mfma_f32_32x32x16_bf16 %0, %8, %10, %0\n\tv_mfma_f32_32x32x16_bf16 %1, %8, %11, %1\n\tv_mfma_f32_32x32x16_bf16 %2, %9, %10, %2\n\tv_mfma_f32_32x32x16_bf16 %3, %9, %11, %3\n\t"
;         "ds_read_b128 %8, %15\n\tds_read_b128 %9, %15 offset:4096\n\tds_read_b128 %10, %19\n\tds_read_b128 %11, %19 offset:4096\n\t"
;         "s_waitcnt lgkmcnt(4)\n\t"
;         "v_mfma_f32_32x32x16_bf16 %0, %4, %6, %0\n\tv_mfma_f32_32x32x16_bf16 %1, %4, %7, %1\n\tv_mfma_f32_32x32x16_bf16 %2, %5, %6, %2\n\tv_mfma_f32_32x32x16_bf16 %3, %5, %7, %3\n\t"
;         "s_waitcnt lgkmcnt(0)\n\t"
;         "v_mfma_f32_32x32x16_bf16 %0, %8, %10, %0\n\tv_mfma_f32_32x32x16_bf16 %1, %8, %11, %1\n\tv_mfma_f32_32x32x16_bf16 %2, %9, %10, %2\n\tv_mfma_f32_32x32x16_bf16 %3, %9, %11, %3"
	v_mfma_f32_16x16x32_bf16 v[0:3], v[84:87], v[100:103], v[0:3]
	v_mfma_f32_16x16x32_bf16 v[4:7], v[84:87], v[104:107], v[4:7]
	v_mfma_f32_16x16x32_bf16 v[8:11], v[84:87], v[108:111], v[8:11]
	v_mfma_f32_16x16x32_bf16 v[12:15], v[84:87], v[112:115], v[12:15]
	v_mfma_f32_16x16x32_bf16 v[16:19], v[88:91], v[100:103], v[16:19]
	s_add_u32 m0, s30, 0x1e000
	v_lshl_add_u64 v[126:127], v[70:71], 0, s[24:25]
	global_load_lds_dwordx4 v[126:127], off
	v_mfma_f32_16x16x32_bf16 v[20:23], v[88:91], v[104:107], v[20:23]
	v_mfma_f32_16x16x32_bf16 v[24:27], v[88:91], v[108:111], v[24:27]
	v_mfma_f32_16x16x32_bf16 v[28:31], v[88:91], v[112:115], v[28:31]
	v_mfma_f32_16x16x32_bf16 v[32:35], v[92:95], v[100:103], v[32:35]
	v_mfma_f32_16x16x32_bf16 v[36:39], v[92:95], v[104:107], v[36:39]
	s_add_u32 m0, s30, 0x20000
	v_lshl_add_u64 v[124:125], v[72:73], 0, s[24:25]
	global_load_lds_dwordx4 v[124:125], off
	v_mfma_f32_16x16x32_bf16 v[40:43], v[92:95], v[108:111], v[40:43]
	v_mfma_f32_16x16x32_bf16 v[44:47], v[92:95], v[112:115], v[44:47]
	v_mfma_f32_16x16x32_bf16 v[48:51], v[96:99], v[100:103], v[48:51]
	v_mfma_f32_16x16x32_bf16 v[52:55], v[96:99], v[104:107], v[52:55]
	v_mfma_f32_16x16x32_bf16 v[56:59], v[96:99], v[108:111], v[56:59]
	s_add_u32 m0, s30, 0x22000
	v_lshl_add_u64 v[126:127], v[74:75], 0, s[24:25]
	global_load_lds_dwordx4 v[126:127], off
	v_mfma_f32_16x16x32_bf16 v[60:63], v[96:99], v[112:115], v[60:63]
	s_waitcnt vmcnt(6) lgkmcnt(0)
	s_barrier
	ds_read_b128 v[84:87], v76 offset:49152
	ds_read_b128 v[88:91], v76 offset:51200
	ds_read_b128 v[92:95], v76 offset:53248
	ds_read_b128 v[96:99], v76 offset:55296
	ds_read_b128 v[100:103], v78 offset:49152
	ds_read_b128 v[104:107], v78 offset:51200
	ds_read_b128 v[108:111], v78 offset:53248
	ds_read_b128 v[112:115], v78 offset:55296
	v_mfma_f32_16x16x32_bf16 v[0:3], v[136:139], v[152:155], v[0:3]
	v_mfma_f32_16x16x32_bf16 v[4:7], v[136:139], v[156:159], v[4:7]
	v_mfma_f32_16x16x32_bf16 v[8:11], v[136:139], v[160:163], v[8:11]
	v_mfma_f32_16x16x32_bf16 v[12:15], v[136:139], v[164:167], v[12:15]
	v_mfma_f32_16x16x32_bf16 v[16:19], v[140:143], v[152:155], v[16:19]
	s_mov_b32 s24, 0x280
	s_mov_b32 s25, 0
	s_mov_b32 m0, s30
	v_lshl_add_u64 v[124:125], v[64:65], 0, s[24:25]
	global_load_lds_dwordx4 v[124:125], off
	v_mfma_f32_16x16x32_bf16 v[20:23], v[140:143], v[156:159], v[20:23]
	v_mfma_f32_16x16x32_bf16 v[24:27], v[140:143], v[160:163], v[24:27]
	v_mfma_f32_16x16x32_bf16 v[28:31], v[140:143], v[164:167], v[28:31]
	v_mfma_f32_16x16x32_bf16 v[32:35], v[144:147], v[152:155], v[32:35]
	v_mfma_f32_16x16x32_bf16 v[36:39], v[144:147], v[156:159], v[36:39]
	s_add_u32 m0, s30, 0x2000
	v_lshl_add_u64 v[126:127], v[66:67], 0, s[24:25]
	global_load_lds_dwordx4 v[126:127], off
	v_mfma_f32_16x16x32_bf16 v[40:43], v[144:147], v[160:163], v[40:43]
	v_mfma_f32_16x16x32_bf16 v[44:47], v[144:147], v[164:167], v[44:47]
	v_mfma_f32_16x16x32_bf16 v[48:51], v[148:151], v[152:155], v[48:51]
	v_mfma_f32_16x16x32_bf16 v[52:55], v[148:151], v[156:159], v[52:55]
	v_mfma_f32_16x16x32_bf16 v[56:59], v[148:151], v[160:163], v[56:59]
	s_add_u32 m0, s30, 0x4000
	v_lshl_add_u64 v[124:125], v[68:69], 0, s[24:25]
	global_load_lds_dwordx4 v[124:125], off
	v_mfma_f32_16x16x32_bf16 v[60:63], v[148:151], v[164:167], v[60:63]
	ds_read_b128 v[136:139], v77 offset:49152
	ds_read_b128 v[140:143], v77 offset:51200
	ds_read_b128 v[144:147], v77 offset:53248
	ds_read_b128 v[148:151], v77 offset:55296
	ds_read_b128 v[152:155], v79 offset:49152
	ds_read_b128 v[156:159], v79 offset:51200
	ds_read_b128 v[160:163], v79 offset:53248
	ds_read_b128 v[164:167], v79 offset:55296
	s_waitcnt lgkmcnt(8)
	v_mfma_f32_16x16x32_bf16 v[0:3], v[84:87], v[100:103], v[0:3]
	v_mfma_f32_16x16x32_bf16 v[4:7], v[84:87], v[104:107], v[4:7]
	v_mfma_f32_16x16x32_bf16 v[8:11], v[84:87], v[108:111], v[8:11]
	v_mfma_f32_16x16x32_bf16 v[12:15], v[84:87], v[112:115], v[12:15]
	v_mfma_f32_16x16x32_bf16 v[16:19], v[88:91], v[100:103], v[16:19]
	s_add_u32 m0, s30, 0x6000
	v_lshl_add_u64 v[126:127], v[70:71], 0, s[24:25]
	global_load_lds_dwordx4 v[126:127], off
	v_mfma_f32_16x16x32_bf16 v[20:23], v[88:91], v[104:107], v[20:23]
	v_mfma_f32_16x16x32_bf16 v[24:27], v[88:91], v[108:111], v[24:27]
	v_mfma_f32_16x16x32_bf16 v[28:31], v[88:91], v[112:115], v[28:31]
	v_mfma_f32_16x16x32_bf16 v[32:35], v[92:95], v[100:103], v[32:35]
	v_mfma_f32_16x16x32_bf16 v[36:39], v[92:95], v[104:107], v[36:39]
	s_add_u32 m0, s30, 0x8000
	v_lshl_add_u64 v[124:125], v[72:73], 0, s[24:25]
	global_load_lds_dwordx4 v[124:125], off
	v_mfma_f32_16x16x32_bf16 v[40:43], v[92:95], v[108:111], v[40:43]
	v_mfma_f32_16x16x32_bf16 v[44:47], v[92:95], v[112:115], v[44:47]
	v_mfma_f32_16x16x32_bf16 v[48:51], v[96:99], v[100:103], v[48:51]
	v_mfma_f32_16x16x32_bf16 v[52:55], v[96:99], v[104:107], v[52:55]
	v_mfma_f32_16x16x32_bf16 v[56:59], v[96:99], v[108:111], v[56:59]
	s_add_u32 m0, s30, 0xa000
	v_lshl_add_u64 v[126:127], v[74:75], 0, s[24:25]
	global_load_lds_dwordx4 v[126:127], off
	v_mfma_f32_16x16x32_bf16 v[60:63], v[96:99], v[112:115], v[60:63]
	s_waitcnt vmcnt(6) lgkmcnt(0)
	s_barrier
;     ...
;   for (int kt = 0; kt < nk; ++kt) {
;     if (kt + 1 < nk) asm volatile("s_waitcnt vmcnt(6)" ::: "memory");
;     else asm volatile("s_waitcnt vmcnt(0)" ::: "memory");
;     __builtin_amdgcn_s_barrier();
;     asm volatile("" ::: "memory");
;     if (kt + 2 < nk) { const int st2 = (st >= 1) ? st - 1 : 2; GEMM_ISSUE(kt + 2, st2); }
;     const char* la = lds + st * STAGE_B;
;     const char* lb = la + 32768;
;     const unsigned sa_u = (unsigned)(size_t)la + arow_u, sb_u = (unsigned)(size_t)lb + brow_u;
;     const unsigned a0 = sa_u + co0, a1 = sa_u + co1, a2 = sa_u + co2, a3 = sa_u + co3;
;     const unsigned b0 = sb_u + co0, b1 = sb_u + co1, b2 = sb_u + co2, b3 = sb_u + co3;
;     {
;       bf16x8 p0, p1, q0, q1, u0, u1, w0, w1;
;       asm volatile(
;         "ds_read_b128 %4, %12\n\tds_read_b128 %5, %12 offset:4096\n\tds_read_b128 %6, %16\n\tds_read_b128 %7, %16 offset:4096\n\t"
;         "ds_read_b128 %8, %13\n\tds_read_b128 %9, %13 offset:4096\n\tds_read_b128 %10, %17\n\tds_read_b128 %11, %17 offset:4096\n\t"
;         "s_waitcnt lgkmcnt(4)\n\t"
;         "v_mfma_f32_32x32x16_bf16 %0, %4, %6, %0\n\tv_mfma_f32_32x32x16_bf16 %1, %4, %7, %1\n\tv_mfma_f32_32x32x16_bf16 %2, %5, %6, %2\n\tv_mfma_f32_32x32x16_bf16 %3, %5, %7, %3\n\t"
;         "ds_read_b128 %4, %14\n\tds_read_b128 %5, %14 offset:4096\n\tds_read_b128 %6, %18\n\tds_read_b128 %7, %18 offset:4096\n\t"
;         "s_waitcnt lgkmcnt(4)\n\t"
;         "v_mfma_f32_32x32x16_bf16 %0, %8, %10, %0\n\tv_mfma_f32_32x32x16_bf16 %1, %8, %11, %1\n\tv_mfma_f32_32x32x16_bf16 %2, %9, %10, %2\n\tv_mfma_f32_32x32x16_bf16 %3, %9, %11, %3\n\t"
;         "ds_read_b128 %8, %15\n\tds_read_b128 %9, %15 offset:4096\n\tds_read_b128 %10, %19\n\tds_read_b128 %11, %19 offset:4096\n\t"
;         "s_waitcnt lgkmcnt(4)\n\t"
;         "v_mfma_f32_32x32x16_bf16 %0, %4, %6, %0\n\tv_mfma_f32_32x32x16_bf16 %1, %4, %7, %1\n\tv_mfma_f32_32x32x16_bf16 %2, %5, %6, %2\n\tv_mfma_f32_32x32x16_bf16 %3, %5, %7, %3\n\t"
;         "s_waitcnt lgkmcnt(0)\n\t"
;         "v_mfma_f32_32x32x16_bf16 %0, %8, %10, %0\n\tv_mfma_f32_32x32x16_bf16 %1, %8, %11, %1\n\tv_mfma_f32_32x32x16_bf16 %2, %9, %10, %2\n\tv_mfma_f32_32x32x16_bf16 %3, %9, %11, %3"
	ds_read_b128 v[84:87], v80
	ds_read_b128 v[88:91], v80 offset:2048
	ds_read_b128 v[92:95], v80 offset:4096
	ds_read_b128 v[96:99], v80 offset:6144
	ds_read_b128 v[100:103], v82
	ds_read_b128 v[104:107], v82 offset:2048
	ds_read_b128 v[108:111], v82 offset:4096
	ds_read_b128 v[112:115], v82 offset:6144
	v_mfma_f32_16x16x32_bf16 v[0:3], v[136:139], v[152:155], v[0:3]
	v_mfma_f32_16x16x32_bf16 v[4:7], v[136:139], v[156:159], v[4:7]
	v_mfma_f32_16x16x32_bf16 v[8:11], v[136:139], v[160:163], v[8:11]
	v_mfma_f32_16x16x32_bf16 v[12:15], v[136:139], v[164:167], v[12:15]
	v_mfma_f32_16x16x32_bf16 v[16:19], v[140:143], v[152:155], v[16:19]
	s_mov_b32 s24, 0x300
	s_mov_b32 s25, 0
	s_add_u32 m0, s30, 0xc000
	v_lshl_add_u64 v[124:125], v[64:65], 0, s[24:25]
	global_load_lds_dwordx4 v[124:125], off
	v_mfma_f32_16x16x32_bf16 v[20:23], v[140:143], v[156:159], v[20:23]
	v_mfma_f32_16x16x32_bf16 v[24:27], v[140:143], v[160:163], v[24:27]
	v_mfma_f32_16x16x32_bf16 v[28:31], v[140:143], v[164:167], v[28:31]
	v_mfma_f32_16x16x32_bf16 v[32:35], v[144:147], v[152:155], v[32:35]
	v_mfma_f32_16x16x32_bf16 v[36:39], v[144:147], v[156:159], v[36:39]
	s_add_u32 m0, s30, 0xe000
	v_lshl_add_u64 v[126:127], v[66:67], 0, s[24:25]
	global_load_lds_dwordx4 v[126:127], off
	v_mfma_f32_16x16x32_bf16 v[40:43], v[144:147], v[160:163], v[40:43]
	v_mfma_f32_16x16x32_bf16 v[44:47], v[144:147], v[164:167], v[44:47]
	v_mfma_f32_16x16x32_bf16 v[48:51], v[148:151], v[152:155], v[48:51]
	v_mfma_f32_16x16x32_bf16 v[52:55], v[148:151], v[156:159], v[52:55]
	v_mfma_f32_16x16x32_bf16 v[56:59], v[148:151], v[160:163], v[56:59]
	s_add_u32 m0, s30, 0x10000
	v_lshl_add_u64 v[124:125], v[68:69], 0, s[24:25]
	global_load_lds_dwordx4 v[124:125], off
	v_mfma_f32_16x16x32_bf16 v[60:63], v[148:151], v[164:167], v[60:63]
	ds_read_b128 v[136:139], v81
	ds_read_b128 v[140:143], v81 offset:2048
	ds_read_b128 v[144:147], v81 offset:4096
	ds_read_b128 v[148:151], v81 offset:6144
	ds_read_b128 v[152:155], v83
	ds_read_b128 v[156:159], v83 offset:2048
	ds_read_b128 v[160:163], v83 offset:4096
	ds_read_b128 v[164:167], v83 offset:6144
	s_waitcnt lgkmcnt(8)
	v_mfma_f32_16x16x32_bf16 v[0:3], v[84:87], v[100:103], v[0:3]
	v_mfma_f32_16x16x32_bf16 v[4:7], v[84:87], v[104:107], v[4:7]
	v_mfma_f32_16x16x32_bf16 v[8:11], v[84:87], v[108:111], v[8:11]
	v_mfma_f32_16x16x32_bf16 v[12:15], v[84:87], v[112:115], v[12:15]
	v_mfma_f32_16x16x32_bf16 v[16:19], v[88:91], v[100:103], v[16:19]
	s_add_u32 m0, s30, 0x12000
	v_lshl_add_u64 v[126:127], v[70:71], 0, s[24:25]
	global_load_lds_dwordx4 v[126:127], off
	v_mfma_f32_16x16x32_bf16 v[20:23], v[88:91], v[104:107], v[20:23]
	v_mfma_f32_16x16x32_bf16 v[24:27], v[88:91], v[108:111], v[24:27]
	v_mfma_f32_16x16x32_bf16 v[28:31], v[88:91], v[112:115], v[28:31]
	v_mfma_f32_16x16x32_bf16 v[32:35], v[92:95], v[100:103], v[32:35]
	v_mfma_f32_16x16x32_bf16 v[36:39], v[92:95], v[104:107], v[36:39]
	s_add_u32 m0, s30, 0x14000
	v_lshl_add_u64 v[124:125], v[72:73], 0, s[24:25]
	global_load_lds_dwordx4 v[124:125], off
	v_mfma_f32_16x16x32_bf16 v[40:43], v[92:95], v[108:111], v[40:43]
	v_mfma_f32_16x16x32_bf16 v[44:47], v[92:95], v[112:115], v[44:47]
	v_mfma_f32_16x16x32_bf16 v[48:51], v[96:99], v[100:103], v[48:51]
	v_mfma_f32_16x16x32_bf16 v[52:55], v[96:99], v[104:107], v[52:55]
	v_mfma_f32_16x16x32_bf16 v[56:59], v[96:99], v[108:111], v[56:59]
	s_add_u32 m0, s30, 0x16000
	v_lshl_add_u64 v[126:127], v[74:75], 0, s[24:25]
	global_load_lds_dwordx4 v[126:127], off
	v_mfma_f32_16x16x32_bf16 v[60:63], v[96:99], v[112:115], v[60:63]
	s_waitcnt vmcnt(6) lgkmcnt(0)
	s_barrier
	ds_read_b128 v[84:87], v76
	ds_read_b128 v[88:91], v76 offset:2048
	ds_read_b128 v[92:95], v76 offset:4096
	ds_read_b128 v[96:99], v76 offset:6144
	ds_read_b128 v[100:103], v78
	ds_read_b128 v[104:107], v78 offset:2048
	ds_read_b128 v[108:111], v78 offset:4096
	ds_read_b128 v[112:115], v78 offset:6144
	v_mfma_f32_16x16x32_bf16 v[0:3], v[136:139], v[152:155], v[0:3]
	v_mfma_f32_16x16x32_bf16 v[4:7], v[136:139], v[156:159], v[4:7]
	v_mfma_f32_16x16x32_bf16 v[8:11], v[136:139], v[160:163], v[8:11]
	v_mfma_f32_16x16x32_bf16 v[12:15], v[136:139], v[164:167], v[12:15]
	v_mfma_f32_16x16x32_bf16 v[16:19], v[140:143], v[152:155], v[16:19]
	s_mov_b32 s24, 0x380
	s_mov_b32 s25, 0
	s_add_u32 m0, s30, 0x18000
	v_lshl_add_u64 v[124:125], v[64:65], 0, s[24:25]
	global_load_lds_dwordx4 v[124:125], off
	v_mfma_f32_16x16x32_bf16 v[20:23], v[140:143], v[156:159], v[20:23]
	v_mfma_f32_16x16x32_bf16 v[24:27], v[140:143], v[160:163], v[24:27]
	v_mfma_f32_16x16x32_bf16 v[28:31], v[140:143], v[164:167], v[28:31]
	v_mfma_f32_16x16x32_bf16 v[32:35], v[144:147], v[152:155], v[32:35]
	v_mfma_f32_16x16x32_bf16 v[36:39], v[144:147], v[156:159], v[36:39]
	s_add_u32 m0, s30, 0x1a000
	v_lshl_add_u64 v[126:127], v[66:67], 0, s[24:25]
	global_load_lds_dwordx4 v[126:127], off
	v_mfma_f32_16x16x32_bf16 v[40:43], v[144:147], v[160:163], v[40:43]
	v_mfma_f32_16x16x32_bf16 v[44:47], v[144:147], v[164:167], v[44:47]
	v_mfma_f32_16x16x32_bf16 v[48:51], v[148:151], v[152:155], v[48:51]
	v_mfma_f32_16x16x32_bf16 v[52:55], v[148:151], v[156:159], v[52:55]
	v_mfma_f32_16x16x32_bf16 v[56:59], v[148:151], v[160:163], v[56:59]
	s_add_u32 m0, s30, 0x1c000
	v_lshl_add_u64 v[124:125], v[68:69], 0, s[24:25]
	global_load_lds_dwordx4 v[124:125], off
	v_mfma_f32_16x16x32_bf16 v[60:63], v[148:151], v[164:167], v[60:63]
	ds_read_b128 v[136:139], v77
	ds_read_b128 v[140:143], v77 offset:2048
	ds_read_b128 v[144:147], v77 offset:4096
	ds_read_b128 v[148:151], v77 offset:6144
	ds_read_b128 v[152:155], v79
	ds_read_b128 v[156:159], v79 offset:2048
	ds_read_b128 v[160:163], v79 offset:4096
	ds_read_b128 v[164:167], v79 offset:6144
	s_waitcnt lgkmcnt(8)
;     ...
;   for (int kt = 0; kt < nk; ++kt) {
;     if (kt + 1 < nk) asm volatile("s_waitcnt vmcnt(6)" ::: "memory");
;     else asm volatile("s_waitcnt vmcnt(0)" ::: "memory");
;     __builtin_amdgcn_s_barrier();
;     asm volatile("" ::: "memory");
;     if (kt + 2 < nk) { const int st2 = (st >= 1) ? st - 1 : 2; GEMM_ISSUE(kt + 2, st2); }
;     const char* la = lds + st * STAGE_B;
;     const char* lb = la + 32768;
;     const unsigned sa_u = (unsigned)(size_t)la + arow_u, sb_u = (unsigned)(size_t)lb + brow_u;
;     const unsigned a0 = sa_u + co0, a1 = sa_u + co1, a2 = sa_u + co2, a3 = sa_u + co3;
;     const unsigned b0 = sb_u + co0, b1 = sb_u + co1, b2 = sb_u + co2, b3 = sb_u + co3;
;     {
;       bf16x8 p0, p1, q0, q1, u0, u1, w0, w1;
;       asm volatile(
;         "ds_read_b128 %4, %12\n\tds_read_b128 %5, %12 offset:4096\n\tds_read_b128 %6, %16\n\tds_read_b128 %7, %16 offset:4096\n\t"
;         "ds_read_b128 %8, %13\n\tds_read_b128 %9, %13 offset:4096\n\tds_read_b128 %10, %17\n\tds_read_b128 %11, %17 offset:4096\n\t"
;         "s_waitcnt lgkmcnt(4)\n\t"
;         "v_mfma_f32_32x32x16_bf16 %0, %4, %6, %0\n\tv_mfma_f32_32x32x16_bf16 %1, %4, %7, %1\n\tv_mfma_f32_32x32x16_bf16 %2, %5, %6, %2\n\tv_mfma_f32_32x32x16_bf16 %3, %5, %7, %3\n\t"
;         "ds_read_b128 %4, %14\n\tds_read_b128 %5, %14 offset:4096\n\tds_read_b128 %6, %18\n\tds_read_b128 %7, %18 offset:4096\n\t"
;         "s_waitcnt lgkmcnt(4)\n\t"
;         "v_mfma_f32_32x32x16_bf16 %0, %8, %10, %0\n\tv_mfma_f32_32x32x16_bf16 %1, %8, %11, %1\n\tv_mfma_f32_32x32x16_bf16 %2, %9, %10, %2\n\tv_mfma_f32_32x32x16_bf16 %3, %9, %11, %3\n\t"
;         "ds_read_b128 %8, %15\n\tds_read_b128 %9, %15 offset:4096\n\tds_read_b128 %10, %19\n\tds_read_b128 %11, %19 offset:4096\n\t"
;         "s_waitcnt lgkmcnt(4)\n\t"
;         "v_mfma_f32_32x32x16_bf16 %0, %4, %6, %0\n\tv_mfma_f32_32x32x16_bf16 %1, %4, %7, %1\n\tv_mfma_f32_32x32x16_bf16 %2, %5, %6, %2\n\tv_mfma_f32_32x32x16_bf16 %3, %5, %7, %3\n\t"
;         "s_waitcnt lgkmcnt(0)\n\t"
;         "v_mfma_f32_32x32x16_bf16 %0, %8, %10, %0\n\tv_mfma_f32_32x32x16_bf16 %1, %8, %11, %1\n\tv_mfma_f32_32x32x16_bf16 %2, %9, %10, %2\n\tv_mfma_f32_32x32x16_bf16 %3, %9, %11, %3"
	v_mfma_f32_16x16x32_bf16 v[0:3], v[84:87], v[100:103], v[0:3]
	v_mfma_f32_16x16x32_bf16 v[4:7], v[84:87], v[104:107], v[4:7]
	v_mfma_f32_16x16x32_bf16 v[8:11], v[84:87], v[108:111], v[8:11]
	v_mfma_f32_16x16x32_bf16 v[12:15], v[84:87], v[112:115], v[12:15]
	v_mfma_f32_16x16x32_bf16 v[16:19], v[88:91], v[100:103], v[16:19]
	s_add_u32 m0, s30, 0x1e000
	v_lshl_add_u64 v[126:127], v[70:71], 0, s[24:25]
	global_load_lds_dwordx4 v[126:127], off
	v_mfma_f32_16x16x32_bf16 v[20:23], v[88:91], v[104:107], v[20:23]
	v_mfma_f32_16x16x32_bf16 v[24:27], v[88:91], v[108:111], v[24:27]
	v_mfma_f32_16x16x32_bf16 v[28:31], v[88:91], v[112:115], v[28:31]
	v_mfma_f32_16x16x32_bf16 v[32:35], v[92:95], v[100:103], v[32:35]
	v_mfma_f32_16x16x32_bf16 v[36:39], v[92:95], v[104:107], v[36:39]
	s_add_u32 m0, s30, 0x20000
	v_lshl_add_u64 v[124:125], v[72:73], 0, s[24:25]
	global_load_lds_dwordx4 v[124:125], off
	v_mfma_f32_16x16x32_bf16 v[40:43], v[92:95], v[108:111], v[40:43]
	v_mfma_f32_16x16x32_bf16 v[44:47], v[92:95], v[112:115], v[44:47]
	v_mfma_f32_16x16x32_bf16 v[48:51], v[96:99], v[100:103], v[48:51]
	v_mfma_f32_16x16x32_bf16 v[52:55], v[96:99], v[104:107], v[52:55]
	v_mfma_f32_16x16x32_bf16 v[56:59], v[96:99], v[108:111], v[56:59]
	s_add_u32 m0, s30, 0x22000
	v_lshl_add_u64 v[126:127], v[74:75], 0, s[24:25]
	global_load_lds_dwordx4 v[126:127], off
	v_mfma_f32_16x16x32_bf16 v[60:63], v[96:99], v[112:115], v[60:63]
	s_waitcnt vmcnt(6) lgkmcnt(0)
	s_barrier
	ds_read_b128 v[84:87], v76 offset:49152
	ds_read_b128 v[88:91], v76 offset:51200
	ds_read_b128 v[92:95], v76 offset:53248
	ds_read_b128 v[96:99], v76 offset:55296
	ds_read_b128 v[100:103], v78 offset:49152
	ds_read_b128 v[104:107], v78 offset:51200
	ds_read_b128 v[108:111], v78 offset:53248
	ds_read_b128 v[112:115], v78 offset:55296
	v_mfma_f32_16x16x32_bf16 v[0:3], v[136:139], v[152:155], v[0:3]
	v_mfma_f32_16x16x32_bf16 v[4:7], v[136:139], v[156:159], v[4:7]
	v_mfma_f32_16x16x32_bf16 v[8:11], v[136:139], v[160:163], v[8:11]
	v_mfma_f32_16x16x32_bf16 v[12:15], v[136:139], v[164:167], v[12:15]
	v_mfma_f32_16x16x32_bf16 v[16:19], v[140:143], v[152:155], v[16:19]
	s_mov_b32 s24, 0x400
	s_mov_b32 s25, 0
	s_mov_b32 m0, s30
	v_lshl_add_u64 v[124:125], v[64:65], 0, s[24:25]
	global_load_lds_dwordx4 v[124:125], off
	v_mfma_f32_16x16x32_bf16 v[20:23], v[140:143], v[156:159], v[20:23]
	v_mfma_f32_16x16x32_bf16 v[24:27], v[140:143], v[160:163], v[24:27]
	v_mfma_f32_16x16x32_bf16 v[28:31], v[140:143], v[164:167], v[28:31]
	v_mfma_f32_16x16x32_bf16 v[32:35], v[144:147], v[152:155], v[32:35]
	v_mfma_f32_16x16x32_bf16 v[36:39], v[144:147], v[156:159], v[36:39]
	s_add_u32 m0, s30, 0x2000
	v_lshl_add_u64 v[126:127], v[66:67], 0, s[24:25]
	global_load_lds_dwordx4 v[126:127], off
	v_mfma_f32_16x16x32_bf16 v[40:43], v[144:147], v[160:163], v[40:43]
	v_mfma_f32_16x16x32_bf16 v[44:47], v[144:147], v[164:167], v[44:47]
	v_mfma_f32_16x16x32_bf16 v[48:51], v[148:151], v[152:155], v[48:51]
	v_mfma_f32_16x16x32_bf16 v[52:55], v[148:151], v[156:159], v[52:55]
	v_mfma_f32_16x16x32_bf16 v[56:59], v[148:151], v[160:163], v[56:59]
	s_add_u32 m0, s30, 0x4000
	v_lshl_add_u64 v[124:125], v[68:69], 0, s[24:25]
	global_load_lds_dwordx4 v[124:125], off
	v_mfma_f32_16x16x32_bf16 v[60:63], v[148:151], v[164:167], v[60:63]
	ds_read_b128 v[136:139], v77 offset:49152
	ds_read_b128 v[140:143], v77 offset:51200
	ds_read_b128 v[144:147], v77 offset:53248
	ds_read_b128 v[148:151], v77 offset:55296
	ds_read_b128 v[152:155], v79 offset:49152
	ds_read_b128 v[156:159], v79 offset:51200
	ds_read_b128 v[160:163], v79 offset:53248
	ds_read_b128 v[164:167], v79 offset:55296
	s_waitcnt lgkmcnt(8)
	v_mfma_f32_16x16x32_bf16 v[0:3], v[84:87], v[100:103], v[0:3]
	v_mfma_f32_16x16x32_bf16 v[4:7], v[84:87], v[104:107], v[4:7]
	v_mfma_f32_16x16x32_bf16 v[8:11], v[84:87], v[108:111], v[8:11]
	v_mfma_f32_16x16x32_bf16 v[12:15], v[84:87], v[112:115], v[12:15]
	v_mfma_f32_16x16x32_bf16 v[16:19], v[88:91], v[100:103], v[16:19]
	s_add_u32 m0, s30, 0x6000
	v_lshl_add_u64 v[126:127], v[70:71], 0, s[24:25]
	global_load_lds_dwordx4 v[126:127], off
	v_mfma_f32_16x16x32_bf16 v[20:23], v[88:91], v[104:107], v[20:23]
	v_mfma_f32_16x16x32_bf16 v[24:27], v[88:91], v[108:111], v[24:27]
	v_mfma_f32_16x16x32_bf16 v[28:31], v[88:91], v[112:115], v[28:31]
	v_mfma_f32_16x16x32_bf16 v[32:35], v[92:95], v[100:103], v[32:35]
	v_mfma_f32_16x16x32_bf16 v[36:39], v[92:95], v[104:107], v[36:39]
	s_add_u32 m0, s30, 0x8000
	v_lshl_add_u64 v[124:125], v[72:73], 0, s[24:25]
	global_load_lds_dwordx4 v[124:125], off
	v_mfma_f32_16x16x32_bf16 v[40:43], v[92:95], v[108:111], v[40:43]
	v_mfma_f32_16x16x32_bf16 v[44:47], v[92:95], v[112:115], v[44:47]
	v_mfma_f32_16x16x32_bf16 v[48:51], v[96:99], v[100:103], v[48:51]
	v_mfma_f32_16x16x32_bf16 v[52:55], v[96:99], v[104:107], v[52:55]
	v_mfma_f32_16x16x32_bf16 v[56:59], v[96:99], v[108:111], v[56:59]
	s_add_u32 m0, s30, 0xa000
	v_lshl_add_u64 v[126:127], v[74:75], 0, s[24:25]
	global_load_lds_dwordx4 v[126:127], off
	v_mfma_f32_16x16x32_bf16 v[60:63], v[96:99], v[112:115], v[60:63]
	s_waitcnt vmcnt(6) lgkmcnt(0)
	s_barrier
;     ...
;   for (int kt = 0; kt < nk; ++kt) {
;     if (kt + 1 < nk) asm volatile("s_waitcnt vmcnt(6)" ::: "memory");
;     else asm volatile("s_waitcnt vmcnt(0)" ::: "memory");
;     __builtin_amdgcn_s_barrier();
;     asm volatile("" ::: "memory");
;     if (kt + 2 < nk) { const int st2 = (st >= 1) ? st - 1 : 2; GEMM_ISSUE(kt + 2, st2); }
;     const char* la = lds + st * STAGE_B;
;     const char* lb = la + 32768;
;     const unsigned sa_u = (unsigned)(size_t)la + arow_u, sb_u = (unsigned)(size_t)lb + brow_u;
;     const unsigned a0 = sa_u + co0, a1 = sa_u + co1, a2 = sa_u + co2, a3 = sa_u + co3;
;     const unsigned b0 = sb_u + co0, b1 = sb_u + co1, b2 = sb_u + co2, b3 = sb_u + co3;
;     {
;       bf16x8 p0, p1, q0, q1, u0, u1, w0, w1;
;       asm volatile(
;         "ds_read_b128 %4, %12\n\tds_read_b128 %5, %12 offset:4096\n\tds_read_b128 %6, %16\n\tds_read_b128 %7, %16 offset:4096\n\t"
;         "ds_read_b128 %8, %13\n\tds_read_b128 %9, %13 offset:4096\n\tds_read_b128 %10, %17\n\tds_read_b128 %11, %17 offset:4096\n\t"
;         "s_waitcnt lgkmcnt(4)\n\t"
;         "v_mfma_f32_32x32x16_bf16 %0, %4, %6, %0\n\tv_mfma_f32_32x32x16_bf16 %1, %4, %7, %1\n\tv_mfma_f32_32x32x16_bf16 %2, %5, %6, %2\n\tv_mfma_f32_32x32x16_bf16 %3, %5, %7, %3\n\t"
;         "ds_read_b128 %4, %14\n\tds_read_b128 %5, %14 offset:4096\n\tds_read_b128 %6, %18\n\tds_read_b128 %7, %18 offset:4096\n\t"
;         "s_waitcnt lgkmcnt(4)\n\t"
;         "v_mfma_f32_32x32x16_bf16 %0, %8, %10, %0\n\tv_mfma_f32_32x32x16_bf16 %1, %8, %11, %1\n\tv_mfma_f32_32x32x16_bf16 %2, %9, %10, %2\n\tv_mfma_f32_32x32x16_bf16 %3, %9, %11, %3\n\t"
;         "ds_read_b128 %8, %15\n\tds_read_b128 %9, %15 offset:4096\n\tds_read_b128 %10, %19\n\tds_read_b128 %11, %19 offset:4096\n\t"
;         "s_waitcnt lgkmcnt(4)\n\t"
;         "v_mfma_f32_32x32x16_bf16 %0, %4, %6, %0\n\tv_mfma_f32_32x32x16_bf16 %1, %4, %7, %1\n\tv_mfma_f32_32x32x16_bf16 %2, %5, %6, %2\n\tv_mfma_f32_32x32x16_bf16 %3, %5, %7, %3\n\t"
;         "s_waitcnt lgkmcnt(0)\n\t"
;         "v_mfma_f32_32x32x16_bf16 %0, %8, %10, %0\n\tv_mfma_f32_32x32x16_bf16 %1, %8, %11, %1\n\tv_mfma_f32_32x32x16_bf16 %2, %9, %10, %2\n\tv_mfma_f32_32x32x16_bf16 %3, %9, %11, %3"
	ds_read_b128 v[84:87], v80
	ds_read_b128 v[88:91], v80 offset:2048
	ds_read_b128 v[92:95], v80 offset:4096
	ds_read_b128 v[96:99], v80 offset:6144
	ds_read_b128 v[100:103], v82
	ds_read_b128 v[104:107], v82 offset:2048
	ds_read_b128 v[108:111], v82 offset:4096
	ds_read_b128 v[112:115], v82 offset:6144
	v_mfma_f32_16x16x32_bf16 v[0:3], v[136:139], v[152:155], v[0:3]
	v_mfma_f32_16x16x32_bf16 v[4:7], v[136:139], v[156:159], v[4:7]
	v_mfma_f32_16x16x32_bf16 v[8:11], v[136:139], v[160:163], v[8:11]
	v_mfma_f32_16x16x32_bf16 v[12:15], v[136:139], v[164:167], v[12:15]
	v_mfma_f32_16x16x32_bf16 v[16:19], v[140:143], v[152:155], v[16:19]
	s_mov_b32 s24, 0x480
	s_mov_b32 s25, 0
	s_add_u32 m0, s30, 0xc000
	v_lshl_add_u64 v[124:125], v[64:65], 0, s[24:25]
	global_load_lds_dwordx4 v[124:125], off
	v_mfma_f32_16x16x32_bf16 v[20:23], v[140:143], v[156:159], v[20:23]
	v_mfma_f32_16x16x32_bf16 v[24:27], v[140:143], v[160:163], v[24:27]
	v_mfma_f32_16x16x32_bf16 v[28:31], v[140:143], v[164:167], v[28:31]
	v_mfma_f32_16x16x32_bf16 v[32:35], v[144:147], v[152:155], v[32:35]
	v_mfma_f32_16x16x32_bf16 v[36:39], v[144:147], v[156:159], v[36:39]
	s_add_u32 m0, s30, 0xe000
	v_lshl_add_u64 v[126:127], v[66:67], 0, s[24:25]
	global_load_lds_dwordx4 v[126:127], off
	v_mfma_f32_16x16x32_bf16 v[40:43], v[144:147], v[160:163], v[40:43]
	v_mfma_f32_16x16x32_bf16 v[44:47], v[144:147], v[164:167], v[44:47]
	v_mfma_f32_16x16x32_bf16 v[48:51], v[148:151], v[152:155], v[48:51]
	v_mfma_f32_16x16x32_bf16 v[52:55], v[148:151], v[156:159], v[52:55]
	v_mfma_f32_16x16x32_bf16 v[56:59], v[148:151], v[160:163], v[56:59]
	s_add_u32 m0, s30, 0x10000
	v_lshl_add_u64 v[124:125], v[68:69], 0, s[24:25]
	global_load_lds_dwordx4 v[124:125], off
	v_mfma_f32_16x16x32_bf16 v[60:63], v[148:151], v[164:167], v[60:63]
	ds_read_b128 v[136:139], v81
	ds_read_b128 v[140:143], v81 offset:2048
	ds_read_b128 v[144:147], v81 offset:4096
	ds_read_b128 v[148:151], v81 offset:6144
	ds_read_b128 v[152:155], v83
	ds_read_b128 v[156:159], v83 offset:2048
	ds_read_b128 v[160:163], v83 offset:4096
	ds_read_b128 v[164:167], v83 offset:6144
	s_waitcnt lgkmcnt(8)
	v_mfma_f32_16x16x32_bf16 v[0:3], v[84:87], v[100:103], v[0:3]
	v_mfma_f32_16x16x32_bf16 v[4:7], v[84:87], v[104:107], v[4:7]
	v_mfma_f32_16x16x32_bf16 v[8:11], v[84:87], v[108:111], v[8:11]
	v_mfma_f32_16x16x32_bf16 v[12:15], v[84:87], v[112:115], v[12:15]
	v_mfma_f32_16x16x32_bf16 v[16:19], v[88:91], v[100:103], v[16:19]
	s_add_u32 m0, s30, 0x12000
	v_lshl_add_u64 v[126:127], v[70:71], 0, s[24:25]
	global_load_lds_dwordx4 v[126:127], off
	v_mfma_f32_16x16x32_bf16 v[20:23], v[88:91], v[104:107], v[20:23]
	v_mfma_f32_16x16x32_bf16 v[24:27], v[88:91], v[108:111], v[24:27]
	v_mfma_f32_16x16x32_bf16 v[28:31], v[88:91], v[112:115], v[28:31]
	v_mfma_f32_16x16x32_bf16 v[32:35], v[92:95], v[100:103], v[32:35]
	v_mfma_f32_16x16x32_bf16 v[36:39], v[92:95], v[104:107], v[36:39]
	s_add_u32 m0, s30, 0x14000
	v_lshl_add_u64 v[124:125], v[72:73], 0, s[24:25]
	global_load_lds_dwordx4 v[124:125], off
	v_mfma_f32_16x16x32_bf16 v[40:43], v[92:95], v[108:111], v[40:43]
	v_mfma_f32_16x16x32_bf16 v[44:47], v[92:95], v[112:115], v[44:47]
	v_mfma_f32_16x16x32_bf16 v[48:51], v[96:99], v[100:103], v[48:51]
	v_mfma_f32_16x16x32_bf16 v[52:55], v[96:99], v[104:107], v[52:55]
	v_mfma_f32_16x16x32_bf16 v[56:59], v[96:99], v[108:111], v[56:59]
	s_add_u32 m0, s30, 0x16000
	v_lshl_add_u64 v[126:127], v[74:75], 0, s[24:25]
	global_load_lds_dwordx4 v[126:127], off
	v_mfma_f32_16x16x32_bf16 v[60:63], v[96:99], v[112:115], v[60:63]
	s_waitcnt vmcnt(6) lgkmcnt(0)
	s_barrier
	ds_read_b128 v[84:87], v76
	ds_read_b128 v[88:91], v76 offset:2048
	ds_read_b128 v[92:95], v76 offset:4096
	ds_read_b128 v[96:99], v76 offset:6144
	ds_read_b128 v[100:103], v78
	ds_read_b128 v[104:107], v78 offset:2048
	ds_read_b128 v[108:111], v78 offset:4096
	ds_read_b128 v[112:115], v78 offset:6144
	v_mfma_f32_16x16x32_bf16 v[0:3], v[136:139], v[152:155], v[0:3]
	v_mfma_f32_16x16x32_bf16 v[4:7], v[136:139], v[156:159], v[4:7]
	v_mfma_f32_16x16x32_bf16 v[8:11], v[136:139], v[160:163], v[8:11]
	v_mfma_f32_16x16x32_bf16 v[12:15], v[136:139], v[164:167], v[12:15]
	v_mfma_f32_16x16x32_bf16 v[16:19], v[140:143], v[152:155], v[16:19]
	s_mov_b32 s24, 0x500
	s_mov_b32 s25, 0
	s_add_u32 m0, s30, 0x18000
	v_lshl_add_u64 v[124:125], v[64:65], 0, s[24:25]
	global_load_lds_dwordx4 v[124:125], off
	v_mfma_f32_16x16x32_bf16 v[20:23], v[140:143], v[156:159], v[20:23]
	v_mfma_f32_16x16x32_bf16 v[24:27], v[140:143], v[160:163], v[24:27]
	v_mfma_f32_16x16x32_bf16 v[28:31], v[140:143], v[164:167], v[28:31]
	v_mfma_f32_16x16x32_bf16 v[32:35], v[144:147], v[152:155], v[32:35]
	v_mfma_f32_16x16x32_bf16 v[36:39], v[144:147], v[156:159], v[36:39]
	s_add_u32 m0, s30, 0x1a000
	v_lshl_add_u64 v[126:127], v[66:67], 0, s[24:25]
	global_load_lds_dwordx4 v[126:127], off
	v_mfma_f32_16x16x32_bf16 v[40:43], v[144:147], v[160:163], v[40:43]
	v_mfma_f32_16x16x32_bf16 v[44:47], v[144:147], v[164:167], v[44:47]
	v_mfma_f32_16x16x32_bf16 v[48:51], v[148:151], v[152:155], v[48:51]
	v_mfma_f32_16x16x32_bf16 v[52:55], v[148:151], v[156:159], v[52:55]
	v_mfma_f32_16x16x32_bf16 v[56:59], v[148:151], v[160:163], v[56:59]
	s_add_u32 m0, s30, 0x1c000
	v_lshl_add_u64 v[124:125], v[68:69], 0, s[24:25]
	global_load_lds_dwordx4 v[124:125], off
	v_mfma_f32_16x16x32_bf16 v[60:63], v[148:151], v[164:167], v[60:63]
	ds_read_b128 v[136:139], v77
	ds_read_b128 v[140:143], v77 offset:2048
	ds_read_b128 v[144:147], v77 offset:4096
	ds_read_b128 v[148:151], v77 offset:6144
	ds_read_b128 v[152:155], v79
	ds_read_b128 v[156:159], v79 offset:2048
	ds_read_b128 v[160:163], v79 offset:4096
	ds_read_b128 v[164:167], v79 offset:6144
	s_waitcnt lgkmcnt(8)
;     ...
;   for (int kt = 0; kt < nk; ++kt) {
;     if (kt + 1 < nk) asm volatile("s_waitcnt vmcnt(6)" ::: "memory");
;     else asm volatile("s_waitcnt vmcnt(0)" ::: "memory");
;     __builtin_amdgcn_s_barrier();
;     asm volatile("" ::: "memory");
;     if (kt + 2 < nk) { const int st2 = (st >= 1) ? st - 1 : 2; GEMM_ISSUE(kt + 2, st2); }
;     const char* la = lds + st * STAGE_B;
;     const char* lb = la + 32768;
;     const unsigned sa_u = (unsigned)(size_t)la + arow_u, sb_u = (unsigned)(size_t)lb + brow_u;
;     const unsigned a0 = sa_u + co0, a1 = sa_u + co1, a2 = sa_u + co2, a3 = sa_u + co3;
;     const unsigned b0 = sb_u + co0, b1 = sb_u + co1, b2 = sb_u + co2, b3 = sb_u + co3;
;     {
;       bf16x8 p0, p1, q0, q1, u0, u1, w0, w1;
;       asm volatile(
;         "ds_read_b128 %4, %12\n\tds_read_b128 %5, %12 offset:4096\n\tds_read_b128 %6, %16\n\tds_read_b128 %7, %16 offset:4096\n\t"
;         "ds_read_b128 %8, %13\n\tds_read_b128 %9, %13 offset:4096\n\tds_read_b128 %10, %17\n\tds_read_b128 %11, %17 offset:4096\n\t"
;         "s_waitcnt lgkmcnt(4)\n\t"
;         "v_mfma_f32_32x32x16_bf16 %0, %4, %6, %0\n\tv_mfma_f32_32x32x16_bf16 %1, %4, %7, %1\n\tv_mfma_f32_32x32x16_bf16 %2, %5, %6, %2\n\tv_mfma_f32_32x32x16_bf16 %3, %5, %7, %3\n\t"
;         "ds_read_b128 %4, %14\n\tds_read_b128 %5, %14 offset:4096\n\tds_read_b128 %6, %18\n\tds_read_b128 %7, %18 offset:4096\n\t"
;         "s_waitcnt lgkmcnt(4)\n\t"
;         "v_mfma_f32_32x32x16_bf16 %0, %8, %10, %0\n\tv_mfma_f32_32x32x16_bf16 %1, %8, %11, %1\n\tv_mfma_f32_32x32x16_bf16 %2, %9, %10, %2\n\tv_mfma_f32_32x32x16_bf16 %3, %9, %11, %3\n\t"
;         "ds_read_b128 %8, %15\n\tds_read_b128 %9, %15 offset:4096\n\tds_read_b128 %10, %19\n\tds_read_b128 %11, %19 offset:4096\n\t"
;         "s_waitcnt lgkmcnt(4)\n\t"
;         "v_mfma_f32_32x32x16_bf16 %0, %4, %6, %0\n\tv_mfma_f32_32x32x16_bf16 %1, %4, %7, %1\n\tv_mfma_f32_32x32x16_bf16 %2, %5, %6, %2\n\tv_mfma_f32_32x32x16_bf16 %3, %5, %7, %3\n\t"
;         "s_waitcnt lgkmcnt(0)\n\t"
;         "v_mfma_f32_32x32x16_bf16 %0, %8, %10, %0\n\tv_mfma_f32_32x32x16_bf16 %1, %8, %11, %1\n\tv_mfma_f32_32x32x16_bf16 %2, %9, %10, %2\n\tv_mfma_f32_32x32x16_bf16 %3, %9, %11, %3"
	v_mfma_f32_16x16x32_bf16 v[0:3], v[84:87], v[100:103], v[0:3]
	v_mfma_f32_16x16x32_bf16 v[4:7], v[84:87], v[104:107], v[4:7]
	v_mfma_f32_16x16x32_bf16 v[8:11], v[84:87], v[108:111], v[8:11]
	v_mfma_f32_16x16x32_bf16 v[12:15], v[84:87], v[112:115], v[12:15]
	v_mfma_f32_16x16x32_bf16 v[16:19], v[88:91], v[100:103], v[16:19]
	s_add_u32 m0, s30, 0x1e000
	v_lshl_add_u64 v[126:127], v[70:71], 0, s[24:25]
	global_load_lds_dwordx4 v[126:127], off
	v_mfma_f32_16x16x32_bf16 v[20:23], v[88:91], v[104:107], v[20:23]
	v_mfma_f32_16x16x32_bf16 v[24:27], v[88:91], v[108:111], v[24:27]
	v_mfma_f32_16x16x32_bf16 v[28:31], v[88:91], v[112:115], v[28:31]
	v_mfma_f32_16x16x32_bf16 v[32:35], v[92:95], v[100:103], v[32:35]
	v_mfma_f32_16x16x32_bf16 v[36:39], v[92:95], v[104:107], v[36:39]
	s_add_u32 m0, s30, 0x20000
	v_lshl_add_u64 v[124:125], v[72:73], 0, s[24:25]
	global_load_lds_dwordx4 v[124:125], off
	v_mfma_f32_16x16x32_bf16 v[40:43], v[92:95], v[108:111], v[40:43]
	v_mfma_f32_16x16x32_bf16 v[44:47], v[92:95], v[112:115], v[44:47]
	v_mfma_f32_16x16x32_bf16 v[48:51], v[96:99], v[100:103], v[48:51]
	v_mfma_f32_16x16x32_bf16 v[52:55], v[96:99], v[104:107], v[52:55]
	v_mfma_f32_16x16x32_bf16 v[56:59], v[96:99], v[108:111], v[56:59]
	s_add_u32 m0, s30, 0x22000
	v_lshl_add_u64 v[126:127], v[74:75], 0, s[24:25]
	global_load_lds_dwordx4 v[126:127], off
	v_mfma_f32_16x16x32_bf16 v[60:63], v[96:99], v[112:115], v[60:63]
	s_waitcnt vmcnt(6) lgkmcnt(0)
	s_barrier
	ds_read_b128 v[84:87], v76 offset:49152
	ds_read_b128 v[88:91], v76 offset:51200
	ds_read_b128 v[92:95], v76 offset:53248
	ds_read_b128 v[96:99], v76 offset:55296
	ds_read_b128 v[100:103], v78 offset:49152
	ds_read_b128 v[104:107], v78 offset:51200
	ds_read_b128 v[108:111], v78 offset:53248
	ds_read_b128 v[112:115], v78 offset:55296
	v_mfma_f32_16x16x32_bf16 v[0:3], v[136:139], v[152:155], v[0:3]
	v_mfma_f32_16x16x32_bf16 v[4:7], v[136:139], v[156:159], v[4:7]
	v_mfma_f32_16x16x32_bf16 v[8:11], v[136:139], v[160:163], v[8:11]
	v_mfma_f32_16x16x32_bf16 v[12:15], v[136:139], v[164:167], v[12:15]
	v_mfma_f32_16x16x32_bf16 v[16:19], v[140:143], v[152:155], v[16:19]
	s_mov_b32 s24, 0x580
	s_mov_b32 s25, 0
	s_mov_b32 m0, s30
	v_lshl_add_u64 v[124:125], v[64:65], 0, s[24:25]
	global_load_lds_dwordx4 v[124:125], off
	v_mfma_f32_16x16x32_bf16 v[20:23], v[140:143], v[156:159], v[20:23]
	v_mfma_f32_16x16x32_bf16 v[24:27], v[140:143], v[160:163], v[24:27]
	v_mfma_f32_16x16x32_bf16 v[28:31], v[140:143], v[164:167], v[28:31]
	v_mfma_f32_16x16x32_bf16 v[32:35], v[144:147], v[152:155], v[32:35]
	v_mfma_f32_16x16x32_bf16 v[36:39], v[144:147], v[156:159], v[36:39]
	s_add_u32 m0, s30, 0x2000
	v_lshl_add_u64 v[126:127], v[66:67], 0, s[24:25]
	global_load_lds_dwordx4 v[126:127], off
	v_mfma_f32_16x16x32_bf16 v[40:43], v[144:147], v[160:163], v[40:43]
	v_mfma_f32_16x16x32_bf16 v[44:47], v[144:147], v[164:167], v[44:47]
	v_mfma_f32_16x16x32_bf16 v[48:51], v[148:151], v[152:155], v[48:51]
	v_mfma_f32_16x16x32_bf16 v[52:55], v[148:151], v[156:159], v[52:55]
	v_mfma_f32_16x16x32_bf16 v[56:59], v[148:151], v[160:163], v[56:59]
	s_add_u32 m0, s30, 0x4000
	v_lshl_add_u64 v[124:125], v[68:69], 0, s[24:25]
	global_load_lds_dwordx4 v[124:125], off
	v_mfma_f32_16x16x32_bf16 v[60:63], v[148:151], v[164:167], v[60:63]
	ds_read_b128 v[136:139], v77 offset:49152
	ds_read_b128 v[140:143], v77 offset:51200
	ds_read_b128 v[144:147], v77 offset:53248
	ds_read_b128 v[148:151], v77 offset:55296
	ds_read_b128 v[152:155], v79 offset:49152
	ds_read_b128 v[156:159], v79 offset:51200
	ds_read_b128 v[160:163], v79 offset:53248
	ds_read_b128 v[164:167], v79 offset:55296
	s_waitcnt lgkmcnt(8)
	v_mfma_f32_16x16x32_bf16 v[0:3], v[84:87], v[100:103], v[0:3]
	v_mfma_f32_16x16x32_bf16 v[4:7], v[84:87], v[104:107], v[4:7]
	v_mfma_f32_16x16x32_bf16 v[8:11], v[84:87], v[108:111], v[8:11]
	v_mfma_f32_16x16x32_bf16 v[12:15], v[84:87], v[112:115], v[12:15]
	v_mfma_f32_16x16x32_bf16 v[16:19], v[88:91], v[100:103], v[16:19]
	s_add_u32 m0, s30, 0x6000
	v_lshl_add_u64 v[126:127], v[70:71], 0, s[24:25]
	global_load_lds_dwordx4 v[126:127], off
	v_mfma_f32_16x16x32_bf16 v[20:23], v[88:91], v[104:107], v[20:23]
	v_mfma_f32_16x16x32_bf16 v[24:27], v[88:91], v[108:111], v[24:27]
	v_mfma_f32_16x16x32_bf16 v[28:31], v[88:91], v[112:115], v[28:31]
	v_mfma_f32_16x16x32_bf16 v[32:35], v[92:95], v[100:103], v[32:35]
	v_mfma_f32_16x16x32_bf16 v[36:39], v[92:95], v[104:107], v[36:39]
	s_add_u32 m0, s30, 0x8000
	v_lshl_add_u64 v[124:125], v[72:73], 0, s[24:25]
	global_load_lds_dwordx4 v[124:125], off
	v_mfma_f32_16x16x32_bf16 v[40:43], v[92:95], v[108:111], v[40:43]
	v_mfma_f32_16x16x32_bf16 v[44:47], v[92:95], v[112:115], v[44:47]
	v_mfma_f32_16x16x32_bf16 v[48:51], v[96:99], v[100:103], v[48:51]
	v_mfma_f32_16x16x32_bf16 v[52:55], v[96:99], v[104:107], v[52:55]
	v_mfma_f32_16x16x32_bf16 v[56:59], v[96:99], v[108:111], v[56:59]
	s_add_u32 m0, s30, 0xa000
	v_lshl_add_u64 v[126:127], v[74:75], 0, s[24:25]
	global_load_lds_dwordx4 v[126:127], off
	v_mfma_f32_16x16x32_bf16 v[60:63], v[96:99], v[112:115], v[60:63]
	s_waitcnt vmcnt(6) lgkmcnt(0)
	s_barrier
;     ...
;   for (int kt = 0; kt < nk; ++kt) {
;     if (kt + 1 < nk) asm volatile("s_waitcnt vmcnt(6)" ::: "memory");
;     else asm volatile("s_waitcnt vmcnt(0)" ::: "memory");
;     __builtin_amdgcn_s_barrier();
;     asm volatile("" ::: "memory");
;     if (kt + 2 < nk) { const int st2 = (st >= 1) ? st - 1 : 2; GEMM_ISSUE(kt + 2, st2); }
;     const char* la = lds + st * STAGE_B;
;     const char* lb = la + 32768;
;     const unsigned sa_u = (unsigned)(size_t)la + arow_u, sb_u = (unsigned)(size_t)lb + brow_u;
;     const unsigned a0 = sa_u + co0, a1 = sa_u + co1, a2 = sa_u + co2, a3 = sa_u + co3;
;     const unsigned b0 = sb_u + co0, b1 = sb_u + co1, b2 = sb_u + co2, b3 = sb_u + co3;
;     {
;       bf16x8 p0, p1, q0, q1, u0, u1, w0, w1;
;       asm volatile(
;         "ds_read_b128 %4, %12\n\tds_read_b128 %5, %12 offset:4096\n\tds_read_b128 %6, %16\n\tds_read_b128 %7, %16 offset:4096\n\t"
;         "ds_read_b128 %8, %13\n\tds_read_b128 %9, %13 offset:4096\n\tds_read_b128 %10, %17\n\tds_read_b128 %11, %17 offset:4096\n\t"
;         "s_waitcnt lgkmcnt(4)\n\t"
;         "v_mfma_f32_32x32x16_bf16 %0, %4, %6, %0\n\tv_mfma_f32_32x32x16_bf16 %1, %4, %7, %1\n\tv_mfma_f32_32x32x16_bf16 %2, %5, %6, %2\n\tv_mfma_f32_32x32x16_bf16 %3, %5, %7, %3\n\t"
;         "ds_read_b128 %4, %14\n\tds_read_b128 %5, %14 offset:4096\n\tds_read_b128 %6, %18\n\tds_read_b128 %7, %18 offset:4096\n\t"
;         "s_waitcnt lgkmcnt(4)\n\t"
;         "v_mfma_f32_32x32x16_bf16 %0, %8, %10, %0\n\tv_mfma_f32_32x32x16_bf16 %1, %8, %11, %1\n\tv_mfma_f32_32x32x16_bf16 %2, %9, %10, %2\n\tv_mfma_f32_32x32x16_bf16 %3, %9, %11, %3\n\t"
;         "ds_read_b128 %8, %15\n\tds_read_b128 %9, %15 offset:4096\n\tds_read_b128 %10, %19\n\tds_read_b128 %11, %19 offset:4096\n\t"
;         "s_waitcnt lgkmcnt(4)\n\t"
;         "v_mfma_f32_32x32x16_bf16 %0, %4, %6, %0\n\tv_mfma_f32_32x32x16_bf16 %1, %4, %7, %1\n\tv_mfma_f32_32x32x16_bf16 %2, %5, %6, %2\n\tv_mfma_f32_32x32x16_bf16 %3, %5, %7, %3\n\t"
;         "s_waitcnt lgkmcnt(0)\n\t"
;         "v_mfma_f32_32x32x16_bf16 %0, %8, %10, %0\n\tv_mfma_f32_32x32x16_bf16 %1, %8, %11, %1\n\tv_mfma_f32_32x32x16_bf16 %2, %9, %10, %2\n\tv_mfma_f32_32x32x16_bf16 %3, %9, %11, %3"
	ds_read_b128 v[84:87], v80
	ds_read_b128 v[88:91], v80 offset:2048
	ds_read_b128 v[92:95], v80 offset:4096
	ds_read_b128 v[96:99], v80 offset:6144
	ds_read_b128 v[100:103], v82
	ds_read_b128 v[104:107], v82 offset:2048
	ds_read_b128 v[108:111], v82 offset:4096
	ds_read_b128 v[112:115], v82 offset:6144
	v_mfma_f32_16x16x32_bf16 v[0:3], v[136:139], v[152:155], v[0:3]
	v_mfma_f32_16x16x32_bf16 v[4:7], v[136:139], v[156:159], v[4:7]
	v_mfma_f32_16x16x32_bf16 v[8:11], v[136:139], v[160:163], v[8:11]
	v_mfma_f32_16x16x32_bf16 v[12:15], v[136:139], v[164:167], v[12:15]
	v_mfma_f32_16x16x32_bf16 v[16:19], v[140:143], v[152:155], v[16:19]
	s_mov_b32 s24, 0x600
	s_mov_b32 s25, 0
	s_add_u32 m0, s30, 0xc000
	v_lshl_add_u64 v[124:125], v[64:65], 0, s[24:25]
	global_load_lds_dwordx4 v[124:125], off
	v_mfma_f32_16x16x32_bf16 v[20:23], v[140:143], v[156:159], v[20:23]
	v_mfma_f32_16x16x32_bf16 v[24:27], v[140:143], v[160:163], v[24:27]
	v_mfma_f32_16x16x32_bf16 v[28:31], v[140:143], v[164:167], v[28:31]
	v_mfma_f32_16x16x32_bf16 v[32:35], v[144:147], v[152:155], v[32:35]
	v_mfma_f32_16x16x32_bf16 v[36:39], v[144:147], v[156:159], v[36:39]
	s_add_u32 m0, s30, 0xe000
	v_lshl_add_u64 v[126:127], v[66:67], 0, s[24:25]
	global_load_lds_dwordx4 v[126:127], off
	v_mfma_f32_16x16x32_bf16 v[40:43], v[144:147], v[160:163], v[40:43]
	v_mfma_f32_16x16x32_bf16 v[44:47], v[144:147], v[164:167], v[44:47]
	v_mfma_f32_16x16x32_bf16 v[48:51], v[148:151], v[152:155], v[48:51]
	v_mfma_f32_16x16x32_bf16 v[52:55], v[148:151], v[156:159], v[52:55]
	v_mfma_f32_16x16x32_bf16 v[56:59], v[148:151], v[160:163], v[56:59]
	s_add_u32 m0, s30, 0x10000
	v_lshl_add_u64 v[124:125], v[68:69], 0, s[24:25]
	global_load_lds_dwordx4 v[124:125], off
	v_mfma_f32_16x16x32_bf16 v[60:63], v[148:151], v[164:167], v[60:63]
	ds_read_b128 v[136:139], v81
	ds_read_b128 v[140:143], v81 offset:2048
	ds_read_b128 v[144:147], v81 offset:4096
	ds_read_b128 v[148:151], v81 offset:6144
	ds_read_b128 v[152:155], v83
	ds_read_b128 v[156:159], v83 offset:2048
	ds_read_b128 v[160:163], v83 offset:4096
	ds_read_b128 v[164:167], v83 offset:6144
	s_waitcnt lgkmcnt(8)
	v_mfma_f32_16x16x32_bf16 v[0:3], v[84:87], v[100:103], v[0:3]
	v_mfma_f32_16x16x32_bf16 v[4:7], v[84:87], v[104:107], v[4:7]
	v_mfma_f32_16x16x32_bf16 v[8:11], v[84:87], v[108:111], v[8:11]
	v_mfma_f32_16x16x32_bf16 v[12:15], v[84:87], v[112:115], v[12:15]
	v_mfma_f32_16x16x32_bf16 v[16:19], v[88:91], v[100:103], v[16:19]
	s_add_u32 m0, s30, 0x12000
	v_lshl_add_u64 v[126:127], v[70:71], 0, s[24:25]
	global_load_lds_dwordx4 v[126:127], off
	v_mfma_f32_16x16x32_bf16 v[20:23], v[88:91], v[104:107], v[20:23]
	v_mfma_f32_16x16x32_bf16 v[24:27], v[88:91], v[108:111], v[24:27]
	v_mfma_f32_16x16x32_bf16 v[28:31], v[88:91], v[112:115], v[28:31]
	v_mfma_f32_16x16x32_bf16 v[32:35], v[92:95], v[100:103], v[32:35]
	v_mfma_f32_16x16x32_bf16 v[36:39], v[92:95], v[104:107], v[36:39]
	s_add_u32 m0, s30, 0x14000
	v_lshl_add_u64 v[124:125], v[72:73], 0, s[24:25]
	global_load_lds_dwordx4 v[124:125], off
	v_mfma_f32_16x16x32_bf16 v[40:43], v[92:95], v[108:111], v[40:43]
	v_mfma_f32_16x16x32_bf16 v[44:47], v[92:95], v[112:115], v[44:47]
	v_mfma_f32_16x16x32_bf16 v[48:51], v[96:99], v[100:103], v[48:51]
	v_mfma_f32_16x16x32_bf16 v[52:55], v[96:99], v[104:107], v[52:55]
	v_mfma_f32_16x16x32_bf16 v[56:59], v[96:99], v[108:111], v[56:59]
	s_add_u32 m0, s30, 0x16000
	v_lshl_add_u64 v[126:127], v[74:75], 0, s[24:25]
	global_load_lds_dwordx4 v[126:127], off
	v_mfma_f32_16x16x32_bf16 v[60:63], v[96:99], v[112:115], v[60:63]
	s_waitcnt vmcnt(6) lgkmcnt(0)
	s_barrier
	ds_read_b128 v[84:87], v76
	ds_read_b128 v[88:91], v76 offset:2048
	ds_read_b128 v[92:95], v76 offset:4096
	ds_read_b128 v[96:99], v76 offset:6144
	ds_read_b128 v[100:103], v78
	ds_read_b128 v[104:107], v78 offset:2048
	ds_read_b128 v[108:111], v78 offset:4096
	ds_read_b128 v[112:115], v78 offset:6144
	v_mfma_f32_16x16x32_bf16 v[0:3], v[136:139], v[152:155], v[0:3]
	v_mfma_f32_16x16x32_bf16 v[4:7], v[136:139], v[156:159], v[4:7]
	v_mfma_f32_16x16x32_bf16 v[8:11], v[136:139], v[160:163], v[8:11]
	v_mfma_f32_16x16x32_bf16 v[12:15], v[136:139], v[164:167], v[12:15]
	v_mfma_f32_16x16x32_bf16 v[16:19], v[140:143], v[152:155], v[16:19]
	s_mov_b32 s24, 0x680
	s_mov_b32 s25, 0
	s_add_u32 m0, s30, 0x18000
	v_lshl_add_u64 v[124:125], v[64:65], 0, s[24:25]
	global_load_lds_dwordx4 v[124:125], off
	v_mfma_f32_16x16x32_bf16 v[20:23], v[140:143], v[156:159], v[20:23]
	v_mfma_f32_16x16x32_bf16 v[24:27], v[140:143], v[160:163], v[24:27]
	v_mfma_f32_16x16x32_bf16 v[28:31], v[140:143], v[164:167], v[28:31]
	v_mfma_f32_16x16x32_bf16 v[32:35], v[144:147], v[152:155], v[32:35]
	v_mfma_f32_16x16x32_bf16 v[36:39], v[144:147], v[156:159], v[36:39]
	s_add_u32 m0, s30, 0x1a000
	v_lshl_add_u64 v[126:127], v[66:67], 0, s[24:25]
	global_load_lds_dwordx4 v[126:127], off
	v_mfma_f32_16x16x32_bf16 v[40:43], v[144:147], v[160:163], v[40:43]
	v_mfma_f32_16x16x32_bf16 v[44:47], v[144:147], v[164:167], v[44:47]
	v_mfma_f32_16x16x32_bf16 v[48:51], v[148:151], v[152:155], v[48:51]
	v_mfma_f32_16x16x32_bf16 v[52:55], v[148:151], v[156:159], v[52:55]
	v_mfma_f32_16x16x32_bf16 v[56:59], v[148:151], v[160:163], v[56:59]
	s_add_u32 m0, s30, 0x1c000
	v_lshl_add_u64 v[124:125], v[68:69], 0, s[24:25]
	global_load_lds_dwordx4 v[124:125], off
	v_mfma_f32_16x16x32_bf16 v[60:63], v[148:151], v[164:167], v[60:63]
	ds_read_b128 v[136:139], v77
	ds_read_b128 v[140:143], v77 offset:2048
	ds_read_b128 v[144:147], v77 offset:4096
	ds_read_b128 v[148:151], v77 offset:6144
	ds_read_b128 v[152:155], v79
	ds_read_b128 v[156:159], v79 offset:2048
	ds_read_b128 v[160:163], v79 offset:4096
	ds_read_b128 v[164:167], v79 offset:6144
	s_waitcnt lgkmcnt(8)
;     ...
;   for (int kt = 0; kt < nk; ++kt) {
;     if (kt + 1 < nk) asm volatile("s_waitcnt vmcnt(6)" ::: "memory");
;     else asm volatile("s_waitcnt vmcnt(0)" ::: "memory");
;     __builtin_amdgcn_s_barrier();
;     asm volatile("" ::: "memory");
;     if (kt + 2 < nk) { const int st2 = (st >= 1) ? st - 1 : 2; GEMM_ISSUE(kt + 2, st2); }
;     const char* la = lds + st * STAGE_B;
;     const char* lb = la + 32768;
;     const unsigned sa_u = (unsigned)(size_t)la + arow_u, sb_u = (unsigned)(size_t)lb + brow_u;
;     const unsigned a0 = sa_u + co0, a1 = sa_u + co1, a2 = sa_u + co2, a3 = sa_u + co3;
;     const unsigned b0 = sb_u + co0, b1 = sb_u + co1, b2 = sb_u + co2, b3 = sb_u + co3;
;     {
;       bf16x8 p0, p1, q0, q1, u0, u1, w0, w1;
;       asm volatile(
;         "ds_read_b128 %4, %12\n\tds_read_b128 %5, %12 offset:4096\n\tds_read_b128 %6, %16\n\tds_read_b128 %7, %16 offset:4096\n\t"
;         "ds_read_b128 %8, %13\n\tds_read_b128 %9, %13 offset:4096\n\tds_read_b128 %10, %17\n\tds_read_b128 %11, %17 offset:4096\n\t"
;         "s_waitcnt lgkmcnt(4)\n\t"
;         "v_mfma_f32_32x32x16_bf16 %0, %4, %6, %0\n\tv_mfma_f32_32x32x16_bf16 %1, %4, %7, %1\n\tv_mfma_f32_32x32x16_bf16 %2, %5, %6, %2\n\tv_mfma_f32_32x32x16_bf16 %3, %5, %7, %3\n\t"
;         "ds_read_b128 %4, %14\n\tds_read_b128 %5, %14 offset:4096\n\tds_read_b128 %6, %18\n\tds_read_b128 %7, %18 offset:4096\n\t"
;         "s_waitcnt lgkmcnt(4)\n\t"
;         "v_mfma_f32_32x32x16_bf16 %0, %8, %10, %0\n\tv_mfma_f32_32x32x16_bf16 %1, %8, %11, %1\n\tv_mfma_f32_32x32x16_bf16 %2, %9, %10, %2\n\tv_mfma_f32_32x32x16_bf16 %3, %9, %11, %3\n\t"
;         "ds_read_b128 %8, %15\n\tds_read_b128 %9, %15 offset:4096\n\tds_read_b128 %10, %19\n\tds_read_b128 %11, %19 offset:4096\n\t"
;         "s_waitcnt lgkmcnt(4)\n\t"
;         "v_mfma_f32_32x32x16_bf16 %0, %4, %6, %0\n\tv_mfma_f32_32x32x16_bf16 %1, %4, %7, %1\n\tv_mfma_f32_32x32x16_bf16 %2, %5, %6, %2\n\tv_mfma_f32_32x32x16_bf16 %3, %5, %7, %3\n\t"
;         "s_waitcnt lgkmcnt(0)\n\t"
;         "v_mfma_f32_32x32x16_bf16 %0, %8, %10, %0\n\tv_mfma_f32_32x32x16_bf16 %1, %8, %11, %1\n\tv_mfma_f32_32x32x16_bf16 %2, %9, %10, %2\n\tv_mfma_f32_32x32x16_bf16 %3, %9, %11, %3"
	v_mfma_f32_16x16x32_bf16 v[0:3], v[84:87], v[100:103], v[0:3]
	v_mfma_f32_16x16x32_bf16 v[4:7], v[84:87], v[104:107], v[4:7]
	v_mfma_f32_16x16x32_bf16 v[8:11], v[84:87], v[108:111], v[8:11]
	v_mfma_f32_16x16x32_bf16 v[12:15], v[84:87], v[112:115], v[12:15]
	v_mfma_f32_16x16x32_bf16 v[16:19], v[88:91], v[100:103], v[16:19]
	s_add_u32 m0, s30, 0x1e000
	v_lshl_add_u64 v[126:127], v[70:71], 0, s[24:25]
	global_load_lds_dwordx4 v[126:127], off
	v_mfma_f32_16x16x32_bf16 v[20:23], v[88:91], v[104:107], v[20:23]
	v_mfma_f32_16x16x32_bf16 v[24:27], v[88:91], v[108:111], v[24:27]
	v_mfma_f32_16x16x32_bf16 v[28:31], v[88:91], v[112:115], v[28:31]
	v_mfma_f32_16x16x32_bf16 v[32:35], v[92:95], v[100:103], v[32:35]
	v_mfma_f32_16x16x32_bf16 v[36:39], v[92:95], v[104:107], v[36:39]
	s_add_u32 m0, s30, 0x20000
	v_lshl_add_u64 v[124:125], v[72:73], 0, s[24:25]
	global_load_lds_dwordx4 v[124:125], off
	v_mfma_f32_16x16x32_bf16 v[40:43], v[92:95], v[108:111], v[40:43]
	v_mfma_f32_16x16x32_bf16 v[44:47], v[92:95], v[112:115], v[44:47]
	v_mfma_f32_16x16x32_bf16 v[48:51], v[96:99], v[100:103], v[48:51]
	v_mfma_f32_16x16x32_bf16 v[52:55], v[96:99], v[104:107], v[52:55]
	v_mfma_f32_16x16x32_bf16 v[56:59], v[96:99], v[108:111], v[56:59]
	s_add_u32 m0, s30, 0x22000
	v_lshl_add_u64 v[126:127], v[74:75], 0, s[24:25]
	global_load_lds_dwordx4 v[126:127], off
	v_mfma_f32_16x16x32_bf16 v[60:63], v[96:99], v[112:115], v[60:63]
	s_waitcnt vmcnt(6) lgkmcnt(0)
	s_barrier
	ds_read_b128 v[84:87], v76 offset:49152
	ds_read_b128 v[88:91], v76 offset:51200
	ds_read_b128 v[92:95], v76 offset:53248
	ds_read_b128 v[96:99], v76 offset:55296
	ds_read_b128 v[100:103], v78 offset:49152
	ds_read_b128 v[104:107], v78 offset:51200
	ds_read_b128 v[108:111], v78 offset:53248
	ds_read_b128 v[112:115], v78 offset:55296
	v_mfma_f32_16x16x32_bf16 v[0:3], v[136:139], v[152:155], v[0:3]
	v_mfma_f32_16x16x32_bf16 v[4:7], v[136:139], v[156:159], v[4:7]
	v_mfma_f32_16x16x32_bf16 v[8:11], v[136:139], v[160:163], v[8:11]
	v_mfma_f32_16x16x32_bf16 v[12:15], v[136:139], v[164:167], v[12:15]
	v_mfma_f32_16x16x32_bf16 v[16:19], v[140:143], v[152:155], v[16:19]
	s_mov_b32 s24, 0x700
	s_mov_b32 s25, 0
	s_mov_b32 m0, s30
	v_lshl_add_u64 v[124:125], v[64:65], 0, s[24:25]
	global_load_lds_dwordx4 v[124:125], off
	v_mfma_f32_16x16x32_bf16 v[20:23], v[140:143], v[156:159], v[20:23]
	v_mfma_f32_16x16x32_bf16 v[24:27], v[140:143], v[160:163], v[24:27]
	v_mfma_f32_16x16x32_bf16 v[28:31], v[140:143], v[164:167], v[28:31]
	v_mfma_f32_16x16x32_bf16 v[32:35], v[144:147], v[152:155], v[32:35]
	v_mfma_f32_16x16x32_bf16 v[36:39], v[144:147], v[156:159], v[36:39]
	s_add_u32 m0, s30, 0x2000
	v_lshl_add_u64 v[126:127], v[66:67], 0, s[24:25]
	global_load_lds_dwordx4 v[126:127], off
	v_mfma_f32_16x16x32_bf16 v[40:43], v[144:147], v[160:163], v[40:43]
	v_mfma_f32_16x16x32_bf16 v[44:47], v[144:147], v[164:167], v[44:47]
	v_mfma_f32_16x16x32_bf16 v[48:51], v[148:151], v[152:155], v[48:51]
	v_mfma_f32_16x16x32_bf16 v[52:55], v[148:151], v[156:159], v[52:55]
	v_mfma_f32_16x16x32_bf16 v[56:59], v[148:151], v[160:163], v[56:59]
	s_add_u32 m0, s30, 0x4000
	v_lshl_add_u64 v[124:125], v[68:69], 0, s[24:25]
	global_load_lds_dwordx4 v[124:125], off
	v_mfma_f32_16x16x32_bf16 v[60:63], v[148:151], v[164:167], v[60:63]
	ds_read_b128 v[136:139], v77 offset:49152
	ds_read_b128 v[140:143], v77 offset:51200
	ds_read_b128 v[144:147], v77 offset:53248
	ds_read_b128 v[148:151], v77 offset:55296
	ds_read_b128 v[152:155], v79 offset:49152
	ds_read_b128 v[156:159], v79 offset:51200
	ds_read_b128 v[160:163], v79 offset:53248
	ds_read_b128 v[164:167], v79 offset:55296
	s_waitcnt lgkmcnt(8)
	v_mfma_f32_16x16x32_bf16 v[0:3], v[84:87], v[100:103], v[0:3]
	v_mfma_f32_16x16x32_bf16 v[4:7], v[84:87], v[104:107], v[4:7]
	v_mfma_f32_16x16x32_bf16 v[8:11], v[84:87], v[108:111], v[8:11]
	v_mfma_f32_16x16x32_bf16 v[12:15], v[84:87], v[112:115], v[12:15]
	v_mfma_f32_16x16x32_bf16 v[16:19], v[88:91], v[100:103], v[16:19]
	s_add_u32 m0, s30, 0x6000
	v_lshl_add_u64 v[126:127], v[70:71], 0, s[24:25]
	global_load_lds_dwordx4 v[126:127], off
	v_mfma_f32_16x16x32_bf16 v[20:23], v[88:91], v[104:107], v[20:23]
	v_mfma_f32_16x16x32_bf16 v[24:27], v[88:91], v[108:111], v[24:27]
	v_mfma_f32_16x16x32_bf16 v[28:31], v[88:91], v[112:115], v[28:31]
	v_mfma_f32_16x16x32_bf16 v[32:35], v[92:95], v[100:103], v[32:35]
	v_mfma_f32_16x16x32_bf16 v[36:39], v[92:95], v[104:107], v[36:39]
	s_add_u32 m0, s30, 0x8000
	v_lshl_add_u64 v[124:125], v[72:73], 0, s[24:25]
	global_load_lds_dwordx4 v[124:125], off
	v_mfma_f32_16x16x32_bf16 v[40:43], v[92:95], v[108:111], v[40:43]
	v_mfma_f32_16x16x32_bf16 v[44:47], v[92:95], v[112:115], v[44:47]
	v_mfma_f32_16x16x32_bf16 v[48:51], v[96:99], v[100:103], v[48:51]
	v_mfma_f32_16x16x32_bf16 v[52:55], v[96:99], v[104:107], v[52:55]
	v_mfma_f32_16x16x32_bf16 v[56:59], v[96:99], v[108:111], v[56:59]
	s_add_u32 m0, s30, 0xa000
	v_lshl_add_u64 v[126:127], v[74:75], 0, s[24:25]
	global_load_lds_dwordx4 v[126:127], off
	v_mfma_f32_16x16x32_bf16 v[60:63], v[96:99], v[112:115], v[60:63]
	s_waitcnt vmcnt(6) lgkmcnt(0)
	s_barrier
;     ...
;   if (PART != 2) {
;     GEMM_ISSUE(0, 0);
;     if (nk > 1) GEMM_ISSUE(1, 1);
;   }
;   if (PART == 1) return;
;   int st = 0;
;   for (int kt = 0; kt < nk; ++kt) {
;     if (kt + 1 < nk) asm volatile("s_waitcnt vmcnt(6)" ::: "memory");
;     else asm volatile("s_waitcnt vmcnt(0)" ::: "memory");
;     __builtin_amdgcn_s_barrier();
;     asm volatile("" ::: "memory");
;     if (kt + 2 < nk) { const int st2 = (st >= 1) ? st - 1 : 2; GEMM_ISSUE(kt + 2, st2); }
;     const char* la = lds + st * STAGE_B;
;     const char* lb = la + 32768;
;     const unsigned sa_u = (unsigned)(size_t)la + arow_u, sb_u = (unsigned)(size_t)lb + brow_u;
;     const unsigned a0 = sa_u + co0, a1 = sa_u + co1, a2 = sa_u + co2, a3 = sa_u + co3;
;     const unsigned b0 = sb_u + co0, b1 = sb_u + co1, b2 = sb_u + co2, b3 = sb_u + co3;
;     {
;       bf16x8 p0, p1, q0, q1, u0, u1, w0, w1;
;       asm volatile(
;         "ds_read_b128 %4, %12\n\tds_read_b128 %5, %12 offset:4096\n\tds_read_b128 %6, %16\n\tds_read_b128 %7, %16 offset:4096\n\t"
;         "ds_read_b128 %8, %13\n\tds_read_b128 %9, %13 offset:4096\n\tds_read_b128 %10, %17\n\tds_read_b128 %11, %17 offset:4096\n\t"
;         "s_waitcnt lgkmcnt(4)\n\t"
;         "v_mfma_f32_32x32x16_bf16 %0, %4, %6, %0\n\tv_mfma_f32_32x32x16_bf16 %1, %4, %7, %1\n\tv_mfma_f32_32x32x16_bf16 %2, %5, %6, %2\n\tv_mfma_f32_32x32x16_bf16 %3, %5, %7, %3\n\t"
;         "ds_read_b128 %4, %14\n\tds_read_b128 %5, %14 offset:4096\n\tds_read_b128 %6, %18\n\tds_read_b128 %7, %18 offset:4096\n\t"
;         "s_waitcnt lgkmcnt(4)\n\t"
;         "v_mfma_f32_32x32x16_bf16 %0, %8, %10, %0\n\tv_mfma_f32_32x32x16_bf16 %1, %8, %11, %1\n\tv_mfma_f32_32x32x16_bf16 %2, %9, %10, %2\n\tv_mfma_f32_32x32x16_bf16 %3, %9, %11, %3\n\t"
;         "ds_read_b128 %8, %15\n\tds_read_b128 %9, %15 offset:4096\n\tds_read_b128 %10, %19\n\tds_read_b128 %11, %19 offset:4096\n\t"
;         "s_waitcnt lgkmcnt(4)\n\t"
;         "v_mfma_f32_32x32x16_bf16 %0, %4, %6, %0\n\tv_mfma_f32_32x32x16_bf16 %1, %4, %7, %1\n\tv_mfma_f32_32x32x16_bf16 %2, %5, %6, %2\n\tv_mfma_f32_32x32x16_bf16 %3, %5, %7, %3\n\t"
;         "s_waitcnt lgkmcnt(0)\n\t"
;         "v_mfma_f32_32x32x16_bf16 %0, %8, %10, %0\n\tv_mfma_f32_32x32x16_bf16 %1, %8, %11, %1\n\tv_mfma_f32_32x32x16_bf16 %2, %9, %10, %2\n\tv_mfma_f32_32x32x16_bf16 %3, %9, %11, %3"
	ds_read_b128 v[84:87], v80
	ds_read_b128 v[88:91], v80 offset:2048
	ds_read_b128 v[92:95], v80 offset:4096
	ds_read_b128 v[96:99], v80 offset:6144
	ds_read_b128 v[100:103], v82
	ds_read_b128 v[104:107], v82 offset:2048
	ds_read_b128 v[108:111], v82 offset:4096
	ds_read_b128 v[112:115], v82 offset:6144
	v_mfma_f32_16x16x32_bf16 v[0:3], v[136:139], v[152:155], v[0:3]
	v_mfma_f32_16x16x32_bf16 v[4:7], v[136:139], v[156:159], v[4:7]
	v_mfma_f32_16x16x32_bf16 v[8:11], v[136:139], v[160:163], v[8:11]
	v_mfma_f32_16x16x32_bf16 v[12:15], v[136:139], v[164:167], v[12:15]
	v_mfma_f32_16x16x32_bf16 v[16:19], v[140:143], v[152:155], v[16:19]
	s_mov_b32 s24, 0x780
	s_mov_b32 s25, 0
	s_add_u32 m0, s30, 0xc000
	v_lshl_add_u64 v[124:125], v[64:65], 0, s[24:25]
	global_load_lds_dwordx4 v[124:125], off
	v_mfma_f32_16x16x32_bf16 v[20:23], v[140:143], v[156:159], v[20:23]
	v_mfma_f32_16x16x32_bf16 v[24:27], v[140:143], v[160:163], v[24:27]
	v_mfma_f32_16x16x32_bf16 v[28:31], v[140:143], v[164:167], v[28:31]
	v_mfma_f32_16x16x32_bf16 v[32:35], v[144:147], v[152:155], v[32:35]
	v_mfma_f32_16x16x32_bf16 v[36:39], v[144:147], v[156:159], v[36:39]
	s_add_u32 m0, s30, 0xe000
	v_lshl_add_u64 v[126:127], v[66:67], 0, s[24:25]
	global_load_lds_dwordx4 v[126:127], off
	v_mfma_f32_16x16x32_bf16 v[40:43], v[144:147], v[160:163], v[40:43]
	v_mfma_f32_16x16x32_bf16 v[44:47], v[144:147], v[164:167], v[44:47]
	v_mfma_f32_16x16x32_bf16 v[48:51], v[148:151], v[152:155], v[48:51]
	v_mfma_f32_16x16x32_bf16 v[52:55], v[148:151], v[156:159], v[52:55]
	v_mfma_f32_16x16x32_bf16 v[56:59], v[148:151], v[160:163], v[56:59]
	s_add_u32 m0, s30, 0x10000
	v_lshl_add_u64 v[124:125], v[68:69], 0, s[24:25]
	global_load_lds_dwordx4 v[124:125], off
	v_mfma_f32_16x16x32_bf16 v[60:63], v[148:151], v[164:167], v[60:63]
	ds_read_b128 v[136:139], v81
	ds_read_b128 v[140:143], v81 offset:2048
	ds_read_b128 v[144:147], v81 offset:4096
	ds_read_b128 v[148:151], v81 offset:6144
	ds_read_b128 v[152:155], v83
	ds_read_b128 v[156:159], v83 offset:2048
	ds_read_b128 v[160:163], v83 offset:4096
	ds_read_b128 v[164:167], v83 offset:6144
	s_waitcnt lgkmcnt(8)
	v_mfma_f32_16x16x32_bf16 v[0:3], v[84:87], v[100:103], v[0:3]
	v_mfma_f32_16x16x32_bf16 v[4:7], v[84:87], v[104:107], v[4:7]
	v_mfma_f32_16x16x32_bf16 v[8:11], v[84:87], v[108:111], v[8:11]
	v_mfma_f32_16x16x32_bf16 v[12:15], v[84:87], v[112:115], v[12:15]
	v_mfma_f32_16x16x32_bf16 v[16:19], v[88:91], v[100:103], v[16:19]
	s_add_u32 m0, s30, 0x12000
	v_lshl_add_u64 v[126:127], v[70:71], 0, s[24:25]
	global_load_lds_dwordx4 v[126:127], off
	v_mfma_f32_16x16x32_bf16 v[20:23], v[88:91], v[104:107], v[20:23]
	v_mfma_f32_16x16x32_bf16 v[24:27], v[88:91], v[108:111], v[24:27]
	v_mfma_f32_16x16x32_bf16 v[28:31], v[88:91], v[112:115], v[28:31]
	v_mfma_f32_16x16x32_bf16 v[32:35], v[92:95], v[100:103], v[32:35]
	v_mfma_f32_16x16x32_bf16 v[36:39], v[92:95], v[104:107], v[36:39]
	s_add_u32 m0, s30, 0x14000
	v_lshl_add_u64 v[124:125], v[72:73], 0, s[24:25]
	global_load_lds_dwordx4 v[124:125], off
	v_mfma_f32_16x16x32_bf16 v[40:43], v[92:95], v[108:111], v[40:43]
	v_mfma_f32_16x16x32_bf16 v[44:47], v[92:95], v[112:115], v[44:47]
	v_mfma_f32_16x16x32_bf16 v[48:51], v[96:99], v[100:103], v[48:51]
	v_mfma_f32_16x16x32_bf16 v[52:55], v[96:99], v[104:107], v[52:55]
	v_mfma_f32_16x16x32_bf16 v[56:59], v[96:99], v[108:111], v[56:59]
	s_add_u32 m0, s30, 0x16000
	v_lshl_add_u64 v[126:127], v[74:75], 0, s[24:25]
	global_load_lds_dwordx4 v[126:127], off
	v_mfma_f32_16x16x32_bf16 v[60:63], v[96:99], v[112:115], v[60:63]
	s_waitcnt vmcnt(6) lgkmcnt(0)
	s_barrier
	ds_read_b128 v[84:87], v76
	ds_read_b128 v[88:91], v76 offset:2048
	ds_read_b128 v[92:95], v76 offset:4096
	ds_read_b128 v[96:99], v76 offset:6144
	ds_read_b128 v[100:103], v78
	ds_read_b128 v[104:107], v78 offset:2048
	ds_read_b128 v[108:111], v78 offset:4096
	ds_read_b128 v[112:115], v78 offset:6144
	v_mfma_f32_16x16x32_bf16 v[0:3], v[136:139], v[152:155], v[0:3]
	v_mfma_f32_16x16x32_bf16 v[4:7], v[136:139], v[156:159], v[4:7]
	v_mfma_f32_16x16x32_bf16 v[8:11], v[136:139], v[160:163], v[8:11]
	v_mfma_f32_16x16x32_bf16 v[12:15], v[136:139], v[164:167], v[12:15]
	v_mfma_f32_16x16x32_bf16 v[16:19], v[140:143], v[152:155], v[16:19]
	s_add_u32 s24, s56, 0x0
	s_addc_u32 s25, s57, 0
	s_add_u32 m0, s30, 0x18000
	v_lshl_add_u64 v[124:125], v[64:65], 0, s[24:25]
	global_load_lds_dwordx4 v[124:125], off
	v_mfma_f32_16x16x32_bf16 v[20:23], v[140:143], v[156:159], v[20:23]
	v_mfma_f32_16x16x32_bf16 v[24:27], v[140:143], v[160:163], v[24:27]
	v_mfma_f32_16x16x32_bf16 v[28:31], v[140:143], v[164:167], v[28:31]
	v_mfma_f32_16x16x32_bf16 v[32:35], v[144:147], v[152:155], v[32:35]
	v_mfma_f32_16x16x32_bf16 v[36:39], v[144:147], v[156:159], v[36:39]
	s_add_u32 m0, s30, 0x1a000
	v_lshl_add_u64 v[126:127], v[66:67], 0, s[24:25]
	global_load_lds_dwordx4 v[126:127], off
	v_mfma_f32_16x16x32_bf16 v[40:43], v[144:147], v[160:163], v[40:43]
	v_mfma_f32_16x16x32_bf16 v[44:47], v[144:147], v[164:167], v[44:47]
	v_mfma_f32_16x16x32_bf16 v[48:51], v[148:151], v[152:155], v[48:51]
	v_mfma_f32_16x16x32_bf16 v[52:55], v[148:151], v[156:159], v[52:55]
	v_mfma_f32_16x16x32_bf16 v[56:59], v[148:151], v[160:163], v[56:59]
	s_add_u32 m0, s30, 0x1c000
	v_lshl_add_u64 v[124:125], v[68:69], 0, s[24:25]
	global_load_lds_dwordx4 v[124:125], off
	v_mfma_f32_16x16x32_bf16 v[60:63], v[148:151], v[164:167], v[60:63]
	ds_read_b128 v[136:139], v77
	ds_read_b128 v[140:143], v77 offset:2048
	ds_read_b128 v[144:147], v77 offset:4096
	ds_read_b128 v[148:151], v77 offset:6144
	ds_read_b128 v[152:155], v79
	ds_read_b128 v[156:159], v79 offset:2048
	ds_read_b128 v[160:163], v79 offset:4096
	ds_read_b128 v[164:167], v79 offset:6144
	s_waitcnt lgkmcnt(8)
;     ...
;   for (int kt = 0; kt < nk; ++kt) {
;     if (kt + 1 < nk) asm volatile("s_waitcnt vmcnt(6)" ::: "memory");
;     else asm volatile("s_waitcnt vmcnt(0)" ::: "memory");
;     __builtin_amdgcn_s_barrier();
;     asm volatile("" ::: "memory");
;     if (kt + 2 < nk) { const int st2 = (st >= 1) ? st - 1 : 2; GEMM_ISSUE(kt + 2, st2); }
;     const char* la = lds + st * STAGE_B;
;     const char* lb = la + 32768;
;     const unsigned sa_u = (unsigned)(size_t)la + arow_u, sb_u = (unsigned)(size_t)lb + brow_u;
;     const unsigned a0 = sa_u + co0, a1 = sa_u + co1, a2 = sa_u + co2, a3 = sa_u + co3;
;     const unsigned b0 = sb_u + co0, b1 = sb_u + co1, b2 = sb_u + co2, b3 = sb_u + co3;
;     {
;       bf16x8 p0, p1, q0, q1, u0, u1, w0, w1;
;       asm volatile(
;         "ds_read_b128 %4, %12\n\tds_read_b128 %5, %12 offset:4096\n\tds_read_b128 %6, %16\n\tds_read_b128 %7, %16 offset:4096\n\t"
;         "ds_read_b128 %8, %13\n\tds_read_b128 %9, %13 offset:4096\n\tds_read_b128 %10, %17\n\tds_read_b128 %11, %17 offset:4096\n\t"
;         "s_waitcnt lgkmcnt(4)\n\t"
;         "v_mfma_f32_32x32x16_bf16 %0, %4, %6, %0\n\tv_mfma_f32_32x32x16_bf16 %1, %4, %7, %1\n\tv_mfma_f32_32x32x16_bf16 %2, %5, %6, %2\n\tv_mfma_f32_32x32x16_bf16 %3, %5, %7, %3\n\t"
;         "ds_read_b128 %4, %14\n\tds_read_b128 %5, %14 offset:4096\n\tds_read_b128 %6, %18\n\tds_read_b128 %7, %18 offset:4096\n\t"
;         "s_waitcnt lgkmcnt(4)\n\t"
;         "v_mfma_f32_32x32x16_bf16 %0, %8, %10, %0\n\tv_mfma_f32_32x32x16_bf16 %1, %8, %11, %1\n\tv_mfma_f32_32x32x16_bf16 %2, %9, %10, %2\n\tv_mfma_f32_32x32x16_bf16 %3, %9, %11, %3\n\t"
;         "ds_read_b128 %8, %15\n\tds_read_b128 %9, %15 offset:4096\n\tds_read_b128 %10, %19\n\tds_read_b128 %11, %19 offset:4096\n\t"
;         "s_waitcnt lgkmcnt(4)\n\t"
;         "v_mfma_f32_32x32x16_bf16 %0, %4, %6, %0\n\tv_mfma_f32_32x32x16_bf16 %1, %4, %7, %1\n\tv_mfma_f32_32x32x16_bf16 %2, %5, %6, %2\n\tv_mfma_f32_32x32x16_bf16 %3, %5, %7, %3\n\t"
;         "s_waitcnt lgkmcnt(0)\n\t"
;         "v_mfma_f32_32x32x16_bf16 %0, %8, %10, %0\n\tv_mfma_f32_32x32x16_bf16 %1, %8, %11, %1\n\tv_mfma_f32_32x32x16_bf16 %2, %9, %10, %2\n\tv_mfma_f32_32x32x16_bf16 %3, %9, %11, %3"
;         : "+v"(acc[0][0]), "+v"(acc[0][1]), "+v"(acc[1][0]), "+v"(acc[1][1]),
;           "=&v"(p0), "=&v"(p1), "=&v"(q0), "=&v"(q1), "=&v"(u0), "=&v"(u1), "=&v"(w0), "=&v"(w1)
	v_mfma_f32_16x16x32_bf16 v[0:3], v[84:87], v[100:103], v[0:3]
	v_mfma_f32_16x16x32_bf16 v[4:7], v[84:87], v[104:107], v[4:7]
	v_mfma_f32_16x16x32_bf16 v[8:11], v[84:87], v[108:111], v[8:11]
	v_mfma_f32_16x16x32_bf16 v[12:15], v[84:87], v[112:115], v[12:15]
	v_mfma_f32_16x16x32_bf16 v[16:19], v[88:91], v[100:103], v[16:19]
	s_add_u32 m0, s30, 0x1e000
	v_lshl_add_u64 v[126:127], v[70:71], 0, s[24:25]
	global_load_lds_dwordx4 v[126:127], off
	v_mfma_f32_16x16x32_bf16 v[20:23], v[88:91], v[104:107], v[20:23]
	v_mfma_f32_16x16x32_bf16 v[24:27], v[88:91], v[108:111], v[24:27]
	v_mfma_f32_16x16x32_bf16 v[28:31], v[88:91], v[112:115], v[28:31]
	v_mfma_f32_16x16x32_bf16 v[32:35], v[92:95], v[100:103], v[32:35]
	v_mfma_f32_16x16x32_bf16 v[36:39], v[92:95], v[104:107], v[36:39]
	s_add_u32 s24, s58, 0x0
	s_addc_u32 s25, s59, 0
	s_add_u32 m0, s30, 0x20000
	v_lshl_add_u64 v[124:125], v[72:73], 0, s[24:25]
	global_load_lds_dwordx4 v[124:125], off
	v_mfma_f32_16x16x32_bf16 v[40:43], v[92:95], v[108:111], v[40:43]
	v_mfma_f32_16x16x32_bf16 v[44:47], v[92:95], v[112:115], v[44:47]
	v_mfma_f32_16x16x32_bf16 v[48:51], v[96:99], v[100:103], v[48:51]
	v_mfma_f32_16x16x32_bf16 v[52:55], v[96:99], v[104:107], v[52:55]
	v_mfma_f32_16x16x32_bf16 v[56:59], v[96:99], v[108:111], v[56:59]
	s_add_u32 m0, s30, 0x22000
	v_lshl_add_u64 v[126:127], v[74:75], 0, s[24:25]
	global_load_lds_dwordx4 v[126:127], off
	v_mfma_f32_16x16x32_bf16 v[60:63], v[96:99], v[112:115], v[60:63]
	s_waitcnt vmcnt(6) lgkmcnt(0)
	s_barrier
	ds_read_b128 v[84:87], v76 offset:49152
	ds_read_b128 v[88:91], v76 offset:51200
	ds_read_b128 v[92:95], v76 offset:53248
	ds_read_b128 v[96:99], v76 offset:55296
	ds_read_b128 v[100:103], v78 offset:49152
	ds_read_b128 v[104:107], v78 offset:51200
	ds_read_b128 v[108:111], v78 offset:53248
	ds_read_b128 v[112:115], v78 offset:55296
	v_mfma_f32_16x16x32_bf16 v[0:3], v[136:139], v[152:155], v[0:3]
	v_mfma_f32_16x16x32_bf16 v[4:7], v[136:139], v[156:159], v[4:7]
	v_mfma_f32_16x16x32_bf16 v[8:11], v[136:139], v[160:163], v[8:11]
	v_mfma_f32_16x16x32_bf16 v[12:15], v[136:139], v[164:167], v[12:15]
	v_mfma_f32_16x16x32_bf16 v[16:19], v[140:143], v[152:155], v[16:19]
	s_add_u32 s24, s56, 0x80
	s_addc_u32 s25, s57, 0
	s_mov_b32 m0, s30
	v_lshl_add_u64 v[124:125], v[64:65], 0, s[24:25]
	global_load_lds_dwordx4 v[124:125], off
	v_mfma_f32_16x16x32_bf16 v[20:23], v[140:143], v[156:159], v[20:23]
	v_mfma_f32_16x16x32_bf16 v[24:27], v[140:143], v[160:163], v[24:27]
	v_mfma_f32_16x16x32_bf16 v[28:31], v[140:143], v[164:167], v[28:31]
	v_mfma_f32_16x16x32_bf16 v[32:35], v[144:147], v[152:155], v[32:35]
	v_mfma_f32_16x16x32_bf16 v[36:39], v[144:147], v[156:159], v[36:39]
	s_add_u32 m0, s30, 0x2000
	v_lshl_add_u64 v[126:127], v[66:67], 0, s[24:25]
	global_load_lds_dwordx4 v[126:127], off
	v_mfma_f32_16x16x32_bf16 v[40:43], v[144:147], v[160:163], v[40:43]
	v_mfma_f32_16x16x32_bf16 v[44:47], v[144:147], v[164:167], v[44:47]
	v_mfma_f32_16x16x32_bf16 v[48:51], v[148:151], v[152:155], v[48:51]
	v_mfma_f32_16x16x32_bf16 v[52:55], v[148:151], v[156:159], v[52:55]
	v_mfma_f32_16x16x32_bf16 v[56:59], v[148:151], v[160:163], v[56:59]
	s_add_u32 m0, s30, 0x4000
	v_lshl_add_u64 v[124:125], v[68:69], 0, s[24:25]
	global_load_lds_dwordx4 v[124:125], off
	v_mfma_f32_16x16x32_bf16 v[60:63], v[148:151], v[164:167], v[60:63]
	ds_read_b128 v[136:139], v77 offset:49152
	ds_read_b128 v[140:143], v77 offset:51200
	ds_read_b128 v[144:147], v77 offset:53248
	ds_read_b128 v[148:151], v77 offset:55296
	ds_read_b128 v[152:155], v79 offset:49152
	ds_read_b128 v[156:159], v79 offset:51200
	ds_read_b128 v[160:163], v79 offset:53248
	ds_read_b128 v[164:167], v79 offset:55296
	s_waitcnt lgkmcnt(8)
	v_mfma_f32_16x16x32_bf16 v[0:3], v[84:87], v[100:103], v[0:3]
	v_mfma_f32_16x16x32_bf16 v[4:7], v[84:87], v[104:107], v[4:7]
	v_mfma_f32_16x16x32_bf16 v[8:11], v[84:87], v[108:111], v[8:11]
	v_mfma_f32_16x16x32_bf16 v[12:15], v[84:87], v[112:115], v[12:15]
	v_mfma_f32_16x16x32_bf16 v[16:19], v[88:91], v[100:103], v[16:19]
	s_add_u32 m0, s30, 0x6000
	v_lshl_add_u64 v[126:127], v[70:71], 0, s[24:25]
	global_load_lds_dwordx4 v[126:127], off
	v_mfma_f32_16x16x32_bf16 v[20:23], v[88:91], v[104:107], v[20:23]
	v_mfma_f32_16x16x32_bf16 v[24:27], v[88:91], v[108:111], v[24:27]
	v_mfma_f32_16x16x32_bf16 v[28:31], v[88:91], v[112:115], v[28:31]
	v_mfma_f32_16x16x32_bf16 v[32:35], v[92:95], v[100:103], v[32:35]
	v_mfma_f32_16x16x32_bf16 v[36:39], v[92:95], v[104:107], v[36:39]
	s_add_u32 s24, s58, 0x80
	s_addc_u32 s25, s59, 0
	s_add_u32 m0, s30, 0x8000
	v_lshl_add_u64 v[124:125], v[72:73], 0, s[24:25]
	global_load_lds_dwordx4 v[124:125], off
	v_mfma_f32_16x16x32_bf16 v[40:43], v[92:95], v[108:111], v[40:43]
	v_mfma_f32_16x16x32_bf16 v[44:47], v[92:95], v[112:115], v[44:47]
	v_mfma_f32_16x16x32_bf16 v[48:51], v[96:99], v[100:103], v[48:51]
	v_mfma_f32_16x16x32_bf16 v[52:55], v[96:99], v[104:107], v[52:55]
	v_mfma_f32_16x16x32_bf16 v[56:59], v[96:99], v[108:111], v[56:59]
	s_add_u32 m0, s30, 0xa000
	v_lshl_add_u64 v[126:127], v[74:75], 0, s[24:25]
	global_load_lds_dwordx4 v[126:127], off
	v_mfma_f32_16x16x32_bf16 v[60:63], v[96:99], v[112:115], v[60:63]
	s_waitcnt lgkmcnt(0)
	v_mfma_f32_16x16x32_bf16 v[0:3], v[136:139], v[152:155], v[0:3]
	v_mfma_f32_16x16x32_bf16 v[4:7], v[136:139], v[156:159], v[4:7]
	v_mfma_f32_16x16x32_bf16 v[8:11], v[136:139], v[160:163], v[8:11]
	v_mfma_f32_16x16x32_bf16 v[12:15], v[136:139], v[164:167], v[12:15]
	v_mfma_f32_16x16x32_bf16 v[16:19], v[140:143], v[152:155], v[16:19]
	v_mfma_f32_16x16x32_bf16 v[20:23], v[140:143], v[156:159], v[20:23]
	v_mfma_f32_16x16x32_bf16 v[24:27], v[140:143], v[160:163], v[24:27]
	v_mfma_f32_16x16x32_bf16 v[28:31], v[140:143], v[164:167], v[28:31]
	v_mfma_f32_16x16x32_bf16 v[32:35], v[144:147], v[152:155], v[32:35]
	v_mfma_f32_16x16x32_bf16 v[36:39], v[144:147], v[156:159], v[36:39]
	v_mfma_f32_16x16x32_bf16 v[40:43], v[144:147], v[160:163], v[40:43]
	v_mfma_f32_16x16x32_bf16 v[44:47], v[144:147], v[164:167], v[44:47]
	v_mfma_f32_16x16x32_bf16 v[48:51], v[148:151], v[152:155], v[48:51]
	v_mfma_f32_16x16x32_bf16 v[52:55], v[148:151], v[156:159], v[52:55]
	v_mfma_f32_16x16x32_bf16 v[56:59], v[148:151], v[160:163], v[56:59]
	v_mfma_f32_16x16x32_bf16 v[60:63], v[148:151], v[164:167], v[60:63]
	s_branch .Ly11_done
;     ...
;   if (PART != 2) {
;     GEMM_ISSUE(0, 0);
;     if (nk > 1) GEMM_ISSUE(1, 1);
;   }
;   if (PART == 1) return;
;   int st = 0;
;   for (int kt = 0; kt < nk; ++kt) {
;     if (kt + 1 < nk) asm volatile("s_waitcnt vmcnt(6)" ::: "memory");
;     else asm volatile("s_waitcnt vmcnt(0)" ::: "memory");
;     __builtin_amdgcn_s_barrier();
;     asm volatile("" ::: "memory");
;     if (kt + 2 < nk) { const int st2 = (st >= 1) ? st - 1 : 2; GEMM_ISSUE(kt + 2, st2); }
;     const char* la = lds + st * STAGE_B;
;     const char* lb = la + 32768;
;     const unsigned sa_u = (unsigned)(size_t)la + arow_u, sb_u = (unsigned)(size_t)lb + brow_u;
;     const unsigned a0 = sa_u + co0, a1 = sa_u + co1, a2 = sa_u + co2, a3 = sa_u + co3;
;     const unsigned b0 = sb_u + co0, b1 = sb_u + co1, b2 = sb_u + co2, b3 = sb_u + co3;
;     {
;       bf16x8 p0, p1, q0, q1, u0, u1, w0, w1;
;       asm volatile(
;         "ds_read_b128 %4, %12\n\tds_read_b128 %5, %12 offset:4096\n\tds_read_b128 %6, %16\n\tds_read_b128 %7, %16 offset:4096\n\t"
;         "ds_read_b128 %8, %13\n\tds_read_b128 %9, %13 offset:4096\n\tds_read_b128 %10, %17\n\tds_read_b128 %11, %17 offset:4096\n\t"
;         "s_waitcnt lgkmcnt(4)\n\t"
;         "v_mfma_f32_32x32x16_bf16 %0, %4, %6, %0\n\tv_mfma_f32_32x32x16_bf16 %1, %4, %7, %1\n\tv_mfma_f32_32x32x16_bf16 %2, %5, %6, %2\n\tv_mfma_f32_32x32x16_bf16 %3, %5, %7, %3\n\t"
;         "ds_read_b128 %4, %14\n\tds_read_b128 %5, %14 offset:4096\n\tds_read_b128 %6, %18\n\tds_read_b128 %7, %18 offset:4096\n\t"
;         "s_waitcnt lgkmcnt(4)\n\t"
;         "v_mfma_f32_32x32x16_bf16 %0, %8, %10, %0\n\tv_mfma_f32_32x32x16_bf16 %1, %8, %11, %1\n\tv_mfma_f32_32x32x16_bf16 %2, %9, %10, %2\n\tv_mfma_f32_32x32x16_bf16 %3, %9, %11, %3\n\t"
;         "ds_read_b128 %8, %15\n\tds_read_b128 %9, %15 offset:4096\n\tds_read_b128 %10, %19\n\tds_read_b128 %11, %19 offset:4096\n\t"
;         "s_waitcnt lgkmcnt(4)\n\t"
;         "v_mfma_f32_32x32x16_bf16 %0, %4, %6, %0\n\tv_mfma_f32_32x32x16_bf16 %1, %4, %7, %1\n\tv_mfma_f32_32x32x16_bf16 %2, %5, %6, %2\n\tv_mfma_f32_32x32x16_bf16 %3, %5, %7, %3\n\t"
;         "s_waitcnt lgkmcnt(0)\n\t"
;         "v_mfma_f32_32x32x16_bf16 %0, %8, %10, %0\n\tv_mfma_f32_32x32x16_bf16 %1, %8, %11, %1\n\tv_mfma_f32_32x32x16_bf16 %2, %9, %10, %2\n\tv_mfma_f32_32x32x16_bf16 %3, %9, %11, %3"
.Ly11_v2:
	ds_read_b128 v[84:87], v80
	ds_read_b128 v[88:91], v80 offset:2048
	ds_read_b128 v[92:95], v80 offset:4096
	ds_read_b128 v[96:99], v80 offset:6144
	ds_read_b128 v[100:103], v82
	ds_read_b128 v[104:107], v82 offset:2048
	ds_read_b128 v[108:111], v82 offset:4096
	ds_read_b128 v[112:115], v82 offset:6144
	s_mov_b32 s24, 0x100
	s_mov_b32 s25, 0
	s_add_u32 m0, s30, 0xc000
	v_lshl_add_u64 v[124:125], v[64:65], 0, s[24:25]
	global_load_lds_dwordx4 v[124:125], off
	s_add_u32 m0, s30, 0xe000
	v_lshl_add_u64 v[126:127], v[66:67], 0, s[24:25]
	global_load_lds_dwordx4 v[126:127], off
	s_add_u32 m0, s30, 0x10000
	v_lshl_add_u64 v[124:125], v[68:69], 0, s[24:25]
	global_load_lds_dwordx4 v[124:125], off
	ds_read_b128 v[136:139], v81
	ds_read_b128 v[140:143], v81 offset:2048
	ds_read_b128 v[144:147], v81 offset:4096
	ds_read_b128 v[148:151], v81 offset:6144
	ds_read_b128 v[152:155], v83
	ds_read_b128 v[156:159], v83 offset:2048
	ds_read_b128 v[160:163], v83 offset:4096
	ds_read_b128 v[164:167], v83 offset:6144
	s_waitcnt lgkmcnt(8)
	v_mfma_f32_16x16x32_bf16 v[0:3], v[84:87], v[100:103], v[0:3]
	v_mfma_f32_16x16x32_bf16 v[4:7], v[84:87], v[104:107], v[4:7]
	v_mfma_f32_16x16x32_bf16 v[8:11], v[84:87], v[108:111], v[8:11]
	v_mfma_f32_16x16x32_bf16 v[12:15], v[84:87], v[112:115], v[12:15]
	v_mfma_f32_16x16x32_bf16 v[16:19], v[88:91], v[100:103], v[16:19]
	s_add_u32 m0, s30, 0x12000
	v_lshl_add_u64 v[126:127], v[70:71], 0, s[24:25]
	global_load_lds_dwordx4 v[126:127], off
	v_mfma_f32_16x16x32_bf16 v[20:23], v[88:91], v[104:107], v[20:23]
	v_mfma_f32_16x16x32_bf16 v[24:27], v[88:91], v[108:111], v[24:27]
	v_mfma_f32_16x16x32_bf16 v[28:31], v[88:91], v[112:115], v[28:31]
	v_mfma_f32_16x16x32_bf16 v[32:35], v[92:95], v[100:103], v[32:35]
	v_mfma_f32_16x16x32_bf16 v[36:39], v[92:95], v[104:107], v[36:39]
	s_add_u32 m0, s30, 0x14000
	v_lshl_add_u64 v[124:125], v[72:73], 0, s[24:25]
	global_load_lds_dwordx4 v[124:125], off
	v_mfma_f32_16x16x32_bf16 v[40:43], v[92:95], v[108:111], v[40:43]
	v_mfma_f32_16x16x32_bf16 v[44:47], v[92:95], v[112:115], v[44:47]
	v_mfma_f32_16x16x32_bf16 v[48:51], v[96:99], v[100:103], v[48:51]
	v_mfma_f32_16x16x32_bf16 v[52:55], v[96:99], v[104:107], v[52:55]
	v_mfma_f32_16x16x32_bf16 v[56:59], v[96:99], v[108:111], v[56:59]
	s_add_u32 m0, s30, 0x16000
	v_lshl_add_u64 v[126:127], v[74:75], 0, s[24:25]
	global_load_lds_dwordx4 v[126:127], off
	v_mfma_f32_16x16x32_bf16 v[60:63], v[96:99], v[112:115], v[60:63]
	s_waitcnt vmcnt(6) lgkmcnt(0)
	s_barrier
	ds_read_b128 v[84:87], v76
	ds_read_b128 v[88:91], v76 offset:2048
	ds_read_b128 v[92:95], v76 offset:4096
	ds_read_b128 v[96:99], v76 offset:6144
	ds_read_b128 v[100:103], v78
	ds_read_b128 v[104:107], v78 offset:2048
	ds_read_b128 v[108:111], v78 offset:4096
	ds_read_b128 v[112:115], v78 offset:6144
	v_mfma_f32_16x16x32_bf16 v[0:3], v[136:139], v[152:155], v[0:3]
	v_mfma_f32_16x16x32_bf16 v[4:7], v[136:139], v[156:159], v[4:7]
	v_mfma_f32_16x16x32_bf16 v[8:11], v[136:139], v[160:163], v[8:11]
	v_mfma_f32_16x16x32_bf16 v[12:15], v[136:139], v[164:167], v[12:15]
	v_mfma_f32_16x16x32_bf16 v[16:19], v[140:143], v[152:155], v[16:19]
	s_mov_b32 s24, 0x180
	s_mov_b32 s25, 0
	s_add_u32 m0, s30, 0x18000
	v_lshl_add_u64 v[124:125], v[64:65], 0, s[24:25]
	global_load_lds_dwordx4 v[124:125], off
	v_mfma_f32_16x16x32_bf16 v[20:23], v[140:143], v[156:159], v[20:23]
	v_mfma_f32_16x16x32_bf16 v[24:27], v[140:143], v[160:163], v[24:27]
	v_mfma_f32_16x16x32_bf16 v[28:31], v[140:143], v[164:167], v[28:31]
	v_mfma_f32_16x16x32_bf16 v[32:35], v[144:147], v[152:155], v[32:35]
	v_mfma_f32_16x16x32_bf16 v[36:39], v[144:147], v[156:159], v[36:39]
	s_add_u32 m0, s30, 0x1a000
	v_lshl_add_u64 v[126:127], v[66:67], 0, s[24:25]
	global_load_lds_dwordx4 v[126:127], off
	v_mfma_f32_16x16x32_bf16 v[40:43], v[144:147], v[160:163], v[40:43]
	v_mfma_f32_16x16x32_bf16 v[44:47], v[144:147], v[164:167], v[44:47]
	v_mfma_f32_16x16x32_bf16 v[48:51], v[148:151], v[152:155], v[48:51]
	v_mfma_f32_16x16x32_bf16 v[52:55], v[148:151], v[156:159], v[52:55]
	v_mfma_f32_16x16x32_bf16 v[56:59], v[148:151], v[160:163], v[56:59]
	s_add_u32 m0, s30, 0x1c000
	v_lshl_add_u64 v[124:125], v[68:69], 0, s[24:25]
	global_load_lds_dwordx4 v[124:125], off
	v_mfma_f32_16x16x32_bf16 v[60:63], v[148:151], v[164:167], v[60:63]
	ds_read_b128 v[136:139], v77
	ds_read_b128 v[140:143], v77 offset:2048
	ds_read_b128 v[144:147], v77 offset:4096
	ds_read_b128 v[148:151], v77 offset:6144
	ds_read_b128 v[152:155], v79
	ds_read_b128 v[156:159], v79 offset:2048
	ds_read_b128 v[160:163], v79 offset:4096
	ds_read_b128 v[164:167], v79 offset:6144
	s_waitcnt lgkmcnt(8)
	v_mfma_f32_16x16x32_bf16 v[0:3], v[84:87], v[100:103], v[0:3]
	v_mfma_f32_16x16x32_bf16 v[4:7], v[84:87], v[104:107], v[4:7]
	v_mfma_f32_16x16x32_bf16 v[8:11], v[84:87], v[108:111], v[8:11]
	v_mfma_f32_16x16x32_bf16 v[12:15], v[84:87], v[112:115], v[12:15]
	v_mfma_f32_16x16x32_bf16 v[16:19], v[88:91], v[100:103], v[16:19]
	s_add_u32 m0, s30, 0x1e000
	v_lshl_add_u64 v[126:127], v[70:71], 0, s[24:25]
	global_load_lds_dwordx4 v[126:127], off
	v_mfma_f32_16x16x32_bf16 v[20:23], v[88:91], v[104:107], v[20:23]
	v_mfma_f32_16x16x32_bf16 v[24:27], v[88:91], v[108:111], v[24:27]
	v_mfma_f32_16x16x32_bf16 v[28:31], v[88:91], v[112:115], v[28:31]
	v_mfma_f32_16x16x32_bf16 v[32:35], v[92:95], v[100:103], v[32:35]
	v_mfma_f32_16x16x32_bf16 v[36:39], v[92:95], v[104:107], v[36:39]
	s_add_u32 m0, s30, 0x20000
	v_lshl_add_u64 v[124:125], v[72:73], 0, s[24:25]
	global_load_lds_dwordx4 v[124:125], off
	v_mfma_f32_16x16x32_bf16 v[40:43], v[92:95], v[108:111], v[40:43]
	v_mfma_f32_16x16x32_bf16 v[44:47], v[92:95], v[112:115], v[44:47]
	v_mfma_f32_16x16x32_bf16 v[48:51], v[96:99], v[100:103], v[48:51]
	v_mfma_f32_16x16x32_bf16 v[52:55], v[96:99], v[104:107], v[52:55]
	v_mfma_f32_16x16x32_bf16 v[56:59], v[96:99], v[108:111], v[56:59]
	s_add_u32 m0, s30, 0x22000
	v_lshl_add_u64 v[126:127], v[74:75], 0, s[24:25]
	global_load_lds_dwordx4 v[126:127], off
	v_mfma_f32_16x16x32_bf16 v[60:63], v[96:99], v[112:115], v[60:63]
	s_waitcnt vmcnt(6) lgkmcnt(0)
	s_barrier
;     ...
;   for (int kt = 0; kt < nk; ++kt) {
;     if (kt + 1 < nk) asm volatile("s_waitcnt vmcnt(6)" ::: "memory");
;     else asm volatile("s_waitcnt vmcnt(0)" ::: "memory");
;     __builtin_amdgcn_s_barrier();
;     asm volatile("" ::: "memory");
;     if (kt + 2 < nk) { const int st2 = (st >= 1) ? st - 1 : 2; GEMM_ISSUE(kt + 2, st2); }
;     const char* la = lds + st * STAGE_B;
;     const char* lb = la + 32768;
;     const unsigned sa_u = (unsigned)(size_t)la + arow_u, sb_u = (unsigned)(size_t)lb + brow_u;
;     const unsigned a0 = sa_u + co0, a1 = sa_u + co1, a2 = sa_u + co2, a3 = sa_u + co3;
;     const unsigned b0 = sb_u + co0, b1 = sb_u + co1, b2 = sb_u + co2, b3 = sb_u + co3;
;     {
;       bf16x8 p0, p1, q0, q1, u0, u1, w0, w1;
;       asm volatile(
;         "ds_read_b128 %4, %12\n\tds_read_b128 %5, %12 offset:4096\n\tds_read_b128 %6, %16\n\tds_read_b128 %7, %16 offset:4096\n\t"
;         "ds_read_b128 %8, %13\n\tds_read_b128 %9, %13 offset:4096\n\tds_read_b128 %10, %17\n\tds_read_b128 %11, %17 offset:4096\n\t"
;         "s_waitcnt lgkmcnt(4)\n\t"
;         "v_mfma_f32_32x32x16_bf16 %0, %4, %6, %0\n\tv_mfma_f32_32x32x16_bf16 %1, %4, %7, %1\n\tv_mfma_f32_32x32x16_bf16 %2, %5, %6, %2\n\tv_mfma_f32_32x32x16_bf16 %3, %5, %7, %3\n\t"
;         "ds_read_b128 %4, %14\n\tds_read_b128 %5, %14 offset:4096\n\tds_read_b128 %6, %18\n\tds_read_b128 %7, %18 offset:4096\n\t"
;         "s_waitcnt lgkmcnt(4)\n\t"
;         "v_mfma_f32_32x32x16_bf16 %0, %8, %10, %0\n\tv_mfma_f32_32x32x16_bf16 %1, %8, %11, %1\n\tv_mfma_f32_32x32x16_bf16 %2, %9, %10, %2\n\tv_mfma_f32_32x32x16_bf16 %3, %9, %11, %3\n\t"
;         "ds_read_b128 %8, %15\n\tds_read_b128 %9, %15 offset:4096\n\tds_read_b128 %10, %19\n\tds_read_b128 %11, %19 offset:4096\n\t"
;         "s_waitcnt lgkmcnt(4)\n\t"
;         "v_mfma_f32_32x32x16_bf16 %0, %4, %6, %0\n\tv_mfma_f32_32x32x16_bf16 %1, %4, %7, %1\n\tv_mfma_f32_32x32x16_bf16 %2, %5, %6, %2\n\tv_mfma_f32_32x32x16_bf16 %3, %5, %7, %3\n\t"
;         "s_waitcnt lgkmcnt(0)\n\t"
;         "v_mfma_f32_32x32x16_bf16 %0, %8, %10, %0\n\tv_mfma_f32_32x32x16_bf16 %1, %8, %11, %1\n\tv_mfma_f32_32x32x16_bf16 %2, %9, %10, %2\n\tv_mfma_f32_32x32x16_bf16 %3, %9, %11, %3"
;         : "+v"(acc[0][0]), "+v"(acc[0][1]), "+v"(acc[1][0]), "+v"(acc[1][1]),
;           "=&v"(p0), "=&v"(p1), "=&v"(q0), "=&v"(q1), "=&v"(u0), "=&v"(u1), "=&v"(w0), "=&v"(w1)
	ds_read_b128 v[84:87], v76 offset:49152
	ds_read_b128 v[88:91], v76 offset:51200
	ds_read_b128 v[92:95], v76 offset:53248
	ds_read_b128 v[96:99], v76 offset:55296
	ds_read_b128 v[100:103], v78 offset:49152
	ds_read_b128 v[104:107], v78 offset:51200
	ds_read_b128 v[108:111], v78 offset:53248
	ds_read_b128 v[112:115], v78 offset:55296
	v_mfma_f32_16x16x32_bf16 v[0:3], v[136:139], v[152:155], v[0:3]
	v_mfma_f32_16x16x32_bf16 v[4:7], v[136:139], v[156:159], v[4:7]
	v_mfma_f32_16x16x32_bf16 v[8:11], v[136:139], v[160:163], v[8:11]
	v_mfma_f32_16x16x32_bf16 v[12:15], v[136:139], v[164:167], v[12:15]
	v_mfma_f32_16x16x32_bf16 v[16:19], v[140:143], v[152:155], v[16:19]
	s_mov_b32 s24, 0x200
	s_mov_b32 s25, 0
	s_mov_b32 m0, s30
	v_lshl_add_u64 v[124:125], v[64:65], 0, s[24:25]
	global_load_lds_dwordx4 v[124:125], off
	v_mfma_f32_16x16x32_bf16 v[20:23], v[140:143], v[156:159], v[20:23]
	v_mfma_f32_16x16x32_bf16 v[24:27], v[140:143], v[160:163], v[24:27]
	v_mfma_f32_16x16x32_bf16 v[28:31], v[140:143], v[164:167], v[28:31]
	v_mfma_f32_16x16x32_bf16 v[32:35], v[144:147], v[152:155], v[32:35]
	v_mfma_f32_16x16x32_bf16 v[36:39], v[144:147], v[156:159], v[36:39]
	s_add_u32 m0, s30, 0x2000
	v_lshl_add_u64 v[126:127], v[66:67], 0, s[24:25]
	global_load_lds_dwordx4 v[126:127], off
	v_mfma_f32_16x16x32_bf16 v[40:43], v[144:147], v[160:163], v[40:43]
	v_mfma_f32_16x16x32_bf16 v[44:47], v[144:147], v[164:167], v[44:47]
	v_mfma_f32_16x16x32_bf16 v[48:51], v[148:151], v[152:155], v[48:51]
	v_mfma_f32_16x16x32_bf16 v[52:55], v[148:151], v[156:159], v[52:55]
	v_mfma_f32_16x16x32_bf16 v[56:59], v[148:151], v[160:163], v[56:59]
	s_add_u32 m0, s30, 0x4000
	v_lshl_add_u64 v[124:125], v[68:69], 0, s[24:25]
	global_load_lds_dwordx4 v[124:125], off
	v_mfma_f32_16x16x32_bf16 v[60:63], v[148:151], v[164:167], v[60:63]
	ds_read_b128 v[136:139], v77 offset:49152
	ds_read_b128 v[140:143], v77 offset:51200
	ds_read_b128 v[144:147], v77 offset:53248
	ds_read_b128 v[148:151], v77 offset:55296
	ds_read_b128 v[152:155], v79 offset:49152
	ds_read_b128 v[156:159], v79 offset:51200
	ds_read_b128 v[160:163], v79 offset:53248
	ds_read_b128 v[164:167], v79 offset:55296
	s_waitcnt lgkmcnt(8)
	v_mfma_f32_16x16x32_bf16 v[0:3], v[84:87], v[100:103], v[0:3]
	v_mfma_f32_16x16x32_bf16 v[4:7], v[84:87], v[104:107], v[4:7]
	v_mfma_f32_16x16x32_bf16 v[8:11], v[84:87], v[108:111], v[8:11]
	v_mfma_f32_16x16x32_bf16 v[12:15], v[84:87], v[112:115], v[12:15]
	v_mfma_f32_16x16x32_bf16 v[16:19], v[88:91], v[100:103], v[16:19]
	s_add_u32 m0, s30, 0x6000
	v_lshl_add_u64 v[126:127], v[70:71], 0, s[24:25]
	global_load_lds_dwordx4 v[126:127], off
	v_mfma_f32_16x16x32_bf16 v[20:23], v[88:91], v[104:107], v[20:23]
	v_mfma_f32_16x16x32_bf16 v[24:27], v[88:91], v[108:111], v[24:27]
	v_mfma_f32_16x16x32_bf16 v[28:31], v[88:91], v[112:115], v[28:31]
	v_mfma_f32_16x16x32_bf16 v[32:35], v[92:95], v[100:103], v[32:35]
	v_mfma_f32_16x16x32_bf16 v[36:39], v[92:95], v[104:107], v[36:39]
	s_add_u32 m0, s30, 0x8000
	v_lshl_add_u64 v[124:125], v[72:73], 0, s[24:25]
	global_load_lds_dwordx4 v[124:125], off
	v_mfma_f32_16x16x32_bf16 v[40:43], v[92:95], v[108:111], v[40:43]
	v_mfma_f32_16x16x32_bf16 v[44:47], v[92:95], v[112:115], v[44:47]
	v_mfma_f32_16x16x32_bf16 v[48:51], v[96:99], v[100:103], v[48:51]
	v_mfma_f32_16x16x32_bf16 v[52:55], v[96:99], v[104:107], v[52:55]
	v_mfma_f32_16x16x32_bf16 v[56:59], v[96:99], v[108:111], v[56:59]
	s_add_u32 m0, s30, 0xa000
	v_lshl_add_u64 v[126:127], v[74:75], 0, s[24:25]
	global_load_lds_dwordx4 v[126:127], off
	v_mfma_f32_16x16x32_bf16 v[60:63], v[96:99], v[112:115], v[60:63]
	s_waitcnt vmcnt(6) lgkmcnt(0)
	s_barrier
	ds_read_b128 v[84:87], v80
	ds_read_b128 v[88:91], v80 offset:2048
	ds_read_b128 v[92:95], v80 offset:4096
	ds_read_b128 v[96:99], v80 offset:6144
	ds_read_b128 v[100:103], v82
	ds_read_b128 v[104:107], v82 offset:2048
	ds_read_b128 v[108:111], v82 offset:4096
	ds_read_b128 v[112:115], v82 offset:6144
	v_mfma_f32_16x16x32_bf16 v[0:3], v[136:139], v[152:155], v[0:3]
	v_mfma_f32_16x16x32_bf16 v[4:7], v[136:139], v[156:159], v[4:7]
	v_mfma_f32_16x16x32_bf16 v[8:11], v[136:139], v[160:163], v[8:11]
	v_mfma_f32_16x16x32_bf16 v[12:15], v[136:139], v[164:167], v[12:15]
	v_mfma_f32_16x16x32_bf16 v[16:19], v[140:143], v[152:155], v[16:19]
	s_mov_b32 s24, 0x280
	s_mov_b32 s25, 0
	s_add_u32 m0, s30, 0xc000
	v_lshl_add_u64 v[124:125], v[64:65], 0, s[24:25]
	global_load_lds_dwordx4 v[124:125], off
	v_mfma_f32_16x16x32_bf16 v[20:23], v[140:143], v[156:159], v[20:23]
	v_mfma_f32_16x16x32_bf16 v[24:27], v[140:143], v[160:163], v[24:27]
	v_mfma_f32_16x16x32_bf16 v[28:31], v[140:143], v[164:167], v[28:31]
	v_mfma_f32_16x16x32_bf16 v[32:35], v[144:147], v[152:155], v[32:35]
	v_mfma_f32_16x16x32_bf16 v[36:39], v[144:147], v[156:159], v[36:39]
	s_add_u32 m0, s30, 0xe000
	v_lshl_add_u64 v[126:127], v[66:67], 0, s[24:25]
	global_load_lds_dwordx4 v[126:127], off
	v_mfma_f32_16x16x32_bf16 v[40:43], v[144:147], v[160:163], v[40:43]
	v_mfma_f32_16x16x32_bf16 v[44:47], v[144:147], v[164:167], v[44:47]
	v_mfma_f32_16x16x32_bf16 v[48:51], v[148:151], v[152:155], v[48:51]
	v_mfma_f32_16x16x32_bf16 v[52:55], v[148:151], v[156:159], v[52:55]
	v_mfma_f32_16x16x32_bf16 v[56:59], v[148:151], v[160:163], v[56:59]
	s_add_u32 m0, s30, 0x10000
	v_lshl_add_u64 v[124:125], v[68:69], 0, s[24:25]
	global_load_lds_dwordx4 v[124:125], off
	v_mfma_f32_16x16x32_bf16 v[60:63], v[148:151], v[164:167], v[60:63]
	ds_read_b128 v[136:139], v81
	ds_read_b128 v[140:143], v81 offset:2048
	ds_read_b128 v[144:147], v81 offset:4096
	ds_read_b128 v[148:151], v81 offset:6144
	ds_read_b128 v[152:155], v83
	ds_read_b128 v[156:159], v83 offset:2048
	ds_read_b128 v[160:163], v83 offset:4096
	ds_read_b128 v[164:167], v83 offset:6144
	s_waitcnt lgkmcnt(8)
;     ...
;   for (int kt = 0; kt < nk; ++kt) {
;     if (kt + 1 < nk) asm volatile("s_waitcnt vmcnt(6)" ::: "memory");
;     else asm volatile("s_waitcnt vmcnt(0)" ::: "memory");
;     __builtin_amdgcn_s_barrier();
;     asm volatile("" ::: "memory");
;     if (kt + 2 < nk) { const int st2 = (st >= 1) ? st - 1 : 2; GEMM_ISSUE(kt + 2, st2); }
;     const char* la = lds + st * STAGE_B;
;     const char* lb = la + 32768;
;     const unsigned sa_u = (unsigned)(size_t)la + arow_u, sb_u = (unsigned)(size_t)lb + brow_u;
;     const unsigned a0 = sa_u + co0, a1 = sa_u + co1, a2 = sa_u + co2, a3 = sa_u + co3;
;     const unsigned b0 = sb_u + co0, b1 = sb_u + co1, b2 = sb_u + co2, b3 = sb_u + co3;
;     {
;       bf16x8 p0, p1, q0, q1, u0, u1, w0, w1;
;       asm volatile(
;         "ds_read_b128 %4, %12\n\tds_read_b128 %5, %12 offset:4096\n\tds_read_b128 %6, %16\n\tds_read_b128 %7, %16 offset:4096\n\t"
;         "ds_read_b128 %8, %13\n\tds_read_b128 %9, %13 offset:4096\n\tds_read_b128 %10, %17\n\tds_read_b128 %11, %17 offset:4096\n\t"
;         "s_waitcnt lgkmcnt(4)\n\t"
;         "v_mfma_f32_32x32x16_bf16 %0, %4, %6, %0\n\tv_mfma_f32_32x32x16_bf16 %1, %4, %7, %1\n\tv_mfma_f32_32x32x16_bf16 %2, %5, %6, %2\n\tv_mfma_f32_32x32x16_bf16 %3, %5, %7, %3\n\t"
;         "ds_read_b128 %4, %14\n\tds_read_b128 %5, %14 offset:4096\n\tds_read_b128 %6, %18\n\tds_read_b128 %7, %18 offset:4096\n\t"
;         "s_waitcnt lgkmcnt(4)\n\t"
;         "v_mfma_f32_32x32x16_bf16 %0, %8, %10, %0\n\tv_mfma_f32_32x32x16_bf16 %1, %8, %11, %1\n\tv_mfma_f32_32x32x16_bf16 %2, %9, %10, %2\n\tv_mfma_f32_32x32x16_bf16 %3, %9, %11, %3\n\t"
;         "ds_read_b128 %8, %15\n\tds_read_b128 %9, %15 offset:4096\n\tds_read_b128 %10, %19\n\tds_read_b128 %11, %19 offset:4096\n\t"
;         "s_waitcnt lgkmcnt(4)\n\t"
;         "v_mfma_f32_32x32x16_bf16 %0, %4, %6, %0\n\tv_mfma_f32_32x32x16_bf16 %1, %4, %7, %1\n\tv_mfma_f32_32x32x16_bf16 %2, %5, %6, %2\n\tv_mfma_f32_32x32x16_bf16 %3, %5, %7, %3\n\t"
;         "s_waitcnt lgkmcnt(0)\n\t"
;         "v_mfma_f32_32x32x16_bf16 %0, %8, %10, %0\n\tv_mfma_f32_32x32x16_bf16 %1, %8, %11, %1\n\tv_mfma_f32_32x32x16_bf16 %2, %9, %10, %2\n\tv_mfma_f32_32x32x16_bf16 %3, %9, %11, %3"
;         : "+v"(acc[0][0]), "+v"(acc[0][1]), "+v"(acc[1][0]), "+v"(acc[1][1]),
;           "=&v"(p0), "=&v"(p1), "=&v"(q0), "=&v"(q1), "=&v"(u0), "=&v"(u1), "=&v"(w0), "=&v"(w1)
	v_mfma_f32_16x16x32_bf16 v[0:3], v[84:87], v[100:103], v[0:3]
	v_mfma_f32_16x16x32_bf16 v[4:7], v[84:87], v[104:107], v[4:7]
	v_mfma_f32_16x16x32_bf16 v[8:11], v[84:87], v[108:111], v[8:11]
	v_mfma_f32_16x16x32_bf16 v[12:15], v[84:87], v[112:115], v[12:15]
	v_mfma_f32_16x16x32_bf16 v[16:19], v[88:91], v[100:103], v[16:19]
	s_add_u32 m0, s30, 0x12000
	v_lshl_add_u64 v[126:127], v[70:71], 0, s[24:25]
	global_load_lds_dwordx4 v[126:127], off
	v_mfma_f32_16x16x32_bf16 v[20:23], v[88:91], v[104:107], v[20:23]
	v_mfma_f32_16x16x32_bf16 v[24:27], v[88:91], v[108:111], v[24:27]
	v_mfma_f32_16x16x32_bf16 v[28:31], v[88:91], v[112:115], v[28:31]
	v_mfma_f32_16x16x32_bf16 v[32:35], v[92:95], v[100:103], v[32:35]
	v_mfma_f32_16x16x32_bf16 v[36:39], v[92:95], v[104:107], v[36:39]
	s_add_u32 m0, s30, 0x14000
	v_lshl_add_u64 v[124:125], v[72:73], 0, s[24:25]
	global_load_lds_dwordx4 v[124:125], off
	v_mfma_f32_16x16x32_bf16 v[40:43], v[92:95], v[108:111], v[40:43]
	v_mfma_f32_16x16x32_bf16 v[44:47], v[92:95], v[112:115], v[44:47]
	v_mfma_f32_16x16x32_bf16 v[48:51], v[96:99], v[100:103], v[48:51]
	v_mfma_f32_16x16x32_bf16 v[52:55], v[96:99], v[104:107], v[52:55]
	v_mfma_f32_16x16x32_bf16 v[56:59], v[96:99], v[108:111], v[56:59]
	s_add_u32 m0, s30, 0x16000
	v_lshl_add_u64 v[126:127], v[74:75], 0, s[24:25]
	global_load_lds_dwordx4 v[126:127], off
	v_mfma_f32_16x16x32_bf16 v[60:63], v[96:99], v[112:115], v[60:63]
	s_waitcnt vmcnt(6) lgkmcnt(0)
	s_barrier
	ds_read_b128 v[84:87], v76
	ds_read_b128 v[88:91], v76 offset:2048
	ds_read_b128 v[92:95], v76 offset:4096
	ds_read_b128 v[96:99], v76 offset:6144
	ds_read_b128 v[100:103], v78
	ds_read_b128 v[104:107], v78 offset:2048
	ds_read_b128 v[108:111], v78 offset:4096
	ds_read_b128 v[112:115], v78 offset:6144
	v_mfma_f32_16x16x32_bf16 v[0:3], v[136:139], v[152:155], v[0:3]
	v_mfma_f32_16x16x32_bf16 v[4:7], v[136:139], v[156:159], v[4:7]
	v_mfma_f32_16x16x32_bf16 v[8:11], v[136:139], v[160:163], v[8:11]
	v_mfma_f32_16x16x32_bf16 v[12:15], v[136:139], v[164:167], v[12:15]
	v_mfma_f32_16x16x32_bf16 v[16:19], v[140:143], v[152:155], v[16:19]
	s_mov_b32 s24, 0x300
	s_mov_b32 s25, 0
	s_add_u32 m0, s30, 0x18000
	v_lshl_add_u64 v[124:125], v[64:65], 0, s[24:25]
	global_load_lds_dwordx4 v[124:125], off
	v_mfma_f32_16x16x32_bf16 v[20:23], v[140:143], v[156:159], v[20:23]
	v_mfma_f32_16x16x32_bf16 v[24:27], v[140:143], v[160:163], v[24:27]
	v_mfma_f32_16x16x32_bf16 v[28:31], v[140:143], v[164:167], v[28:31]
	v_mfma_f32_16x16x32_bf16 v[32:35], v[144:147], v[152:155], v[32:35]
	v_mfma_f32_16x16x32_bf16 v[36:39], v[144:147], v[156:159], v[36:39]
	s_add_u32 m0, s30, 0x1a000
	v_lshl_add_u64 v[126:127], v[66:67], 0, s[24:25]
	global_load_lds_dwordx4 v[126:127], off
	v_mfma_f32_16x16x32_bf16 v[40:43], v[144:147], v[160:163], v[40:43]
	v_mfma_f32_16x16x32_bf16 v[44:47], v[144:147], v[164:167], v[44:47]
	v_mfma_f32_16x16x32_bf16 v[48:51], v[148:151], v[152:155], v[48:51]
	v_mfma_f32_16x16x32_bf16 v[52:55], v[148:151], v[156:159], v[52:55]
	v_mfma_f32_16x16x32_bf16 v[56:59], v[148:151], v[160:163], v[56:59]
	s_add_u32 m0, s30, 0x1c000
	v_lshl_add_u64 v[124:125], v[68:69], 0, s[24:25]
	global_load_lds_dwordx4 v[124:125], off
	v_mfma_f32_16x16x32_bf16 v[60:63], v[148:151], v[164:167], v[60:63]
	ds_read_b128 v[136:139], v77
	ds_read_b128 v[140:143], v77 offset:2048
	ds_read_b128 v[144:147], v77 offset:4096
	ds_read_b128 v[148:151], v77 offset:6144
	ds_read_b128 v[152:155], v79
	ds_read_b128 v[156:159], v79 offset:2048
	ds_read_b128 v[160:163], v79 offset:4096
	ds_read_b128 v[164:167], v79 offset:6144
	s_waitcnt lgkmcnt(8)
	v_mfma_f32_16x16x32_bf16 v[0:3], v[84:87], v[100:103], v[0:3]
	v_mfma_f32_16x16x32_bf16 v[4:7], v[84:87], v[104:107], v[4:7]
	v_mfma_f32_16x16x32_bf16 v[8:11], v[84:87], v[108:111], v[8:11]
	v_mfma_f32_16x16x32_bf16 v[12:15], v[84:87], v[112:115], v[12:15]
	v_mfma_f32_16x16x32_bf16 v[16:19], v[88:91], v[100:103], v[16:19]
	s_add_u32 m0, s30, 0x1e000
	v_lshl_add_u64 v[126:127], v[70:71], 0, s[24:25]
	global_load_lds_dwordx4 v[126:127], off
	v_mfma_f32_16x16x32_bf16 v[20:23], v[88:91], v[104:107], v[20:23]
	v_mfma_f32_16x16x32_bf16 v[24:27], v[88:91], v[108:111], v[24:27]
	v_mfma_f32_16x16x32_bf16 v[28:31], v[88:91], v[112:115], v[28:31]
	v_mfma_f32_16x16x32_bf16 v[32:35], v[92:95], v[100:103], v[32:35]
	v_mfma_f32_16x16x32_bf16 v[36:39], v[92:95], v[104:107], v[36:39]
	s_add_u32 m0, s30, 0x20000
	v_lshl_add_u64 v[124:125], v[72:73], 0, s[24:25]
	global_load_lds_dwordx4 v[124:125], off
	v_mfma_f32_16x16x32_bf16 v[40:43], v[92:95], v[108:111], v[40:43]
	v_mfma_f32_16x16x32_bf16 v[44:47], v[92:95], v[112:115], v[44:47]
	v_mfma_f32_16x16x32_bf16 v[48:51], v[96:99], v[100:103], v[48:51]
	v_mfma_f32_16x16x32_bf16 v[52:55], v[96:99], v[104:107], v[52:55]
	v_mfma_f32_16x16x32_bf16 v[56:59], v[96:99], v[108:111], v[56:59]
	s_add_u32 m0, s30, 0x22000
	v_lshl_add_u64 v[126:127], v[74:75], 0, s[24:25]
	global_load_lds_dwordx4 v[126:127], off
	v_mfma_f32_16x16x32_bf16 v[60:63], v[96:99], v[112:115], v[60:63]
	s_waitcnt vmcnt(6) lgkmcnt(0)
	s_barrier
;     ...
;   for (int kt = 0; kt < nk; ++kt) {
;     if (kt + 1 < nk) asm volatile("s_waitcnt vmcnt(6)" ::: "memory");
;     else asm volatile("s_waitcnt vmcnt(0)" ::: "memory");
;     __builtin_amdgcn_s_barrier();
;     asm volatile("" ::: "memory");
;     if (kt + 2 < nk) { const int st2 = (st >= 1) ? st - 1 : 2; GEMM_ISSUE(kt + 2, st2); }
;     const char* la = lds + st * STAGE_B;
;     const char* lb = la + 32768;
;     const unsigned sa_u = (unsigned)(size_t)la + arow_u, sb_u = (unsigned)(size_t)lb + brow_u;
;     const unsigned a0 = sa_u + co0, a1 = sa_u + co1, a2 = sa_u + co2, a3 = sa_u + co3;
;     const unsigned b0 = sb_u + co0, b1 = sb_u + co1, b2 = sb_u + co2, b3 = sb_u + co3;
;     {
;       bf16x8 p0, p1, q0, q1, u0, u1, w0, w1;
;       asm volatile(
;         "ds_read_b128 %4, %12\n\tds_read_b128 %5, %12 offset:4096\n\tds_read_b128 %6, %16\n\tds_read_b128 %7, %16 offset:4096\n\t"
;         "ds_read_b128 %8, %13\n\tds_read_b128 %9, %13 offset:4096\n\tds_read_b128 %10, %17\n\tds_read_b128 %11, %17 offset:4096\n\t"
;         "s_waitcnt lgkmcnt(4)\n\t"
;         "v_mfma_f32_32x32x16_bf16 %0, %4, %6, %0\n\tv_mfma_f32_32x32x16_bf16 %1, %4, %7, %1\n\tv_mfma_f32_32x32x16_bf16 %2, %5, %6, %2\n\tv_mfma_f32_32x32x16_bf16 %3, %5, %7, %3\n\t"
;         "ds_read_b128 %4, %14\n\tds_read_b128 %5, %14 offset:4096\n\tds_read_b128 %6, %18\n\tds_read_b128 %7, %18 offset:4096\n\t"
;         "s_waitcnt lgkmcnt(4)\n\t"
;         "v_mfma_f32_32x32x16_bf16 %0, %8, %10, %0\n\tv_mfma_f32_32x32x16_bf16 %1, %8, %11, %1\n\tv_mfma_f32_32x32x16_bf16 %2, %9, %10, %2\n\tv_mfma_f32_32x32x16_bf16 %3, %9, %11, %3\n\t"
;         "ds_read_b128 %8, %15\n\tds_read_b128 %9, %15 offset:4096\n\tds_read_b128 %10, %19\n\tds_read_b128 %11, %19 offset:4096\n\t"
;         "s_waitcnt lgkmcnt(4)\n\t"
;         "v_mfma_f32_32x32x16_bf16 %0, %4, %6, %0\n\tv_mfma_f32_32x32x16_bf16 %1, %4, %7, %1\n\tv_mfma_f32_32x32x16_bf16 %2, %5, %6, %2\n\tv_mfma_f32_32x32x16_bf16 %3, %5, %7, %3\n\t"
;         "s_waitcnt lgkmcnt(0)\n\t"
;         "v_mfma_f32_32x32x16_bf16 %0, %8, %10, %0\n\tv_mfma_f32_32x32x16_bf16 %1, %8, %11, %1\n\tv_mfma_f32_32x32x16_bf16 %2, %9, %10, %2\n\tv_mfma_f32_32x32x16_bf16 %3, %9, %11, %3"
;         : "+v"(acc[0][0]), "+v"(acc[0][1]), "+v"(acc[1][0]), "+v"(acc[1][1]),
;           "=&v"(p0), "=&v"(p1), "=&v"(q0), "=&v"(q1), "=&v"(u0), "=&v"(u1), "=&v"(w0), "=&v"(w1)
	ds_read_b128 v[84:87], v76 offset:49152
	ds_read_b128 v[88:91], v76 offset:51200
	ds_read_b128 v[92:95], v76 offset:53248
	ds_read_b128 v[96:99], v76 offset:55296
	ds_read_b128 v[100:103], v78 offset:49152
	ds_read_b128 v[104:107], v78 offset:51200
	ds_read_b128 v[108:111], v78 offset:53248
	ds_read_b128 v[112:115], v78 offset:55296
	v_mfma_f32_16x16x32_bf16 v[0:3], v[136:139], v[152:155], v[0:3]
	v_mfma_f32_16x16x32_bf16 v[4:7], v[136:139], v[156:159], v[4:7]
	v_mfma_f32_16x16x32_bf16 v[8:11], v[136:139], v[160:163], v[8:11]
	v_mfma_f32_16x16x32_bf16 v[12:15], v[136:139], v[164:167], v[12:15]
	v_mfma_f32_16x16x32_bf16 v[16:19], v[140:143], v[152:155], v[16:19]
	s_mov_b32 s24, 0x380
	s_mov_b32 s25, 0
	s_mov_b32 m0, s30
	v_lshl_add_u64 v[124:125], v[64:65], 0, s[24:25]
	global_load_lds_dwordx4 v[124:125], off
	v_mfma_f32_16x16x32_bf16 v[20:23], v[140:143], v[156:159], v[20:23]
	v_mfma_f32_16x16x32_bf16 v[24:27], v[140:143], v[160:163], v[24:27]
	v_mfma_f32_16x16x32_bf16 v[28:31], v[140:143], v[164:167], v[28:31]
	v_mfma_f32_16x16x32_bf16 v[32:35], v[144:147], v[152:155], v[32:35]
	v_mfma_f32_16x16x32_bf16 v[36:39], v[144:147], v[156:159], v[36:39]
	s_add_u32 m0, s30, 0x2000
	v_lshl_add_u64 v[126:127], v[66:67], 0, s[24:25]
	global_load_lds_dwordx4 v[126:127], off
	v_mfma_f32_16x16x32_bf16 v[40:43], v[144:147], v[160:163], v[40:43]
	v_mfma_f32_16x16x32_bf16 v[44:47], v[144:147], v[164:167], v[44:47]
	v_mfma_f32_16x16x32_bf16 v[48:51], v[148:151], v[152:155], v[48:51]
	v_mfma_f32_16x16x32_bf16 v[52:55], v[148:151], v[156:159], v[52:55]
	v_mfma_f32_16x16x32_bf16 v[56:59], v[148:151], v[160:163], v[56:59]
	s_add_u32 m0, s30, 0x4000
	v_lshl_add_u64 v[124:125], v[68:69], 0, s[24:25]
	global_load_lds_dwordx4 v[124:125], off
	v_mfma_f32_16x16x32_bf16 v[60:63], v[148:151], v[164:167], v[60:63]
	ds_read_b128 v[136:139], v77 offset:49152
	ds_read_b128 v[140:143], v77 offset:51200
	ds_read_b128 v[144:147], v77 offset:53248
	ds_read_b128 v[148:151], v77 offset:55296
	ds_read_b128 v[152:155], v79 offset:49152
	ds_read_b128 v[156:159], v79 offset:51200
	ds_read_b128 v[160:163], v79 offset:53248
	ds_read_b128 v[164:167], v79 offset:55296
	s_waitcnt lgkmcnt(8)
	v_mfma_f32_16x16x32_bf16 v[0:3], v[84:87], v[100:103], v[0:3]
	v_mfma_f32_16x16x32_bf16 v[4:7], v[84:87], v[104:107], v[4:7]
	v_mfma_f32_16x16x32_bf16 v[8:11], v[84:87], v[108:111], v[8:11]
	v_mfma_f32_16x16x32_bf16 v[12:15], v[84:87], v[112:115], v[12:15]
	v_mfma_f32_16x16x32_bf16 v[16:19], v[88:91], v[100:103], v[16:19]
	s_add_u32 m0, s30, 0x6000
	v_lshl_add_u64 v[126:127], v[70:71], 0, s[24:25]
	global_load_lds_dwordx4 v[126:127], off
	v_mfma_f32_16x16x32_bf16 v[20:23], v[88:91], v[104:107], v[20:23]
	v_mfma_f32_16x16x32_bf16 v[24:27], v[88:91], v[108:111], v[24:27]
	v_mfma_f32_16x16x32_bf16 v[28:31], v[88:91], v[112:115], v[28:31]
	v_mfma_f32_16x16x32_bf16 v[32:35], v[92:95], v[100:103], v[32:35]
	v_mfma_f32_16x16x32_bf16 v[36:39], v[92:95], v[104:107], v[36:39]
	s_add_u32 m0, s30, 0x8000
	v_lshl_add_u64 v[124:125], v[72:73], 0, s[24:25]
	global_load_lds_dwordx4 v[124:125], off
	v_mfma_f32_16x16x32_bf16 v[40:43], v[92:95], v[108:111], v[40:43]
	v_mfma_f32_16x16x32_bf16 v[44:47], v[92:95], v[112:115], v[44:47]
	v_mfma_f32_16x16x32_bf16 v[48:51], v[96:99], v[100:103], v[48:51]
	v_mfma_f32_16x16x32_bf16 v[52:55], v[96:99], v[104:107], v[52:55]
	v_mfma_f32_16x16x32_bf16 v[56:59], v[96:99], v[108:111], v[56:59]
	s_add_u32 m0, s30, 0xa000
	v_lshl_add_u64 v[126:127], v[74:75], 0, s[24:25]
	global_load_lds_dwordx4 v[126:127], off
	v_mfma_f32_16x16x32_bf16 v[60:63], v[96:99], v[112:115], v[60:63]
	s_waitcnt vmcnt(6) lgkmcnt(0)
	s_barrier
	ds_read_b128 v[84:87], v80
	ds_read_b128 v[88:91], v80 offset:2048
	ds_read_b128 v[92:95], v80 offset:4096
	ds_read_b128 v[96:99], v80 offset:6144
	ds_read_b128 v[100:103], v82
	ds_read_b128 v[104:107], v82 offset:2048
	ds_read_b128 v[108:111], v82 offset:4096
	ds_read_b128 v[112:115], v82 offset:6144
	v_mfma_f32_16x16x32_bf16 v[0:3], v[136:139], v[152:155], v[0:3]
	v_mfma_f32_16x16x32_bf16 v[4:7], v[136:139], v[156:159], v[4:7]
	v_mfma_f32_16x16x32_bf16 v[8:11], v[136:139], v[160:163], v[8:11]
	v_mfma_f32_16x16x32_bf16 v[12:15], v[136:139], v[164:167], v[12:15]
	v_mfma_f32_16x16x32_bf16 v[16:19], v[140:143], v[152:155], v[16:19]
	s_mov_b32 s24, 0x400
	s_mov_b32 s25, 0
	s_add_u32 m0, s30, 0xc000
	v_lshl_add_u64 v[124:125], v[64:65], 0, s[24:25]
	global_load_lds_dwordx4 v[124:125], off
	v_mfma_f32_16x16x32_bf16 v[20:23], v[140:143], v[156:159], v[20:23]
	v_mfma_f32_16x16x32_bf16 v[24:27], v[140:143], v[160:163], v[24:27]
	v_mfma_f32_16x16x32_bf16 v[28:31], v[140:143], v[164:167], v[28:31]
	v_mfma_f32_16x16x32_bf16 v[32:35], v[144:147], v[152:155], v[32:35]
	v_mfma_f32_16x16x32_bf16 v[36:39], v[144:147], v[156:159], v[36:39]
	s_add_u32 m0, s30, 0xe000
	v_lshl_add_u64 v[126:127], v[66:67], 0, s[24:25]
	global_load_lds_dwordx4 v[126:127], off
	v_mfma_f32_16x16x32_bf16 v[40:43], v[144:147], v[160:163], v[40:43]
	v_mfma_f32_16x16x32_bf16 v[44:47], v[144:147], v[164:167], v[44:47]
	v_mfma_f32_16x16x32_bf16 v[48:51], v[148:151], v[152:155], v[48:51]
	v_mfma_f32_16x16x32_bf16 v[52:55], v[148:151], v[156:159], v[52:55]
	v_mfma_f32_16x16x32_bf16 v[56:59], v[148:151], v[160:163], v[56:59]
	s_add_u32 m0, s30, 0x10000
	v_lshl_add_u64 v[124:125], v[68:69], 0, s[24:25]
	global_load_lds_dwordx4 v[124:125], off
	v_mfma_f32_16x16x32_bf16 v[60:63], v[148:151], v[164:167], v[60:63]
	ds_read_b128 v[136:139], v81
	ds_read_b128 v[140:143], v81 offset:2048
	ds_read_b128 v[144:147], v81 offset:4096
	ds_read_b128 v[148:151], v81 offset:6144
	ds_read_b128 v[152:155], v83
	ds_read_b128 v[156:159], v83 offset:2048
	ds_read_b128 v[160:163], v83 offset:4096
	ds_read_b128 v[164:167], v83 offset:6144
	s_waitcnt lgkmcnt(8)
;     ...
;   for (int kt = 0; kt < nk; ++kt) {
;     if (kt + 1 < nk) asm volatile("s_waitcnt vmcnt(6)" ::: "memory");
;     else asm volatile("s_waitcnt vmcnt(0)" ::: "memory");
;     __builtin_amdgcn_s_barrier();
;     asm volatile("" ::: "memory");
;     if (kt + 2 < nk) { const int st2 = (st >= 1) ? st - 1 : 2; GEMM_ISSUE(kt + 2, st2); }
;     const char* la = lds + st * STAGE_B;
;     const char* lb = la + 32768;
;     const unsigned sa_u = (unsigned)(size_t)la + arow_u, sb_u = (unsigned)(size_t)lb + brow_u;
;     const unsigned a0 = sa_u + co0, a1 = sa_u + co1, a2 = sa_u + co2, a3 = sa_u + co3;
;     const unsigned b0 = sb_u + co0, b1 = sb_u + co1, b2 = sb_u + co2, b3 = sb_u + co3;
;     {
;       bf16x8 p0, p1, q0, q1, u0, u1, w0, w1;
;       asm volatile(
;         "ds_read_b128 %4, %12\n\tds_read_b128 %5, %12 offset:4096\n\tds_read_b128 %6, %16\n\tds_read_b128 %7, %16 offset:4096\n\t"
;         "ds_read_b128 %8, %13\n\tds_read_b128 %9, %13 offset:4096\n\tds_read_b128 %10, %17\n\tds_read_b128 %11, %17 offset:4096\n\t"
;         "s_waitcnt lgkmcnt(4)\n\t"
;         "v_mfma_f32_32x32x16_bf16 %0, %4, %6, %0\n\tv_mfma_f32_32x32x16_bf16 %1, %4, %7, %1\n\tv_mfma_f32_32x32x16_bf16 %2, %5, %6, %2\n\tv_mfma_f32_32x32x16_bf16 %3, %5, %7, %3\n\t"
;         "ds_read_b128 %4, %14\n\tds_read_b128 %5, %14 offset:4096\n\tds_read_b128 %6, %18\n\tds_read_b128 %7, %18 offset:4096\n\t"
;         "s_waitcnt lgkmcnt(4)\n\t"
;         "v_mfma_f32_32x32x16_bf16 %0, %8, %10, %0\n\tv_mfma_f32_32x32x16_bf16 %1, %8, %11, %1\n\tv_mfma_f32_32x32x16_bf16 %2, %9, %10, %2\n\tv_mfma_f32_32x32x16_bf16 %3, %9, %11, %3\n\t"
;         "ds_read_b128 %8, %15\n\tds_read_b128 %9, %15 offset:4096\n\tds_read_b128 %10, %19\n\tds_read_b128 %11, %19 offset:4096\n\t"
;         "s_waitcnt lgkmcnt(4)\n\t"
;         "v_mfma_f32_32x32x16_bf16 %0, %4, %6, %0\n\tv_mfma_f32_32x32x16_bf16 %1, %4, %7, %1\n\tv_mfma_f32_32x32x16_bf16 %2, %5, %6, %2\n\tv_mfma_f32_32x32x16_bf16 %3, %5, %7, %3\n\t"
;         "s_waitcnt lgkmcnt(0)\n\t"
;         "v_mfma_f32_32x32x16_bf16 %0, %8, %10, %0\n\tv_mfma_f32_32x32x16_bf16 %1, %8, %11, %1\n\tv_mfma_f32_32x32x16_bf16 %2, %9, %10, %2\n\tv_mfma_f32_32x32x16_bf16 %3, %9, %11, %3"
;         : "+v"(acc[0][0]), "+v"(acc[0][1]), "+v"(acc[1][0]), "+v"(acc[1][1]),
;           "=&v"(p0), "=&v"(p1), "=&v"(q0), "=&v"(q1), "=&v"(u0), "=&v"(u1), "=&v"(w0), "=&v"(w1)
	v_mfma_f32_16x16x32_bf16 v[0:3], v[84:87], v[100:103], v[0:3]
	v_mfma_f32_16x16x32_bf16 v[4:7], v[84:87], v[104:107], v[4:7]
	v_mfma_f32_16x16x32_bf16 v[8:11], v[84:87], v[108:111], v[8:11]
	v_mfma_f32_16x16x32_bf16 v[12:15], v[84:87], v[112:115], v[12:15]
	v_mfma_f32_16x16x32_bf16 v[16:19], v[88:91], v[100:103], v[16:19]
	s_add_u32 m0, s30, 0x12000
	v_lshl_add_u64 v[126:127], v[70:71], 0, s[24:25]
	global_load_lds_dwordx4 v[126:127], off
	v_mfma_f32_16x16x32_bf16 v[20:23], v[88:91], v[104:107], v[20:23]
	v_mfma_f32_16x16x32_bf16 v[24:27], v[88:91], v[108:111], v[24:27]
	v_mfma_f32_16x16x32_bf16 v[28:31], v[88:91], v[112:115], v[28:31]
	v_mfma_f32_16x16x32_bf16 v[32:35], v[92:95], v[100:103], v[32:35]
	v_mfma_f32_16x16x32_bf16 v[36:39], v[92:95], v[104:107], v[36:39]
	s_add_u32 m0, s30, 0x14000
	v_lshl_add_u64 v[124:125], v[72:73], 0, s[24:25]
	global_load_lds_dwordx4 v[124:125], off
	v_mfma_f32_16x16x32_bf16 v[40:43], v[92:95], v[108:111], v[40:43]
	v_mfma_f32_16x16x32_bf16 v[44:47], v[92:95], v[112:115], v[44:47]
	v_mfma_f32_16x16x32_bf16 v[48:51], v[96:99], v[100:103], v[48:51]
	v_mfma_f32_16x16x32_bf16 v[52:55], v[96:99], v[104:107], v[52:55]
	v_mfma_f32_16x16x32_bf16 v[56:59], v[96:99], v[108:111], v[56:59]
	s_add_u32 m0, s30, 0x16000
	v_lshl_add_u64 v[126:127], v[74:75], 0, s[24:25]
	global_load_lds_dwordx4 v[126:127], off
	v_mfma_f32_16x16x32_bf16 v[60:63], v[96:99], v[112:115], v[60:63]
	s_waitcnt vmcnt(6) lgkmcnt(0)
	s_barrier
	ds_read_b128 v[84:87], v76
	ds_read_b128 v[88:91], v76 offset:2048
	ds_read_b128 v[92:95], v76 offset:4096
	ds_read_b128 v[96:99], v76 offset:6144
	ds_read_b128 v[100:103], v78
	ds_read_b128 v[104:107], v78 offset:2048
	ds_read_b128 v[108:111], v78 offset:4096
	ds_read_b128 v[112:115], v78 offset:6144
	v_mfma_f32_16x16x32_bf16 v[0:3], v[136:139], v[152:155], v[0:3]
	v_mfma_f32_16x16x32_bf16 v[4:7], v[136:139], v[156:159], v[4:7]
	v_mfma_f32_16x16x32_bf16 v[8:11], v[136:139], v[160:163], v[8:11]
	v_mfma_f32_16x16x32_bf16 v[12:15], v[136:139], v[164:167], v[12:15]
	v_mfma_f32_16x16x32_bf16 v[16:19], v[140:143], v[152:155], v[16:19]
	s_mov_b32 s24, 0x480
	s_mov_b32 s25, 0
	s_add_u32 m0, s30, 0x18000
	v_lshl_add_u64 v[124:125], v[64:65], 0, s[24:25]
	global_load_lds_dwordx4 v[124:125], off
	v_mfma_f32_16x16x32_bf16 v[20:23], v[140:143], v[156:159], v[20:23]
	v_mfma_f32_16x16x32_bf16 v[24:27], v[140:143], v[160:163], v[24:27]
	v_mfma_f32_16x16x32_bf16 v[28:31], v[140:143], v[164:167], v[28:31]
	v_mfma_f32_16x16x32_bf16 v[32:35], v[144:147], v[152:155], v[32:35]
	v_mfma_f32_16x16x32_bf16 v[36:39], v[144:147], v[156:159], v[36:39]
	s_add_u32 m0, s30, 0x1a000
	v_lshl_add_u64 v[126:127], v[66:67], 0, s[24:25]
	global_load_lds_dwordx4 v[126:127], off
	v_mfma_f32_16x16x32_bf16 v[40:43], v[144:147], v[160:163], v[40:43]
	v_mfma_f32_16x16x32_bf16 v[44:47], v[144:147], v[164:167], v[44:47]
	v_mfma_f32_16x16x32_bf16 v[48:51], v[148:151], v[152:155], v[48:51]
	v_mfma_f32_16x16x32_bf16 v[52:55], v[148:151], v[156:159], v[52:55]
	v_mfma_f32_16x16x32_bf16 v[56:59], v[148:151], v[160:163], v[56:59]
	s_add_u32 m0, s30, 0x1c000
	v_lshl_add_u64 v[124:125], v[68:69], 0, s[24:25]
	global_load_lds_dwordx4 v[124:125], off
	v_mfma_f32_16x16x32_bf16 v[60:63], v[148:151], v[164:167], v[60:63]
	ds_read_b128 v[136:139], v77
	ds_read_b128 v[140:143], v77 offset:2048
	ds_read_b128 v[144:147], v77 offset:4096
	ds_read_b128 v[148:151], v77 offset:6144
	ds_read_b128 v[152:155], v79
	ds_read_b128 v[156:159], v79 offset:2048
	ds_read_b128 v[160:163], v79 offset:4096
	ds_read_b128 v[164:167], v79 offset:6144
	s_waitcnt lgkmcnt(8)
	v_mfma_f32_16x16x32_bf16 v[0:3], v[84:87], v[100:103], v[0:3]
	v_mfma_f32_16x16x32_bf16 v[4:7], v[84:87], v[104:107], v[4:7]
	v_mfma_f32_16x16x32_bf16 v[8:11], v[84:87], v[108:111], v[8:11]
	v_mfma_f32_16x16x32_bf16 v[12:15], v[84:87], v[112:115], v[12:15]
	v_mfma_f32_16x16x32_bf16 v[16:19], v[88:91], v[100:103], v[16:19]
	s_add_u32 m0, s30, 0x1e000
	v_lshl_add_u64 v[126:127], v[70:71], 0, s[24:25]
	global_load_lds_dwordx4 v[126:127], off
	v_mfma_f32_16x16x32_bf16 v[20:23], v[88:91], v[104:107], v[20:23]
	v_mfma_f32_16x16x32_bf16 v[24:27], v[88:91], v[108:111], v[24:27]
	v_mfma_f32_16x16x32_bf16 v[28:31], v[88:91], v[112:115], v[28:31]
	v_mfma_f32_16x16x32_bf16 v[32:35], v[92:95], v[100:103], v[32:35]
	v_mfma_f32_16x16x32_bf16 v[36:39], v[92:95], v[104:107], v[36:39]
	s_add_u32 m0, s30, 0x20000
	v_lshl_add_u64 v[124:125], v[72:73], 0, s[24:25]
	global_load_lds_dwordx4 v[124:125], off
	v_mfma_f32_16x16x32_bf16 v[40:43], v[92:95], v[108:111], v[40:43]
	v_mfma_f32_16x16x32_bf16 v[44:47], v[92:95], v[112:115], v[44:47]
	v_mfma_f32_16x16x32_bf16 v[48:51], v[96:99], v[100:103], v[48:51]
	v_mfma_f32_16x16x32_bf16 v[52:55], v[96:99], v[104:107], v[52:55]
	v_mfma_f32_16x16x32_bf16 v[56:59], v[96:99], v[108:111], v[56:59]
	s_add_u32 m0, s30, 0x22000
	v_lshl_add_u64 v[126:127], v[74:75], 0, s[24:25]
	global_load_lds_dwordx4 v[126:127], off
	v_mfma_f32_16x16x32_bf16 v[60:63], v[96:99], v[112:115], v[60:63]
	s_waitcnt vmcnt(6) lgkmcnt(0)
	s_barrier
;     ...
;   for (int kt = 0; kt < nk; ++kt) {
;     if (kt + 1 < nk) asm volatile("s_waitcnt vmcnt(6)" ::: "memory");
;     else asm volatile("s_waitcnt vmcnt(0)" ::: "memory");
;     __builtin_amdgcn_s_barrier();
;     asm volatile("" ::: "memory");
;     if (kt + 2 < nk) { const int st2 = (st >= 1) ? st - 1 : 2; GEMM_ISSUE(kt + 2, st2); }
;     const char* la = lds + st * STAGE_B;
;     const char* lb = la + 32768;
;     const unsigned sa_u = (unsigned)(size_t)la + arow_u, sb_u = (unsigned)(size_t)lb + brow_u;
;     const unsigned a0 = sa_u + co0, a1 = sa_u + co1, a2 = sa_u + co2, a3 = sa_u + co3;
;     const unsigned b0 = sb_u + co0, b1 = sb_u + co1, b2 = sb_u + co2, b3 = sb_u + co3;
;     {
;       bf16x8 p0, p1, q0, q1, u0, u1, w0, w1;
;       asm volatile(
;         "ds_read_b128 %4, %12\n\tds_read_b128 %5, %12 offset:4096\n\tds_read_b128 %6, %16\n\tds_read_b128 %7, %16 offset:4096\n\t"
;         "ds_read_b128 %8, %13\n\tds_read_b128 %9, %13 offset:4096\n\tds_read_b128 %10, %17\n\tds_read_b128 %11, %17 offset:4096\n\t"
;         "s_waitcnt lgkmcnt(4)\n\t"
;         "v_mfma_f32_32x32x16_bf16 %0, %4, %6, %0\n\tv_mfma_f32_32x32x16_bf16 %1, %4, %7, %1\n\tv_mfma_f32_32x32x16_bf16 %2, %5, %6, %2\n\tv_mfma_f32_32x32x16_bf16 %3, %5, %7, %3\n\t"
;         "ds_read_b128 %4, %14\n\tds_read_b128 %5, %14 offset:4096\n\tds_read_b128 %6, %18\n\tds_read_b128 %7, %18 offset:4096\n\t"
;         "s_waitcnt lgkmcnt(4)\n\t"
;         "v_mfma_f32_32x32x16_bf16 %0, %8, %10, %0\n\tv_mfma_f32_32x32x16_bf16 %1, %8, %11, %1\n\tv_mfma_f32_32x32x16_bf16 %2, %9, %10, %2\n\tv_mfma_f32_32x32x16_bf16 %3, %9, %11, %3\n\t"
;         "ds_read_b128 %8, %15\n\tds_read_b128 %9, %15 offset:4096\n\tds_read_b128 %10, %19\n\tds_read_b128 %11, %19 offset:4096\n\t"
;         "s_waitcnt lgkmcnt(4)\n\t"
;         "v_mfma_f32_32x32x16_bf16 %0, %4, %6, %0\n\tv_mfma_f32_32x32x16_bf16 %1, %4, %7, %1\n\tv_mfma_f32_32x32x16_bf16 %2, %5, %6, %2\n\tv_mfma_f32_32x32x16_bf16 %3, %5, %7, %3\n\t"
;         "s_waitcnt lgkmcnt(0)\n\t"
;         "v_mfma_f32_32x32x16_bf16 %0, %8, %10, %0\n\tv_mfma_f32_32x32x16_bf16 %1, %8, %11, %1\n\tv_mfma_f32_32x32x16_bf16 %2, %9, %10, %2\n\tv_mfma_f32_32x32x16_bf16 %3, %9, %11, %3"
;         : "+v"(acc[0][0]), "+v"(acc[0][1]), "+v"(acc[1][0]), "+v"(acc[1][1]),
;           "=&v"(p0), "=&v"(p1), "=&v"(q0), "=&v"(q1), "=&v"(u0), "=&v"(u1), "=&v"(w0), "=&v"(w1)
	ds_read_b128 v[84:87], v76 offset:49152
	ds_read_b128 v[88:91], v76 offset:51200
	ds_read_b128 v[92:95], v76 offset:53248
	ds_read_b128 v[96:99], v76 offset:55296
	ds_read_b128 v[100:103], v78 offset:49152
	ds_read_b128 v[104:107], v78 offset:51200
	ds_read_b128 v[108:111], v78 offset:53248
	ds_read_b128 v[112:115], v78 offset:55296
	v_mfma_f32_16x16x32_bf16 v[0:3], v[136:139], v[152:155], v[0:3]
	v_mfma_f32_16x16x32_bf16 v[4:7], v[136:139], v[156:159], v[4:7]
	v_mfma_f32_16x16x32_bf16 v[8:11], v[136:139], v[160:163], v[8:11]
	v_mfma_f32_16x16x32_bf16 v[12:15], v[136:139], v[164:167], v[12:15]
	v_mfma_f32_16x16x32_bf16 v[16:19], v[140:143], v[152:155], v[16:19]
	s_mov_b32 s24, 0x500
	s_mov_b32 s25, 0
	s_mov_b32 m0, s30
	v_lshl_add_u64 v[124:125], v[64:65], 0, s[24:25]
	global_load_lds_dwordx4 v[124:125], off
	v_mfma_f32_16x16x32_bf16 v[20:23], v[140:143], v[156:159], v[20:23]
	v_mfma_f32_16x16x32_bf16 v[24:27], v[140:143], v[160:163], v[24:27]
	v_mfma_f32_16x16x32_bf16 v[28:31], v[140:143], v[164:167], v[28:31]
	v_mfma_f32_16x16x32_bf16 v[32:35], v[144:147], v[152:155], v[32:35]
	v_mfma_f32_16x16x32_bf16 v[36:39], v[144:147], v[156:159], v[36:39]
	s_add_u32 m0, s30, 0x2000
	v_lshl_add_u64 v[126:127], v[66:67], 0, s[24:25]
	global_load_lds_dwordx4 v[126:127], off
	v_mfma_f32_16x16x32_bf16 v[40:43], v[144:147], v[160:163], v[40:43]
	v_mfma_f32_16x16x32_bf16 v[44:47], v[144:147], v[164:167], v[44:47]
	v_mfma_f32_16x16x32_bf16 v[48:51], v[148:151], v[152:155], v[48:51]
	v_mfma_f32_16x16x32_bf16 v[52:55], v[148:151], v[156:159], v[52:55]
	v_mfma_f32_16x16x32_bf16 v[56:59], v[148:151], v[160:163], v[56:59]
	s_add_u32 m0, s30, 0x4000
	v_lshl_add_u64 v[124:125], v[68:69], 0, s[24:25]
	global_load_lds_dwordx4 v[124:125], off
	v_mfma_f32_16x16x32_bf16 v[60:63], v[148:151], v[164:167], v[60:63]
	ds_read_b128 v[136:139], v77 offset:49152
	ds_read_b128 v[140:143], v77 offset:51200
	ds_read_b128 v[144:147], v77 offset:53248
	ds_read_b128 v[148:151], v77 offset:55296
	ds_read_b128 v[152:155], v79 offset:49152
	ds_read_b128 v[156:159], v79 offset:51200
	ds_read_b128 v[160:163], v79 offset:53248
	ds_read_b128 v[164:167], v79 offset:55296
	s_waitcnt lgkmcnt(8)
	v_mfma_f32_16x16x32_bf16 v[0:3], v[84:87], v[100:103], v[0:3]
	v_mfma_f32_16x16x32_bf16 v[4:7], v[84:87], v[104:107], v[4:7]
	v_mfma_f32_16x16x32_bf16 v[8:11], v[84:87], v[108:111], v[8:11]
	v_mfma_f32_16x16x32_bf16 v[12:15], v[84:87], v[112:115], v[12:15]
	v_mfma_f32_16x16x32_bf16 v[16:19], v[88:91], v[100:103], v[16:19]
	s_add_u32 m0, s30, 0x6000
	v_lshl_add_u64 v[126:127], v[70:71], 0, s[24:25]
	global_load_lds_dwordx4 v[126:127], off
	v_mfma_f32_16x16x32_bf16 v[20:23], v[88:91], v[104:107], v[20:23]
	v_mfma_f32_16x16x32_bf16 v[24:27], v[88:91], v[108:111], v[24:27]
	v_mfma_f32_16x16x32_bf16 v[28:31], v[88:91], v[112:115], v[28:31]
	v_mfma_f32_16x16x32_bf16 v[32:35], v[92:95], v[100:103], v[32:35]
	v_mfma_f32_16x16x32_bf16 v[36:39], v[92:95], v[104:107], v[36:39]
	s_add_u32 m0, s30, 0x8000
	v_lshl_add_u64 v[124:125], v[72:73], 0, s[24:25]
	global_load_lds_dwordx4 v[124:125], off
	v_mfma_f32_16x16x32_bf16 v[40:43], v[92:95], v[108:111], v[40:43]
	v_mfma_f32_16x16x32_bf16 v[44:47], v[92:95], v[112:115], v[44:47]
	v_mfma_f32_16x16x32_bf16 v[48:51], v[96:99], v[100:103], v[48:51]
	v_mfma_f32_16x16x32_bf16 v[52:55], v[96:99], v[104:107], v[52:55]
	v_mfma_f32_16x16x32_bf16 v[56:59], v[96:99], v[108:111], v[56:59]
	s_add_u32 m0, s30, 0xa000
	v_lshl_add_u64 v[126:127], v[74:75], 0, s[24:25]
	global_load_lds_dwordx4 v[126:127], off
	v_mfma_f32_16x16x32_bf16 v[60:63], v[96:99], v[112:115], v[60:63]
	s_waitcnt vmcnt(6) lgkmcnt(0)
	s_barrier
	ds_read_b128 v[84:87], v80
	ds_read_b128 v[88:91], v80 offset:2048
	ds_read_b128 v[92:95], v80 offset:4096
	ds_read_b128 v[96:99], v80 offset:6144
	ds_read_b128 v[100:103], v82
	ds_read_b128 v[104:107], v82 offset:2048
	ds_read_b128 v[108:111], v82 offset:4096
	ds_read_b128 v[112:115], v82 offset:6144
	v_mfma_f32_16x16x32_bf16 v[0:3], v[136:139], v[152:155], v[0:3]
	v_mfma_f32_16x16x32_bf16 v[4:7], v[136:139], v[156:159], v[4:7]
	v_mfma_f32_16x16x32_bf16 v[8:11], v[136:139], v[160:163], v[8:11]
	v_mfma_f32_16x16x32_bf16 v[12:15], v[136:139], v[164:167], v[12:15]
	v_mfma_f32_16x16x32_bf16 v[16:19], v[140:143], v[152:155], v[16:19]
	s_mov_b32 s24, 0x580
	s_mov_b32 s25, 0
	s_add_u32 m0, s30, 0xc000
	v_lshl_add_u64 v[124:125], v[64:65], 0, s[24:25]
	global_load_lds_dwordx4 v[124:125], off
	v_mfma_f32_16x16x32_bf16 v[20:23], v[140:143], v[156:159], v[20:23]
	v_mfma_f32_16x16x32_bf16 v[24:27], v[140:143], v[160:163], v[24:27]
	v_mfma_f32_16x16x32_bf16 v[28:31], v[140:143], v[164:167], v[28:31]
	v_mfma_f32_16x16x32_bf16 v[32:35], v[144:147], v[152:155], v[32:35]
	v_mfma_f32_16x16x32_bf16 v[36:39], v[144:147], v[156:159], v[36:39]
	s_add_u32 m0, s30, 0xe000
	v_lshl_add_u64 v[126:127], v[66:67], 0, s[24:25]
	global_load_lds_dwordx4 v[126:127], off
	v_mfma_f32_16x16x32_bf16 v[40:43], v[144:147], v[160:163], v[40:43]
	v_mfma_f32_16x16x32_bf16 v[44:47], v[144:147], v[164:167], v[44:47]
	v_mfma_f32_16x16x32_bf16 v[48:51], v[148:151], v[152:155], v[48:51]
	v_mfma_f32_16x16x32_bf16 v[52:55], v[148:151], v[156:159], v[52:55]
	v_mfma_f32_16x16x32_bf16 v[56:59], v[148:151], v[160:163], v[56:59]
	s_add_u32 m0, s30, 0x10000
	v_lshl_add_u64 v[124:125], v[68:69], 0, s[24:25]
	global_load_lds_dwordx4 v[124:125], off
	v_mfma_f32_16x16x32_bf16 v[60:63], v[148:151], v[164:167], v[60:63]
	ds_read_b128 v[136:139], v81
	ds_read_b128 v[140:143], v81 offset:2048
	ds_read_b128 v[144:147], v81 offset:4096
	ds_read_b128 v[148:151], v81 offset:6144
	ds_read_b128 v[152:155], v83
	ds_read_b128 v[156:159], v83 offset:2048
	ds_read_b128 v[160:163], v83 offset:4096
	ds_read_b128 v[164:167], v83 offset:6144
	s_waitcnt lgkmcnt(8)
;     ...
;   for (int kt = 0; kt < nk; ++kt) {
;     if (kt + 1 < nk) asm volatile("s_waitcnt vmcnt(6)" ::: "memory");
;     else asm volatile("s_waitcnt vmcnt(0)" ::: "memory");
;     __builtin_amdgcn_s_barrier();
;     asm volatile("" ::: "memory");
;     if (kt + 2 < nk) { const int st2 = (st >= 1) ? st - 1 : 2; GEMM_ISSUE(kt + 2, st2); }
;     const char* la = lds + st * STAGE_B;
;     const char* lb = la + 32768;
;     const unsigned sa_u = (unsigned)(size_t)la + arow_u, sb_u = (unsigned)(size_t)lb + brow_u;
;     const unsigned a0 = sa_u + co0, a1 = sa_u + co1, a2 = sa_u + co2, a3 = sa_u + co3;
;     const unsigned b0 = sb_u + co0, b1 = sb_u + co1, b2 = sb_u + co2, b3 = sb_u + co3;
;     {
;       bf16x8 p0, p1, q0, q1, u0, u1, w0, w1;
;       asm volatile(
;         "ds_read_b128 %4, %12\n\tds_read_b128 %5, %12 offset:4096\n\tds_read_b128 %6, %16\n\tds_read_b128 %7, %16 offset:4096\n\t"
;         "ds_read_b128 %8, %13\n\tds_read_b128 %9, %13 offset:4096\n\tds_read_b128 %10, %17\n\tds_read_b128 %11, %17 offset:4096\n\t"
;         "s_waitcnt lgkmcnt(4)\n\t"
;         "v_mfma_f32_32x32x16_bf16 %0, %4, %6, %0\n\tv_mfma_f32_32x32x16_bf16 %1, %4, %7, %1\n\tv_mfma_f32_32x32x16_bf16 %2, %5, %6, %2\n\tv_mfma_f32_32x32x16_bf16 %3, %5, %7, %3\n\t"
;         "ds_read_b128 %4, %14\n\tds_read_b128 %5, %14 offset:4096\n\tds_read_b128 %6, %18\n\tds_read_b128 %7, %18 offset:4096\n\t"
;         "s_waitcnt lgkmcnt(4)\n\t"
;         "v_mfma_f32_32x32x16_bf16 %0, %8, %10, %0\n\tv_mfma_f32_32x32x16_bf16 %1, %8, %11, %1\n\tv_mfma_f32_32x32x16_bf16 %2, %9, %10, %2\n\tv_mfma_f32_32x32x16_bf16 %3, %9, %11, %3\n\t"
;         "ds_read_b128 %8, %15\n\tds_read_b128 %9, %15 offset:4096\n\tds_read_b128 %10, %19\n\tds_read_b128 %11, %19 offset:4096\n\t"
;         "s_waitcnt lgkmcnt(4)\n\t"
;         "v_mfma_f32_32x32x16_bf16 %0, %4, %6, %0\n\tv_mfma_f32_32x32x16_bf16 %1, %4, %7, %1\n\tv_mfma_f32_32x32x16_bf16 %2, %5, %6, %2\n\tv_mfma_f32_32x32x16_bf16 %3, %5, %7, %3\n\t"
;         "s_waitcnt lgkmcnt(0)\n\t"
;         "v_mfma_f32_32x32x16_bf16 %0, %8, %10, %0\n\tv_mfma_f32_32x32x16_bf16 %1, %8, %11, %1\n\tv_mfma_f32_32x32x16_bf16 %2, %9, %10, %2\n\tv_mfma_f32_32x32x16_bf16 %3, %9, %11, %3"
;         : "+v"(acc[0][0]), "+v"(acc[0][1]), "+v"(acc[1][0]), "+v"(acc[1][1]),
;           "=&v"(p0), "=&v"(p1), "=&v"(q0), "=&v"(q1), "=&v"(u0), "=&v"(u1), "=&v"(w0), "=&v"(w1)
	v_mfma_f32_16x16x32_bf16 v[0:3], v[84:87], v[100:103], v[0:3]
	v_mfma_f32_16x16x32_bf16 v[4:7], v[84:87], v[104:107], v[4:7]
	v_mfma_f32_16x16x32_bf16 v[8:11], v[84:87], v[108:111], v[8:11]
	v_mfma_f32_16x16x32_bf16 v[12:15], v[84:87], v[112:115], v[12:15]
	v_mfma_f32_16x16x32_bf16 v[16:19], v[88:91], v[100:103], v[16:19]
	s_add_u32 m0, s30, 0x12000
	v_lshl_add_u64 v[126:127], v[70:71], 0, s[24:25]
	global_load_lds_dwordx4 v[126:127], off
	v_mfma_f32_16x16x32_bf16 v[20:23], v[88:91], v[104:107], v[20:23]
	v_mfma_f32_16x16x32_bf16 v[24:27], v[88:91], v[108:111], v[24:27]
	v_mfma_f32_16x16x32_bf16 v[28:31], v[88:91], v[112:115], v[28:31]
	v_mfma_f32_16x16x32_bf16 v[32:35], v[92:95], v[100:103], v[32:35]
	v_mfma_f32_16x16x32_bf16 v[36:39], v[92:95], v[104:107], v[36:39]
	s_add_u32 m0, s30, 0x14000
	v_lshl_add_u64 v[124:125], v[72:73], 0, s[24:25]
	global_load_lds_dwordx4 v[124:125], off
	v_mfma_f32_16x16x32_bf16 v[40:43], v[92:95], v[108:111], v[40:43]
	v_mfma_f32_16x16x32_bf16 v[44:47], v[92:95], v[112:115], v[44:47]
	v_mfma_f32_16x16x32_bf16 v[48:51], v[96:99], v[100:103], v[48:51]
	v_mfma_f32_16x16x32_bf16 v[52:55], v[96:99], v[104:107], v[52:55]
	v_mfma_f32_16x16x32_bf16 v[56:59], v[96:99], v[108:111], v[56:59]
	s_add_u32 m0, s30, 0x16000
	v_lshl_add_u64 v[126:127], v[74:75], 0, s[24:25]
	global_load_lds_dwordx4 v[126:127], off
	v_mfma_f32_16x16x32_bf16 v[60:63], v[96:99], v[112:115], v[60:63]
	s_waitcnt vmcnt(6) lgkmcnt(0)
	s_barrier
	ds_read_b128 v[84:87], v76
	ds_read_b128 v[88:91], v76 offset:2048
	ds_read_b128 v[92:95], v76 offset:4096
	ds_read_b128 v[96:99], v76 offset:6144
	ds_read_b128 v[100:103], v78
	ds_read_b128 v[104:107], v78 offset:2048
	ds_read_b128 v[108:111], v78 offset:4096
	ds_read_b128 v[112:115], v78 offset:6144
	v_mfma_f32_16x16x32_bf16 v[0:3], v[136:139], v[152:155], v[0:3]
	v_mfma_f32_16x16x32_bf16 v[4:7], v[136:139], v[156:159], v[4:7]
	v_mfma_f32_16x16x32_bf16 v[8:11], v[136:139], v[160:163], v[8:11]
	v_mfma_f32_16x16x32_bf16 v[12:15], v[136:139], v[164:167], v[12:15]
	v_mfma_f32_16x16x32_bf16 v[16:19], v[140:143], v[152:155], v[16:19]
	s_mov_b32 s24, 0x600
	s_mov_b32 s25, 0
	s_add_u32 m0, s30, 0x18000
	v_lshl_add_u64 v[124:125], v[64:65], 0, s[24:25]
	global_load_lds_dwordx4 v[124:125], off
	v_mfma_f32_16x16x32_bf16 v[20:23], v[140:143], v[156:159], v[20:23]
	v_mfma_f32_16x16x32_bf16 v[24:27], v[140:143], v[160:163], v[24:27]
	v_mfma_f32_16x16x32_bf16 v[28:31], v[140:143], v[164:167], v[28:31]
	v_mfma_f32_16x16x32_bf16 v[32:35], v[144:147], v[152:155], v[32:35]
	v_mfma_f32_16x16x32_bf16 v[36:39], v[144:147], v[156:159], v[36:39]
	s_add_u32 m0, s30, 0x1a000
	v_lshl_add_u64 v[126:127], v[66:67], 0, s[24:25]
	global_load_lds_dwordx4 v[126:127], off
	v_mfma_f32_16x16x32_bf16 v[40:43], v[144:147], v[160:163], v[40:43]
	v_mfma_f32_16x16x32_bf16 v[44:47], v[144:147], v[164:167], v[44:47]
	v_mfma_f32_16x16x32_bf16 v[48:51], v[148:151], v[152:155], v[48:51]
	v_mfma_f32_16x16x32_bf16 v[52:55], v[148:151], v[156:159], v[52:55]
	v_mfma_f32_16x16x32_bf16 v[56:59], v[148:151], v[160:163], v[56:59]
	s_add_u32 m0, s30, 0x1c000
	v_lshl_add_u64 v[124:125], v[68:69], 0, s[24:25]
	global_load_lds_dwordx4 v[124:125], off
	v_mfma_f32_16x16x32_bf16 v[60:63], v[148:151], v[164:167], v[60:63]
	ds_read_b128 v[136:139], v77
	ds_read_b128 v[140:143], v77 offset:2048
	ds_read_b128 v[144:147], v77 offset:4096
	ds_read_b128 v[148:151], v77 offset:6144
	ds_read_b128 v[152:155], v79
	ds_read_b128 v[156:159], v79 offset:2048
	ds_read_b128 v[160:163], v79 offset:4096
	ds_read_b128 v[164:167], v79 offset:6144
	s_waitcnt lgkmcnt(8)
	v_mfma_f32_16x16x32_bf16 v[0:3], v[84:87], v[100:103], v[0:3]
	v_mfma_f32_16x16x32_bf16 v[4:7], v[84:87], v[104:107], v[4:7]
	v_mfma_f32_16x16x32_bf16 v[8:11], v[84:87], v[108:111], v[8:11]
	v_mfma_f32_16x16x32_bf16 v[12:15], v[84:87], v[112:115], v[12:15]
	v_mfma_f32_16x16x32_bf16 v[16:19], v[88:91], v[100:103], v[16:19]
	s_add_u32 m0, s30, 0x1e000
	v_lshl_add_u64 v[126:127], v[70:71], 0, s[24:25]
	global_load_lds_dwordx4 v[126:127], off
	v_mfma_f32_16x16x32_bf16 v[20:23], v[88:91], v[104:107], v[20:23]
	v_mfma_f32_16x16x32_bf16 v[24:27], v[88:91], v[108:111], v[24:27]
	v_mfma_f32_16x16x32_bf16 v[28:31], v[88:91], v[112:115], v[28:31]
	v_mfma_f32_16x16x32_bf16 v[32:35], v[92:95], v[100:103], v[32:35]
	v_mfma_f32_16x16x32_bf16 v[36:39], v[92:95], v[104:107], v[36:39]
	s_add_u32 m0, s30, 0x20000
	v_lshl_add_u64 v[124:125], v[72:73], 0, s[24:25]
	global_load_lds_dwordx4 v[124:125], off
	v_mfma_f32_16x16x32_bf16 v[40:43], v[92:95], v[108:111], v[40:43]
	v_mfma_f32_16x16x32_bf16 v[44:47], v[92:95], v[112:115], v[44:47]
	v_mfma_f32_16x16x32_bf16 v[48:51], v[96:99], v[100:103], v[48:51]
	v_mfma_f32_16x16x32_bf16 v[52:55], v[96:99], v[104:107], v[52:55]
	v_mfma_f32_16x16x32_bf16 v[56:59], v[96:99], v[108:111], v[56:59]
	s_add_u32 m0, s30, 0x22000
	v_lshl_add_u64 v[126:127], v[74:75], 0, s[24:25]
	global_load_lds_dwordx4 v[126:127], off
	v_mfma_f32_16x16x32_bf16 v[60:63], v[96:99], v[112:115], v[60:63]
	s_waitcnt vmcnt(6) lgkmcnt(0)
	s_barrier
;     ...
;   for (int kt = 0; kt < nk; ++kt) {
;     if (kt + 1 < nk) asm volatile("s_waitcnt vmcnt(6)" ::: "memory");
;     else asm volatile("s_waitcnt vmcnt(0)" ::: "memory");
;     __builtin_amdgcn_s_barrier();
;     asm volatile("" ::: "memory");
;     if (kt + 2 < nk) { const int st2 = (st >= 1) ? st - 1 : 2; GEMM_ISSUE(kt + 2, st2); }
;     const char* la = lds + st * STAGE_B;
;     const char* lb = la + 32768;
;     const unsigned sa_u = (unsigned)(size_t)la + arow_u, sb_u = (unsigned)(size_t)lb + brow_u;
;     const unsigned a0 = sa_u + co0, a1 = sa_u + co1, a2 = sa_u + co2, a3 = sa_u + co3;
;     const unsigned b0 = sb_u + co0, b1 = sb_u + co1, b2 = sb_u + co2, b3 = sb_u + co3;
;     {
;       bf16x8 p0, p1, q0, q1, u0, u1, w0, w1;
;       asm volatile(
;         "ds_read_b128 %4, %12\n\tds_read_b128 %5, %12 offset:4096\n\tds_read_b128 %6, %16\n\tds_read_b128 %7, %16 offset:4096\n\t"
;         "ds_read_b128 %8, %13\n\tds_read_b128 %9, %13 offset:4096\n\tds_read_b128 %10, %17\n\tds_read_b128 %11, %17 offset:4096\n\t"
;         "s_waitcnt lgkmcnt(4)\n\t"
;         "v_mfma_f32_32x32x16_bf16 %0, %4, %6, %0\n\tv_mfma_f32_32x32x16_bf16 %1, %4, %7, %1\n\tv_mfma_f32_32x32x16_bf16 %2, %5, %6, %2\n\tv_mfma_f32_32x32x16_bf16 %3, %5, %7, %3\n\t"
;         "ds_read_b128 %4, %14\n\tds_read_b128 %5, %14 offset:4096\n\tds_read_b128 %6, %18\n\tds_read_b128 %7, %18 offset:4096\n\t"
;         "s_waitcnt lgkmcnt(4)\n\t"
;         "v_mfma_f32_32x32x16_bf16 %0, %8, %10, %0\n\tv_mfma_f32_32x32x16_bf16 %1, %8, %11, %1\n\tv_mfma_f32_32x32x16_bf16 %2, %9, %10, %2\n\tv_mfma_f32_32x32x16_bf16 %3, %9, %11, %3\n\t"
;         "ds_read_b128 %8, %15\n\tds_read_b128 %9, %15 offset:4096\n\tds_read_b128 %10, %19\n\tds_read_b128 %11, %19 offset:4096\n\t"
;         "s_waitcnt lgkmcnt(4)\n\t"
;         "v_mfma_f32_32x32x16_bf16 %0, %4, %6, %0\n\tv_mfma_f32_32x32x16_bf16 %1, %4, %7, %1\n\tv_mfma_f32_32x32x16_bf16 %2, %5, %6, %2\n\tv_mfma_f32_32x32x16_bf16 %3, %5, %7, %3\n\t"
;         "s_waitcnt lgkmcnt(0)\n\t"
;         "v_mfma_f32_32x32x16_bf16 %0, %8, %10, %0\n\tv_mfma_f32_32x32x16_bf16 %1, %8, %11, %1\n\tv_mfma_f32_32x32x16_bf16 %2, %9, %10, %2\n\tv_mfma_f32_32x32x16_bf16 %3, %9, %11, %3"
;         : "+v"(acc[0][0]), "+v"(acc[0][1]), "+v"(acc[1][0]), "+v"(acc[1][1]),
;           "=&v"(p0), "=&v"(p1), "=&v"(q0), "=&v"(q1), "=&v"(u0), "=&v"(u1), "=&v"(w0), "=&v"(w1)
	ds_read_b128 v[84:87], v76 offset:49152
	ds_read_b128 v[88:91], v76 offset:51200
	ds_read_b128 v[92:95], v76 offset:53248
	ds_read_b128 v[96:99], v76 offset:55296
	ds_read_b128 v[100:103], v78 offset:49152
	ds_read_b128 v[104:107], v78 offset:51200
	ds_read_b128 v[108:111], v78 offset:53248
	ds_read_b128 v[112:115], v78 offset:55296
	v_mfma_f32_16x16x32_bf16 v[0:3], v[136:139], v[152:155], v[0:3]
	v_mfma_f32_16x16x32_bf16 v[4:7], v[136:139], v[156:159], v[4:7]
	v_mfma_f32_16x16x32_bf16 v[8:11], v[136:139], v[160:163], v[8:11]
	v_mfma_f32_16x16x32_bf16 v[12:15], v[136:139], v[164:167], v[12:15]
	v_mfma_f32_16x16x32_bf16 v[16:19], v[140:143], v[152:155], v[16:19]
	s_mov_b32 s24, 0x680
	s_mov_b32 s25, 0
	s_mov_b32 m0, s30
	v_lshl_add_u64 v[124:125], v[64:65], 0, s[24:25]
	global_load_lds_dwordx4 v[124:125], off
	v_mfma_f32_16x16x32_bf16 v[20:23], v[140:143], v[156:159], v[20:23]
	v_mfma_f32_16x16x32_bf16 v[24:27], v[140:143], v[160:163], v[24:27]
	v_mfma_f32_16x16x32_bf16 v[28:31], v[140:143], v[164:167], v[28:31]
	v_mfma_f32_16x16x32_bf16 v[32:35], v[144:147], v[152:155], v[32:35]
	v_mfma_f32_16x16x32_bf16 v[36:39], v[144:147], v[156:159], v[36:39]
	s_add_u32 m0, s30, 0x2000
	v_lshl_add_u64 v[126:127], v[66:67], 0, s[24:25]
	global_load_lds_dwordx4 v[126:127], off
	v_mfma_f32_16x16x32_bf16 v[40:43], v[144:147], v[160:163], v[40:43]
	v_mfma_f32_16x16x32_bf16 v[44:47], v[144:147], v[164:167], v[44:47]
	v_mfma_f32_16x16x32_bf16 v[48:51], v[148:151], v[152:155], v[48:51]
	v_mfma_f32_16x16x32_bf16 v[52:55], v[148:151], v[156:159], v[52:55]
	v_mfma_f32_16x16x32_bf16 v[56:59], v[148:151], v[160:163], v[56:59]
	s_add_u32 m0, s30, 0x4000
	v_lshl_add_u64 v[124:125], v[68:69], 0, s[24:25]
	global_load_lds_dwordx4 v[124:125], off
	v_mfma_f32_16x16x32_bf16 v[60:63], v[148:151], v[164:167], v[60:63]
	ds_read_b128 v[136:139], v77 offset:49152
	ds_read_b128 v[140:143], v77 offset:51200
	ds_read_b128 v[144:147], v77 offset:53248
	ds_read_b128 v[148:151], v77 offset:55296
	ds_read_b128 v[152:155], v79 offset:49152
	ds_read_b128 v[156:159], v79 offset:51200
	ds_read_b128 v[160:163], v79 offset:53248
	ds_read_b128 v[164:167], v79 offset:55296
	s_waitcnt lgkmcnt(8)
	v_mfma_f32_16x16x32_bf16 v[0:3], v[84:87], v[100:103], v[0:3]
	v_mfma_f32_16x16x32_bf16 v[4:7], v[84:87], v[104:107], v[4:7]
	v_mfma_f32_16x16x32_bf16 v[8:11], v[84:87], v[108:111], v[8:11]
	v_mfma_f32_16x16x32_bf16 v[12:15], v[84:87], v[112:115], v[12:15]
	v_mfma_f32_16x16x32_bf16 v[16:19], v[88:91], v[100:103], v[16:19]
	s_add_u32 m0, s30, 0x6000
	v_lshl_add_u64 v[126:127], v[70:71], 0, s[24:25]
	global_load_lds_dwordx4 v[126:127], off
	v_mfma_f32_16x16x32_bf16 v[20:23], v[88:91], v[104:107], v[20:23]
	v_mfma_f32_16x16x32_bf16 v[24:27], v[88:91], v[108:111], v[24:27]
	v_mfma_f32_16x16x32_bf16 v[28:31], v[88:91], v[112:115], v[28:31]
	v_mfma_f32_16x16x32_bf16 v[32:35], v[92:95], v[100:103], v[32:35]
	v_mfma_f32_16x16x32_bf16 v[36:39], v[92:95], v[104:107], v[36:39]
	s_add_u32 m0, s30, 0x8000
	v_lshl_add_u64 v[124:125], v[72:73], 0, s[24:25]
	global_load_lds_dwordx4 v[124:125], off
	v_mfma_f32_16x16x32_bf16 v[40:43], v[92:95], v[108:111], v[40:43]
	v_mfma_f32_16x16x32_bf16 v[44:47], v[92:95], v[112:115], v[44:47]
	v_mfma_f32_16x16x32_bf16 v[48:51], v[96:99], v[100:103], v[48:51]
	v_mfma_f32_16x16x32_bf16 v[52:55], v[96:99], v[104:107], v[52:55]
	v_mfma_f32_16x16x32_bf16 v[56:59], v[96:99], v[108:111], v[56:59]
	s_add_u32 m0, s30, 0xa000
	v_lshl_add_u64 v[126:127], v[74:75], 0, s[24:25]
	global_load_lds_dwordx4 v[126:127], off
	v_mfma_f32_16x16x32_bf16 v[60:63], v[96:99], v[112:115], v[60:63]
	s_waitcnt vmcnt(6) lgkmcnt(0)
	s_barrier
	ds_read_b128 v[84:87], v80
	ds_read_b128 v[88:91], v80 offset:2048
	ds_read_b128 v[92:95], v80 offset:4096
	ds_read_b128 v[96:99], v80 offset:6144
	ds_read_b128 v[100:103], v82
	ds_read_b128 v[104:107], v82 offset:2048
	ds_read_b128 v[108:111], v82 offset:4096
	ds_read_b128 v[112:115], v82 offset:6144
	v_mfma_f32_16x16x32_bf16 v[0:3], v[136:139], v[152:155], v[0:3]
	v_mfma_f32_16x16x32_bf16 v[4:7], v[136:139], v[156:159], v[4:7]
	v_mfma_f32_16x16x32_bf16 v[8:11], v[136:139], v[160:163], v[8:11]
	v_mfma_f32_16x16x32_bf16 v[12:15], v[136:139], v[164:167], v[12:15]
	v_mfma_f32_16x16x32_bf16 v[16:19], v[140:143], v[152:155], v[16:19]
	s_mov_b32 s24, 0x700
	s_mov_b32 s25, 0
	s_add_u32 m0, s30, 0xc000
	v_lshl_add_u64 v[124:125], v[64:65], 0, s[24:25]
	global_load_lds_dwordx4 v[124:125], off
	v_mfma_f32_16x16x32_bf16 v[20:23], v[140:143], v[156:159], v[20:23]
	v_mfma_f32_16x16x32_bf16 v[24:27], v[140:143], v[160:163], v[24:27]
	v_mfma_f32_16x16x32_bf16 v[28:31], v[140:143], v[164:167], v[28:31]
	v_mfma_f32_16x16x32_bf16 v[32:35], v[144:147], v[152:155], v[32:35]
	v_mfma_f32_16x16x32_bf16 v[36:39], v[144:147], v[156:159], v[36:39]
	s_add_u32 m0, s30, 0xe000
	v_lshl_add_u64 v[126:127], v[66:67], 0, s[24:25]
	global_load_lds_dwordx4 v[126:127], off
	v_mfma_f32_16x16x32_bf16 v[40:43], v[144:147], v[160:163], v[40:43]
	v_mfma_f32_16x16x32_bf16 v[44:47], v[144:147], v[164:167], v[44:47]
	v_mfma_f32_16x16x32_bf16 v[48:51], v[148:151], v[152:155], v[48:51]
	v_mfma_f32_16x16x32_bf16 v[52:55], v[148:151], v[156:159], v[52:55]
	v_mfma_f32_16x16x32_bf16 v[56:59], v[148:151], v[160:163], v[56:59]
	s_add_u32 m0, s30, 0x10000
	v_lshl_add_u64 v[124:125], v[68:69], 0, s[24:25]
	global_load_lds_dwordx4 v[124:125], off
	v_mfma_f32_16x16x32_bf16 v[60:63], v[148:151], v[164:167], v[60:63]
	ds_read_b128 v[136:139], v81
	ds_read_b128 v[140:143], v81 offset:2048
	ds_read_b128 v[144:147], v81 offset:4096
	ds_read_b128 v[148:151], v81 offset:6144
	ds_read_b128 v[152:155], v83
	ds_read_b128 v[156:159], v83 offset:2048
	ds_read_b128 v[160:163], v83 offset:4096
	ds_read_b128 v[164:167], v83 offset:6144
	s_waitcnt lgkmcnt(8)
;     ...
;   for (int kt = 0; kt < nk; ++kt) {
;     if (kt + 1 < nk) asm volatile("s_waitcnt vmcnt(6)" ::: "memory");
;     else asm volatile("s_waitcnt vmcnt(0)" ::: "memory");
;     __builtin_amdgcn_s_barrier();
;     asm volatile("" ::: "memory");
;     if (kt + 2 < nk) { const int st2 = (st >= 1) ? st - 1 : 2; GEMM_ISSUE(kt + 2, st2); }
;     const char* la = lds + st * STAGE_B;
;     const char* lb = la + 32768;
;     const unsigned sa_u = (unsigned)(size_t)la + arow_u, sb_u = (unsigned)(size_t)lb + brow_u;
;     const unsigned a0 = sa_u + co0, a1 = sa_u + co1, a2 = sa_u + co2, a3 = sa_u + co3;
;     const unsigned b0 = sb_u + co0, b1 = sb_u + co1, b2 = sb_u + co2, b3 = sb_u + co3;
;     {
;       bf16x8 p0, p1, q0, q1, u0, u1, w0, w1;
;       asm volatile(
;         "ds_read_b128 %4, %12\n\tds_read_b128 %5, %12 offset:4096\n\tds_read_b128 %6, %16\n\tds_read_b128 %7, %16 offset:4096\n\t"
;         "ds_read_b128 %8, %13\n\tds_read_b128 %9, %13 offset:4096\n\tds_read_b128 %10, %17\n\tds_read_b128 %11, %17 offset:4096\n\t"
;         "s_waitcnt lgkmcnt(4)\n\t"
;         "v_mfma_f32_32x32x16_bf16 %0, %4, %6, %0\n\tv_mfma_f32_32x32x16_bf16 %1, %4, %7, %1\n\tv_mfma_f32_32x32x16_bf16 %2, %5, %6, %2\n\tv_mfma_f32_32x32x16_bf16 %3, %5, %7, %3\n\t"
;         "ds_read_b128 %4, %14\n\tds_read_b128 %5, %14 offset:4096\n\tds_read_b128 %6, %18\n\tds_read_b128 %7, %18 offset:4096\n\t"
;         "s_waitcnt lgkmcnt(4)\n\t"
;         "v_mfma_f32_32x32x16_bf16 %0, %8, %10, %0\n\tv_mfma_f32_32x32x16_bf16 %1, %8, %11, %1\n\tv_mfma_f32_32x32x16_bf16 %2, %9, %10, %2\n\tv_mfma_f32_32x32x16_bf16 %3, %9, %11, %3\n\t"
;         "ds_read_b128 %8, %15\n\tds_read_b128 %9, %15 offset:4096\n\tds_read_b128 %10, %19\n\tds_read_b128 %11, %19 offset:4096\n\t"
;         "s_waitcnt lgkmcnt(4)\n\t"
;         "v_mfma_f32_32x32x16_bf16 %0, %4, %6, %0\n\tv_mfma_f32_32x32x16_bf16 %1, %4, %7, %1\n\tv_mfma_f32_32x32x16_bf16 %2, %5, %6, %2\n\tv_mfma_f32_32x32x16_bf16 %3, %5, %7, %3\n\t"
;         "s_waitcnt lgkmcnt(0)\n\t"
;         "v_mfma_f32_32x32x16_bf16 %0, %8, %10, %0\n\tv_mfma_f32_32x32x16_bf16 %1, %8, %11, %1\n\tv_mfma_f32_32x32x16_bf16 %2, %9, %10, %2\n\tv_mfma_f32_32x32x16_bf16 %3, %9, %11, %3"
;         : "+v"(acc[0][0]), "+v"(acc[0][1]), "+v"(acc[1][0]), "+v"(acc[1][1]),
;           "=&v"(p0), "=&v"(p1), "=&v"(q0), "=&v"(q1), "=&v"(u0), "=&v"(u1), "=&v"(w0), "=&v"(w1)
	v_mfma_f32_16x16x32_bf16 v[0:3], v[84:87], v[100:103], v[0:3]
	v_mfma_f32_16x16x32_bf16 v[4:7], v[84:87], v[104:107], v[4:7]
	v_mfma_f32_16x16x32_bf16 v[8:11], v[84:87], v[108:111], v[8:11]
	v_mfma_f32_16x16x32_bf16 v[12:15], v[84:87], v[112:115], v[12:15]
	v_mfma_f32_16x16x32_bf16 v[16:19], v[88:91], v[100:103], v[16:19]
	s_add_u32 m0, s30, 0x12000
	v_lshl_add_u64 v[126:127], v[70:71], 0, s[24:25]
	global_load_lds_dwordx4 v[126:127], off
	v_mfma_f32_16x16x32_bf16 v[20:23], v[88:91], v[104:107], v[20:23]
	v_mfma_f32_16x16x32_bf16 v[24:27], v[88:91], v[108:111], v[24:27]
	v_mfma_f32_16x16x32_bf16 v[28:31], v[88:91], v[112:115], v[28:31]
	v_mfma_f32_16x16x32_bf16 v[32:35], v[92:95], v[100:103], v[32:35]
	v_mfma_f32_16x16x32_bf16 v[36:39], v[92:95], v[104:107], v[36:39]
	s_add_u32 m0, s30, 0x14000
	v_lshl_add_u64 v[124:125], v[72:73], 0, s[24:25]
	global_load_lds_dwordx4 v[124:125], off
	v_mfma_f32_16x16x32_bf16 v[40:43], v[92:95], v[108:111], v[40:43]
	v_mfma_f32_16x16x32_bf16 v[44:47], v[92:95], v[112:115], v[44:47]
	v_mfma_f32_16x16x32_bf16 v[48:51], v[96:99], v[100:103], v[48:51]
	v_mfma_f32_16x16x32_bf16 v[52:55], v[96:99], v[104:107], v[52:55]
	v_mfma_f32_16x16x32_bf16 v[56:59], v[96:99], v[108:111], v[56:59]
	s_add_u32 m0, s30, 0x16000
	v_lshl_add_u64 v[126:127], v[74:75], 0, s[24:25]
	global_load_lds_dwordx4 v[126:127], off
	v_mfma_f32_16x16x32_bf16 v[60:63], v[96:99], v[112:115], v[60:63]
	s_waitcnt vmcnt(6) lgkmcnt(0)
	s_barrier
	ds_read_b128 v[84:87], v76
	ds_read_b128 v[88:91], v76 offset:2048
	ds_read_b128 v[92:95], v76 offset:4096
	ds_read_b128 v[96:99], v76 offset:6144
	ds_read_b128 v[100:103], v78
	ds_read_b128 v[104:107], v78 offset:2048
	ds_read_b128 v[108:111], v78 offset:4096
	ds_read_b128 v[112:115], v78 offset:6144
	v_mfma_f32_16x16x32_bf16 v[0:3], v[136:139], v[152:155], v[0:3]
	v_mfma_f32_16x16x32_bf16 v[4:7], v[136:139], v[156:159], v[4:7]
	v_mfma_f32_16x16x32_bf16 v[8:11], v[136:139], v[160:163], v[8:11]
	v_mfma_f32_16x16x32_bf16 v[12:15], v[136:139], v[164:167], v[12:15]
	v_mfma_f32_16x16x32_bf16 v[16:19], v[140:143], v[152:155], v[16:19]
	s_mov_b32 s24, 0x780
	s_mov_b32 s25, 0
	s_add_u32 m0, s30, 0x18000
	v_lshl_add_u64 v[124:125], v[64:65], 0, s[24:25]
	global_load_lds_dwordx4 v[124:125], off
	v_mfma_f32_16x16x32_bf16 v[20:23], v[140:143], v[156:159], v[20:23]
	v_mfma_f32_16x16x32_bf16 v[24:27], v[140:143], v[160:163], v[24:27]
	v_mfma_f32_16x16x32_bf16 v[28:31], v[140:143], v[164:167], v[28:31]
	v_mfma_f32_16x16x32_bf16 v[32:35], v[144:147], v[152:155], v[32:35]
	v_mfma_f32_16x16x32_bf16 v[36:39], v[144:147], v[156:159], v[36:39]
	s_add_u32 m0, s30, 0x1a000
	v_lshl_add_u64 v[126:127], v[66:67], 0, s[24:25]
	global_load_lds_dwordx4 v[126:127], off
	v_mfma_f32_16x16x32_bf16 v[40:43], v[144:147], v[160:163], v[40:43]
	v_mfma_f32_16x16x32_bf16 v[44:47], v[144:147], v[164:167], v[44:47]
	v_mfma_f32_16x16x32_bf16 v[48:51], v[148:151], v[152:155], v[48:51]
	v_mfma_f32_16x16x32_bf16 v[52:55], v[148:151], v[156:159], v[52:55]
	v_mfma_f32_16x16x32_bf16 v[56:59], v[148:151], v[160:163], v[56:59]
	s_add_u32 m0, s30, 0x1c000
	v_lshl_add_u64 v[124:125], v[68:69], 0, s[24:25]
	global_load_lds_dwordx4 v[124:125], off
	v_mfma_f32_16x16x32_bf16 v[60:63], v[148:151], v[164:167], v[60:63]
	ds_read_b128 v[136:139], v77
	ds_read_b128 v[140:143], v77 offset:2048
	ds_read_b128 v[144:147], v77 offset:4096
	ds_read_b128 v[148:151], v77 offset:6144
	ds_read_b128 v[152:155], v79
	ds_read_b128 v[156:159], v79 offset:2048
	ds_read_b128 v[160:163], v79 offset:4096
	ds_read_b128 v[164:167], v79 offset:6144
	s_waitcnt lgkmcnt(8)
	v_mfma_f32_16x16x32_bf16 v[0:3], v[84:87], v[100:103], v[0:3]
	v_mfma_f32_16x16x32_bf16 v[4:7], v[84:87], v[104:107], v[4:7]
	v_mfma_f32_16x16x32_bf16 v[8:11], v[84:87], v[108:111], v[8:11]
	v_mfma_f32_16x16x32_bf16 v[12:15], v[84:87], v[112:115], v[12:15]
	v_mfma_f32_16x16x32_bf16 v[16:19], v[88:91], v[100:103], v[16:19]
	s_add_u32 m0, s30, 0x1e000
	v_lshl_add_u64 v[126:127], v[70:71], 0, s[24:25]
	global_load_lds_dwordx4 v[126:127], off
	v_mfma_f32_16x16x32_bf16 v[20:23], v[88:91], v[104:107], v[20:23]
	v_mfma_f32_16x16x32_bf16 v[24:27], v[88:91], v[108:111], v[24:27]
	v_mfma_f32_16x16x32_bf16 v[28:31], v[88:91], v[112:115], v[28:31]
	v_mfma_f32_16x16x32_bf16 v[32:35], v[92:95], v[100:103], v[32:35]
	v_mfma_f32_16x16x32_bf16 v[36:39], v[92:95], v[104:107], v[36:39]
	s_add_u32 m0, s30, 0x20000
	v_lshl_add_u64 v[124:125], v[72:73], 0, s[24:25]
	global_load_lds_dwordx4 v[124:125], off
	v_mfma_f32_16x16x32_bf16 v[40:43], v[92:95], v[108:111], v[40:43]
	v_mfma_f32_16x16x32_bf16 v[44:47], v[92:95], v[112:115], v[44:47]
	v_mfma_f32_16x16x32_bf16 v[48:51], v[96:99], v[100:103], v[48:51]
	v_mfma_f32_16x16x32_bf16 v[52:55], v[96:99], v[104:107], v[52:55]
	v_mfma_f32_16x16x32_bf16 v[56:59], v[96:99], v[108:111], v[56:59]
	s_add_u32 m0, s30, 0x22000
	v_lshl_add_u64 v[126:127], v[74:75], 0, s[24:25]
	global_load_lds_dwordx4 v[126:127], off
	v_mfma_f32_16x16x32_bf16 v[60:63], v[96:99], v[112:115], v[60:63]
	s_waitcnt vmcnt(6) lgkmcnt(0)
	s_barrier
;     ...
;   if (PART != 2) {
;     GEMM_ISSUE(0, 0);
;     if (nk > 1) GEMM_ISSUE(1, 1);
;   }
;   if (PART == 1) return;
;   int st = 0;
;   for (int kt = 0; kt < nk; ++kt) {
;     if (kt + 1 < nk) asm volatile("s_waitcnt vmcnt(6)" ::: "memory");
;     else asm volatile("s_waitcnt vmcnt(0)" ::: "memory");
;     __builtin_amdgcn_s_barrier();
;     asm volatile("" ::: "memory");
;     if (kt + 2 < nk) { const int st2 = (st >= 1) ? st - 1 : 2; GEMM_ISSUE(kt + 2, st2); }
;     const char* la = lds + st * STAGE_B;
;     const char* lb = la + 32768;
;     const unsigned sa_u = (unsigned)(size_t)la + arow_u, sb_u = (unsigned)(size_t)lb + brow_u;
;     const unsigned a0 = sa_u + co0, a1 = sa_u + co1, a2 = sa_u + co2, a3 = sa_u + co3;
;     const unsigned b0 = sb_u + co0, b1 = sb_u + co1, b2 = sb_u + co2, b3 = sb_u + co3;
;     {
;       bf16x8 p0, p1, q0, q1, u0, u1, w0, w1;
;       asm volatile(
;         "ds_read_b128 %4, %12\n\tds_read_b128 %5, %12 offset:4096\n\tds_read_b128 %6, %16\n\tds_read_b128 %7, %16 offset:4096\n\t"
;         "ds_read_b128 %8, %13\n\tds_read_b128 %9, %13 offset:4096\n\tds_read_b128 %10, %17\n\tds_read_b128 %11, %17 offset:4096\n\t"
;         "s_waitcnt lgkmcnt(4)\n\t"
;         "v_mfma_f32_32x32x16_bf16 %0, %4, %6, %0\n\tv_mfma_f32_32x32x16_bf16 %1, %4, %7, %1\n\tv_mfma_f32_32x32x16_bf16 %2, %5, %6, %2\n\tv_mfma_f32_32x32x16_bf16 %3, %5, %7, %3\n\t"
;         "ds_read_b128 %4, %14\n\tds_read_b128 %5, %14 offset:4096\n\tds_read_b128 %6, %18\n\tds_read_b128 %7, %18 offset:4096\n\t"
;         "s_waitcnt lgkmcnt(4)\n\t"
;         "v_mfma_f32_32x32x16_bf16 %0, %8, %10, %0\n\tv_mfma_f32_32x32x16_bf16 %1, %8, %11, %1\n\tv_mfma_f32_32x32x16_bf16 %2, %9, %10, %2\n\tv_mfma_f32_32x32x16_bf16 %3, %9, %11, %3\n\t"
;         "ds_read_b128 %8, %15\n\tds_read_b128 %9, %15 offset:4096\n\tds_read_b128 %10, %19\n\tds_read_b128 %11, %19 offset:4096\n\t"
;         "s_waitcnt lgkmcnt(4)\n\t"
;         "v_mfma_f32_32x32x16_bf16 %0, %4, %6, %0\n\tv_mfma_f32_32x32x16_bf16 %1, %4, %7, %1\n\tv_mfma_f32_32x32x16_bf16 %2, %5, %6, %2\n\tv_mfma_f32_32x32x16_bf16 %3, %5, %7, %3\n\t"
;         "s_waitcnt lgkmcnt(0)\n\t"
;         "v_mfma_f32_32x32x16_bf16 %0, %8, %10, %0\n\tv_mfma_f32_32x32x16_bf16 %1, %8, %11, %1\n\tv_mfma_f32_32x32x16_bf16 %2, %9, %10, %2\n\tv_mfma_f32_32x32x16_bf16 %3, %9, %11, %3"
	ds_read_b128 v[84:87], v76 offset:49152
	ds_read_b128 v[88:91], v76 offset:51200
	ds_read_b128 v[92:95], v76 offset:53248
	ds_read_b128 v[96:99], v76 offset:55296
	ds_read_b128 v[100:103], v78 offset:49152
	ds_read_b128 v[104:107], v78 offset:51200
	ds_read_b128 v[108:111], v78 offset:53248
	ds_read_b128 v[112:115], v78 offset:55296
	v_mfma_f32_16x16x32_bf16 v[0:3], v[136:139], v[152:155], v[0:3]
	v_mfma_f32_16x16x32_bf16 v[4:7], v[136:139], v[156:159], v[4:7]
	v_mfma_f32_16x16x32_bf16 v[8:11], v[136:139], v[160:163], v[8:11]
	v_mfma_f32_16x16x32_bf16 v[12:15], v[136:139], v[164:167], v[12:15]
	v_mfma_f32_16x16x32_bf16 v[16:19], v[140:143], v[152:155], v[16:19]
	s_add_u32 s24, s56, 0x0
	s_addc_u32 s25, s57, 0
	s_mov_b32 m0, s30
	v_lshl_add_u64 v[124:125], v[64:65], 0, s[24:25]
	global_load_lds_dwordx4 v[124:125], off
	v_mfma_f32_16x16x32_bf16 v[20:23], v[140:143], v[156:159], v[20:23]
	v_mfma_f32_16x16x32_bf16 v[24:27], v[140:143], v[160:163], v[24:27]
	v_mfma_f32_16x16x32_bf16 v[28:31], v[140:143], v[164:167], v[28:31]
	v_mfma_f32_16x16x32_bf16 v[32:35], v[144:147], v[152:155], v[32:35]
	v_mfma_f32_16x16x32_bf16 v[36:39], v[144:147], v[156:159], v[36:39]
	s_add_u32 m0, s30, 0x2000
	v_lshl_add_u64 v[126:127], v[66:67], 0, s[24:25]
	global_load_lds_dwordx4 v[126:127], off
	v_mfma_f32_16x16x32_bf16 v[40:43], v[144:147], v[160:163], v[40:43]
	v_mfma_f32_16x16x32_bf16 v[44:47], v[144:147], v[164:167], v[44:47]
	v_mfma_f32_16x16x32_bf16 v[48:51], v[148:151], v[152:155], v[48:51]
	v_mfma_f32_16x16x32_bf16 v[52:55], v[148:151], v[156:159], v[52:55]
	v_mfma_f32_16x16x32_bf16 v[56:59], v[148:151], v[160:163], v[56:59]
	s_add_u32 m0, s30, 0x4000
	v_lshl_add_u64 v[124:125], v[68:69], 0, s[24:25]
	global_load_lds_dwordx4 v[124:125], off
	v_mfma_f32_16x16x32_bf16 v[60:63], v[148:151], v[164:167], v[60:63]
	ds_read_b128 v[136:139], v77 offset:49152
	ds_read_b128 v[140:143], v77 offset:51200
	ds_read_b128 v[144:147], v77 offset:53248
	ds_read_b128 v[148:151], v77 offset:55296
	ds_read_b128 v[152:155], v79 offset:49152
	ds_read_b128 v[156:159], v79 offset:51200
	ds_read_b128 v[160:163], v79 offset:53248
	ds_read_b128 v[164:167], v79 offset:55296
	s_waitcnt lgkmcnt(8)
	v_mfma_f32_16x16x32_bf16 v[0:3], v[84:87], v[100:103], v[0:3]
	v_mfma_f32_16x16x32_bf16 v[4:7], v[84:87], v[104:107], v[4:7]
	v_mfma_f32_16x16x32_bf16 v[8:11], v[84:87], v[108:111], v[8:11]
	v_mfma_f32_16x16x32_bf16 v[12:15], v[84:87], v[112:115], v[12:15]
	v_mfma_f32_16x16x32_bf16 v[16:19], v[88:91], v[100:103], v[16:19]
	s_add_u32 m0, s30, 0x6000
	v_lshl_add_u64 v[126:127], v[70:71], 0, s[24:25]
	global_load_lds_dwordx4 v[126:127], off
	v_mfma_f32_16x16x32_bf16 v[20:23], v[88:91], v[104:107], v[20:23]
	v_mfma_f32_16x16x32_bf16 v[24:27], v[88:91], v[108:111], v[24:27]
	v_mfma_f32_16x16x32_bf16 v[28:31], v[88:91], v[112:115], v[28:31]
	v_mfma_f32_16x16x32_bf16 v[32:35], v[92:95], v[100:103], v[32:35]
	v_mfma_f32_16x16x32_bf16 v[36:39], v[92:95], v[104:107], v[36:39]
	s_add_u32 s24, s58, 0x0
	s_addc_u32 s25, s59, 0
	s_add_u32 m0, s30, 0x8000
	v_lshl_add_u64 v[124:125], v[72:73], 0, s[24:25]
	global_load_lds_dwordx4 v[124:125], off
	v_mfma_f32_16x16x32_bf16 v[40:43], v[92:95], v[108:111], v[40:43]
	v_mfma_f32_16x16x32_bf16 v[44:47], v[92:95], v[112:115], v[44:47]
	v_mfma_f32_16x16x32_bf16 v[48:51], v[96:99], v[100:103], v[48:51]
	v_mfma_f32_16x16x32_bf16 v[52:55], v[96:99], v[104:107], v[52:55]
	v_mfma_f32_16x16x32_bf16 v[56:59], v[96:99], v[108:111], v[56:59]
	s_add_u32 m0, s30, 0xa000
	v_lshl_add_u64 v[126:127], v[74:75], 0, s[24:25]
	global_load_lds_dwordx4 v[126:127], off
	v_mfma_f32_16x16x32_bf16 v[60:63], v[96:99], v[112:115], v[60:63]
	s_waitcnt vmcnt(6) lgkmcnt(0)
	s_barrier
;     ...
;   for (int kt = 0; kt < nk; ++kt) {
;     if (kt + 1 < nk) asm volatile("s_waitcnt vmcnt(6)" ::: "memory");
;     else asm volatile("s_waitcnt vmcnt(0)" ::: "memory");
;     __builtin_amdgcn_s_barrier();
;     asm volatile("" ::: "memory");
;     if (kt + 2 < nk) { const int st2 = (st >= 1) ? st - 1 : 2; GEMM_ISSUE(kt + 2, st2); }
;     const char* la = lds + st * STAGE_B;
;     const char* lb = la + 32768;
;     const unsigned sa_u = (unsigned)(size_t)la + arow_u, sb_u = (unsigned)(size_t)lb + brow_u;
;     const unsigned a0 = sa_u + co0, a1 = sa_u + co1, a2 = sa_u + co2, a3 = sa_u + co3;
;     const unsigned b0 = sb_u + co0, b1 = sb_u + co1, b2 = sb_u + co2, b3 = sb_u + co3;
;     {
;       bf16x8 p0, p1, q0, q1, u0, u1, w0, w1;
;       asm volatile(
;         "ds_read_b128 %4, %12\n\tds_read_b128 %5, %12 offset:4096\n\tds_read_b128 %6, %16\n\tds_read_b128 %7, %16 offset:4096\n\t"
;         "ds_read_b128 %8, %13\n\tds_read_b128 %9, %13 offset:4096\n\tds_read_b128 %10, %17\n\tds_read_b128 %11, %17 offset:4096\n\t"
;         "s_waitcnt lgkmcnt(4)\n\t"
;         "v_mfma_f32_32x32x16_bf16 %0, %4, %6, %0\n\tv_mfma_f32_32x32x16_bf16 %1, %4, %7, %1\n\tv_mfma_f32_32x32x16_bf16 %2, %5, %6, %2\n\tv_mfma_f32_32x32x16_bf16 %3, %5, %7, %3\n\t"
;         "ds_read_b128 %4, %14\n\tds_read_b128 %5, %14 offset:4096\n\tds_read_b128 %6, %18\n\tds_read_b128 %7, %18 offset:4096\n\t"
;         "s_waitcnt lgkmcnt(4)\n\t"
;         "v_mfma_f32_32x32x16_bf16 %0, %8, %10, %0\n\tv_mfma_f32_32x32x16_bf16 %1, %8, %11, %1\n\tv_mfma_f32_32x32x16_bf16 %2, %9, %10, %2\n\tv_mfma_f32_32x32x16_bf16 %3, %9, %11, %3\n\t"
;         "ds_read_b128 %8, %15\n\tds_read_b128 %9, %15 offset:4096\n\tds_read_b128 %10, %19\n\tds_read_b128 %11, %19 offset:4096\n\t"
;         "s_waitcnt lgkmcnt(4)\n\t"
;         "v_mfma_f32_32x32x16_bf16 %0, %4, %6, %0\n\tv_mfma_f32_32x32x16_bf16 %1, %4, %7, %1\n\tv_mfma_f32_32x32x16_bf16 %2, %5, %6, %2\n\tv_mfma_f32_32x32x16_bf16 %3, %5, %7, %3\n\t"
;         "s_waitcnt lgkmcnt(0)\n\t"
;         "v_mfma_f32_32x32x16_bf16 %0, %8, %10, %0\n\tv_mfma_f32_32x32x16_bf16 %1, %8, %11, %1\n\tv_mfma_f32_32x32x16_bf16 %2, %9, %10, %2\n\tv_mfma_f32_32x32x16_bf16 %3, %9, %11, %3"
;         : "+v"(acc[0][0]), "+v"(acc[0][1]), "+v"(acc[1][0]), "+v"(acc[1][1]),
;           "=&v"(p0), "=&v"(p1), "=&v"(q0), "=&v"(q1), "=&v"(u0), "=&v"(u1), "=&v"(w0), "=&v"(w1)
	ds_read_b128 v[84:87], v80
	ds_read_b128 v[88:91], v80 offset:2048
	ds_read_b128 v[92:95], v80 offset:4096
	ds_read_b128 v[96:99], v80 offset:6144
	ds_read_b128 v[100:103], v82
	ds_read_b128 v[104:107], v82 offset:2048
	ds_read_b128 v[108:111], v82 offset:4096
	ds_read_b128 v[112:115], v82 offset:6144
	v_mfma_f32_16x16x32_bf16 v[0:3], v[136:139], v[152:155], v[0:3]
	v_mfma_f32_16x16x32_bf16 v[4:7], v[136:139], v[156:159], v[4:7]
	v_mfma_f32_16x16x32_bf16 v[8:11], v[136:139], v[160:163], v[8:11]
	v_mfma_f32_16x16x32_bf16 v[12:15], v[136:139], v[164:167], v[12:15]
	v_mfma_f32_16x16x32_bf16 v[16:19], v[140:143], v[152:155], v[16:19]
	s_add_u32 s24, s56, 0x80
	s_addc_u32 s25, s57, 0
	s_add_u32 m0, s30, 0xc000
	v_lshl_add_u64 v[124:125], v[64:65], 0, s[24:25]
	global_load_lds_dwordx4 v[124:125], off
	v_mfma_f32_16x16x32_bf16 v[20:23], v[140:143], v[156:159], v[20:23]
	v_mfma_f32_16x16x32_bf16 v[24:27], v[140:143], v[160:163], v[24:27]
	v_mfma_f32_16x16x32_bf16 v[28:31], v[140:143], v[164:167], v[28:31]
	v_mfma_f32_16x16x32_bf16 v[32:35], v[144:147], v[152:155], v[32:35]
	v_mfma_f32_16x16x32_bf16 v[36:39], v[144:147], v[156:159], v[36:39]
	s_add_u32 m0, s30, 0xe000
	v_lshl_add_u64 v[126:127], v[66:67], 0, s[24:25]
	global_load_lds_dwordx4 v[126:127], off
	v_mfma_f32_16x16x32_bf16 v[40:43], v[144:147], v[160:163], v[40:43]
	v_mfma_f32_16x16x32_bf16 v[44:47], v[144:147], v[164:167], v[44:47]
	v_mfma_f32_16x16x32_bf16 v[48:51], v[148:151], v[152:155], v[48:51]
	v_mfma_f32_16x16x32_bf16 v[52:55], v[148:151], v[156:159], v[52:55]
	v_mfma_f32_16x16x32_bf16 v[56:59], v[148:151], v[160:163], v[56:59]
	s_add_u32 m0, s30, 0x10000
	v_lshl_add_u64 v[124:125], v[68:69], 0, s[24:25]
	global_load_lds_dwordx4 v[124:125], off
	v_mfma_f32_16x16x32_bf16 v[60:63], v[148:151], v[164:167], v[60:63]
	ds_read_b128 v[136:139], v81
	ds_read_b128 v[140:143], v81 offset:2048
	ds_read_b128 v[144:147], v81 offset:4096
	ds_read_b128 v[148:151], v81 offset:6144
	ds_read_b128 v[152:155], v83
	ds_read_b128 v[156:159], v83 offset:2048
	ds_read_b128 v[160:163], v83 offset:4096
	ds_read_b128 v[164:167], v83 offset:6144
	s_waitcnt lgkmcnt(8)
	v_mfma_f32_16x16x32_bf16 v[0:3], v[84:87], v[100:103], v[0:3]
	v_mfma_f32_16x16x32_bf16 v[4:7], v[84:87], v[104:107], v[4:7]
	v_mfma_f32_16x16x32_bf16 v[8:11], v[84:87], v[108:111], v[8:11]
	v_mfma_f32_16x16x32_bf16 v[12:15], v[84:87], v[112:115], v[12:15]
	v_mfma_f32_16x16x32_bf16 v[16:19], v[88:91], v[100:103], v[16:19]
	s_add_u32 m0, s30, 0x12000
	v_lshl_add_u64 v[126:127], v[70:71], 0, s[24:25]
	global_load_lds_dwordx4 v[126:127], off
	v_mfma_f32_16x16x32_bf16 v[20:23], v[88:91], v[104:107], v[20:23]
	v_mfma_f32_16x16x32_bf16 v[24:27], v[88:91], v[108:111], v[24:27]
	v_mfma_f32_16x16x32_bf16 v[28:31], v[88:91], v[112:115], v[28:31]
	v_mfma_f32_16x16x32_bf16 v[32:35], v[92:95], v[100:103], v[32:35]
	v_mfma_f32_16x16x32_bf16 v[36:39], v[92:95], v[104:107], v[36:39]
	s_add_u32 s24, s58, 0x80
	s_addc_u32 s25, s59, 0
	s_add_u32 m0, s30, 0x14000
	v_lshl_add_u64 v[124:125], v[72:73], 0, s[24:25]
	global_load_lds_dwordx4 v[124:125], off
	v_mfma_f32_16x16x32_bf16 v[40:43], v[92:95], v[108:111], v[40:43]
	v_mfma_f32_16x16x32_bf16 v[44:47], v[92:95], v[112:115], v[44:47]
	v_mfma_f32_16x16x32_bf16 v[48:51], v[96:99], v[100:103], v[48:51]
	v_mfma_f32_16x16x32_bf16 v[52:55], v[96:99], v[104:107], v[52:55]
	v_mfma_f32_16x16x32_bf16 v[56:59], v[96:99], v[108:111], v[56:59]
	s_add_u32 m0, s30, 0x16000
	v_lshl_add_u64 v[126:127], v[74:75], 0, s[24:25]
	global_load_lds_dwordx4 v[126:127], off
	v_mfma_f32_16x16x32_bf16 v[60:63], v[96:99], v[112:115], v[60:63]
	s_waitcnt lgkmcnt(0)
	v_mfma_f32_16x16x32_bf16 v[0:3], v[136:139], v[152:155], v[0:3]
	v_mfma_f32_16x16x32_bf16 v[4:7], v[136:139], v[156:159], v[4:7]
	v_mfma_f32_16x16x32_bf16 v[8:11], v[136:139], v[160:163], v[8:11]
	v_mfma_f32_16x16x32_bf16 v[12:15], v[136:139], v[164:167], v[12:15]
	v_mfma_f32_16x16x32_bf16 v[16:19], v[140:143], v[152:155], v[16:19]
	v_mfma_f32_16x16x32_bf16 v[20:23], v[140:143], v[156:159], v[20:23]
	v_mfma_f32_16x16x32_bf16 v[24:27], v[140:143], v[160:163], v[24:27]
	v_mfma_f32_16x16x32_bf16 v[28:31], v[140:143], v[164:167], v[28:31]
	v_mfma_f32_16x16x32_bf16 v[32:35], v[144:147], v[152:155], v[32:35]
	v_mfma_f32_16x16x32_bf16 v[36:39], v[144:147], v[156:159], v[36:39]
	v_mfma_f32_16x16x32_bf16 v[40:43], v[144:147], v[160:163], v[40:43]
	v_mfma_f32_16x16x32_bf16 v[44:47], v[144:147], v[164:167], v[44:47]
	v_mfma_f32_16x16x32_bf16 v[48:51], v[148:151], v[152:155], v[48:51]
	v_mfma_f32_16x16x32_bf16 v[52:55], v[148:151], v[156:159], v[52:55]
	v_mfma_f32_16x16x32_bf16 v[56:59], v[148:151], v[160:163], v[56:59]
	v_mfma_f32_16x16x32_bf16 v[60:63], v[148:151], v[164:167], v[60:63]
